# EpiRes GEMMs (P4/P6): waves own 64 contiguous output columns (B-fragment LDS rows 64wc+32bj instead of 128bj+32wc); each wave reads/writes 128 contiguous bytes per residual row
# speedup vs baseline: 1.0166x; 1.0004x over previous
; #define PG8_STAGE(bufoff, gbase, voff) do { _Pragma("unroll") for (int _i = 0; _i < 2; ++_i) \
;         __builtin_amdgcn_global_load_lds((const unsigned*)((const char*)(gbase) + (voff)[_i]), (LAS unsigned*)(lds + (bufoff) + ldsw + _i * 8192), 16, 0, 0); } while (0)
; #define PG8_STAGEA(bufoff, gbase, voff) do { _Pragma("unroll") for (int _i = 0; _i < 2; ++_i) \
;         __builtin_amdgcn_global_load_lds((const unsigned*)((const char*)(gbase) + (voff)[_i]), (LAS unsigned*)(lds + (bufoff) + ldsw + _i * 8192), 16, 0, 0); } while (0)
; #define PG8_WAIT_V(n) asm volatile("s_waitcnt vmcnt(" #n ")" ::: "memory")
; #define PG8_BAR __builtin_amdgcn_s_barrier()
; template <class Epi, int PARTS>
; __device__ __forceinline__ void gemm_phase(LAS unsigned char* lds, const Gemm g, const StaticOrder& S, const Epi& E) {
;     ...
;     for (int i = 0; i < 2; ++i) { int R, C; stage_rc(tid * 16 + i * 8192, R, C);
;         const int TR = g.wstride ? g.wstride * (R >> 6) + 8 * (R & 15) + ((R >> 4) & 3) : R;
;         voffA[i] = (unsigned)(TR * g.lda + C) * 2u; voffB[i] = (unsigned)(R * g.ldb + C) * 2u; }
;     const size_t kstep = (size_t)(BK * 2);
;     const size_t hstepA = (size_t)(g.wstride ? 4 : HALF) * g.lda * 2, hstepB = (size_t)HALF * g.ldb * 2;
;     const unsigned ldsw = (unsigned)wid * 1024u;
;     const int aoff = lds_byte(wr * 64 + fr, fq * 8), boff = lds_byte(wc * 32 + fr, fq * 8);
;     ...
;     PG8_STAGE(PG8_SB(1, 0), cB + kstep, voffB); PG8_STAGEA(PG8_SA(1, 0), cA + kstep, voffA); PG8_STAGE(PG8_SB(1, 1), cB + hstepB + kstep, voffB);
;     PG8_WAIT_V(6); PG8_BAR;
.LBB0_163:
	v_lshl_add_u64 v[10:11], s[60:61], 0, v[0:1]
	v_mov_b32_e32 v131, v1
	v_lshl_add_u64 v[12:13], s[60:61], 0, v[130:131]
	s_and_b32 s76, s33, 3
	s_add_i32 m0, s67, 0x18000
	v_lshl_add_u64 v[10:11], v[10:11], 0, s[72:73]
	v_lshl_add_u64 v[14:15], s[58:59], 0, v[0:1]
	s_lshl_b32 s34, s37, 13
	s_lshl_b32 s35, s76, 13
	s_waitcnt vmcnt(2)
	s_barrier
	global_load_lds_dwordx4 v[10:11], off
	v_lshl_add_u64 v[10:11], v[12:13], 0, s[72:73]
	s_add_i32 m0, s67, 0x1a000
	s_add_i32 s33, s67, 0x8000
	s_add_i32 s36, s67, 0xa000
	v_lshl_add_u64 v[16:17], s[58:59], 0, v[130:131]
	global_load_lds_dwordx4 v[10:11], off
	v_lshl_add_u64 v[10:11], v[14:15], 0, s[72:73]
	s_mov_b32 m0, s33
	s_add_u32 s38, s60, 0x40080
	global_load_lds_dwordx4 v[10:11], off
	v_lshl_add_u64 v[10:11], v[16:17], 0, s[72:73]
	s_mov_b32 m0, s36
	s_addc_u32 s39, s61, 0
	global_load_lds_dwordx4 v[10:11], off
	s_add_i32 m0, s67, 0x1c000
	v_lshl_add_u64 v[10:11], s[38:39], 0, v[0:1]
	global_load_lds_dwordx4 v[10:11], off
	v_lshl_add_u64 v[10:11], s[38:39], 0, v[130:131]
	s_add_i32 m0, s67, 0x1e000
	v_bfe_u32 v9, v2, 4, 2
	global_load_lds_dwordx4 v[10:11], off
	v_and_b32_e32 v10, 15, v2
	v_lshlrev_b32_e32 v12, 4, v9
	v_lshlrev_b32_e32 v2, 2, v2
	v_lshl_or_b32 v140, s37, 6, v10
	v_lshl_or_b32 v10, v10, 6, v12
	v_and_b32_e32 v2, 32, v2
	v_bitop3_b32 v12, v10, s34, v2 bitop3:0xde
	v_bitop3_b32 v141, v10, s35, v2 bitop3:0xde
	v_lshlrev_b32_e32 v2, 14, v6
	v_and_b32_e32 v2, 0xffff8000, v2
	v_lshl_add_u32 v2, v7, 11, v2
	v_and_b32_e32 v6, 1, v6
	v_lshl_or_b32 v2, v6, 6, v2
	v_lshl_add_u32 v132, v8, 1, v2
	v_lshlrev_b32_e32 v2, 14, v3
	v_and_b32_e32 v2, 0xffff8000, v2
	s_waitcnt vmcnt(6)
	v_lshl_add_u32 v2, v4, 11, v2
	v_and_b32_e32 v3, 1, v3
	v_lshlrev_b32_e32 v11, 3, v9
	s_cmpk_lt_u32 s20, 0x100
	v_lshl_or_b32 v2, v3, 6, v2
	v_lshl_or_b32 v142, s76, 6, v11
	s_cselect_b64 s[46:47], -1, 0
	s_mov_b32 s37, 0
	v_cmp_eq_u32_e64 s[38:39], 0, v9
	v_mov_b32_e32 v133, v1
	v_lshl_add_u32 v134, v5, 1, v2
	v_mov_b32_e32 v135, v1
	v_add_u32_e32 v143, 0, v12
	v_readlane_b32 s20, v253, 59
	s_movk_i32 s49, 0xc1
	s_barrier
	s_branch .LBB0_166

; #define PG8_STAGE(bufoff, gbase, voff) do { _Pragma("unroll") for (int _i = 0; _i < 2; ++_i) \
;         __builtin_amdgcn_global_load_lds((const unsigned*)((const char*)(gbase) + (voff)[_i]), (LAS unsigned*)(lds + (bufoff) + ldsw + _i * 8192), 16, 0, 0); } while (0)
; #define PG8_STAGEA(bufoff, gbase, voff) do { _Pragma("unroll") for (int _i = 0; _i < 2; ++_i) \
;         __builtin_amdgcn_global_load_lds((const unsigned*)((const char*)(gbase) + (voff)[_i]), (LAS unsigned*)(lds + (bufoff) + ldsw + _i * 8192), 16, 0, 0); } while (0)
; #define PG8_LDA(dst, b, h) do { _Pragma("unroll") for (int m = 0; m < 4; ++m) _Pragma("unroll") for (int k = 0; k < 2; ++k) dst[m][k] = *(const LAS bf16x8*)(lds + PG8_SA(b, h) + aoff + m * 2048 + k * 1024); } while (0)
; #define PG8_LDB(dst, b, h) do { _Pragma("unroll") for (int n = 0; n < 2; ++n) _Pragma("unroll") for (int k = 0; k < 2; ++k) dst[n][k] = *(const LAS bf16x8*)(lds + PG8_SB(b, h) + boff + n * 2048 + k * 1024); } while (0)
; #define PG8_MMA(ai, bj, At, Bt) do { __builtin_amdgcn_s_setprio(3); _Pragma("unroll") for (int m = 0; m < 4; ++m) _Pragma("unroll") for (int n = 0; n < 2; ++n) _Pragma("unroll") for (int k = 0; k < 2; ++k) \
;         acc[ai][bj][m][n] = __builtin_amdgcn_mfma_f32_16x16x32_bf16(Bt[n][k], At[m][k], acc[ai][bj][m][n], 0, 0, 0); __builtin_amdgcn_s_setprio(0); } while (0)
; #define PG8_WAIT_V(n) asm volatile("s_waitcnt vmcnt(" #n ")" ::: "memory")
; #define PG8_WAIT_L(n) asm volatile("s_waitcnt lgkmcnt(" #n ")" ::: "memory")
; #define PG8_BAR __builtin_amdgcn_s_barrier()
; #define PG8_SCHED __builtin_amdgcn_sched_barrier(0)
; template <class Epi, int PARTS>
; __device__ __forceinline__ void gemm_phase(LAS unsigned char* lds, const Gemm g, const StaticOrder& S, const Epi& E) {
;     ...
;             PG8_LDB(B0, 0, 0); PG8_LDB(B1, 0, 1); PG8_SCHED; PG8_LDA(At, 0, 0); PG8_STAGEA(PG8_SA(1, 1), a1 + hstepA, voffA);
;             PG8_WAIT_V(8); PG8_WAIT_L(0); PG8_BAR; PG8_MMA(0, 0, At, B0); PG8_MMA(0, 1, At, B1); PG8_BAR; PG8_SCHED;
;             PG8_LDA(At, 0, 1); PG8_STAGE(PG8_SB(0, 0), b2, voffB); PG8_STAGE(PG8_SB(0, 1), b2 + hstepB, voffB); PG8_STAGEA(PG8_SA(0, 0), a2, voffA);
;             PG8_WAIT_V(8); PG8_WAIT_L(0); PG8_BAR; PG8_MMA(1, 0, At, B0); PG8_MMA(1, 1, At, B1); PG8_BAR; PG8_SCHED;
.Lgprio1:
	s_add_u32 s34, s58, 0xfffc0080
	s_addc_u32 s35, s59, -1
	s_add_i32 s83, 0, 0x10000
	s_cmp_eq_u32 s82, 12
	s_cselect_b32 s63, s51, s35
	s_cselect_b32 s62, s57, s34
	s_cselect_b32 s61, s49, s81
	s_cselect_b32 s60, s77, s80
	s_add_i32 s34, 0, 0x14000
	v_add_u32_e32 v152, s83, v141
	v_add_u32_e32 v168, s83, v141
	ds_read_b128 v[136:139], v152
	ds_read_b128 v[144:147], v152 offset:1024
	ds_read_b128 v[148:151], v152 offset:2048
	ds_read_b128 v[152:155], v152 offset:3072
	ds_read_b128 v[156:159], v168 offset:4096
	ds_read_b128 v[160:163], v168 offset:5120
	ds_read_b128 v[164:167], v168 offset:6144
	ds_read_b128 v[168:171], v168 offset:7168
	v_lshl_add_u64 v[188:189], s[58:59], 0, v[132:133]
	s_add_i32 m0, s67, 0xc000
	ds_read_b128 v[172:175], v143
	ds_read_b128 v[176:179], v143 offset:1024
	ds_read_b128 v[180:183], v143 offset:2048
	ds_read_b128 v[184:187], v143 offset:3072
	ds_read_b128 v[196:199], v143 offset:4096
	ds_read_b128 v[200:203], v143 offset:5120
	ds_read_b128 v[204:207], v143 offset:6144
	ds_read_b128 v[208:211], v143 offset:7168
	global_load_lds_dwordx4 v[188:189], off
	v_lshl_add_u64 v[188:189], s[58:59], 0, v[134:135]
	s_add_i32 m0, s67, 0xe000
	s_nop 0
	global_load_lds_dwordx4 v[188:189], off
	s_waitcnt vmcnt(8)
	s_waitcnt lgkmcnt(0)
	s_barrier
	s_waitcnt lgkmcnt(0)
	v_mfma_f32_16x16x32_bf16 v[126:129], v[136:139], v[172:175], 0
	v_mfma_f32_16x16x32_bf16 v[122:125], v[148:151], v[172:175], 0
	v_mfma_f32_16x16x32_bf16 v[110:113], v[136:139], v[180:183], 0
	v_mfma_f32_16x16x32_bf16 v[106:109], v[148:151], v[180:183], 0
	v_mfma_f32_16x16x32_bf16 v[94:97], v[136:139], v[196:199], 0
	v_mfma_f32_16x16x32_bf16 v[90:93], v[148:151], v[196:199], 0
	v_mfma_f32_16x16x32_bf16 v[78:81], v[136:139], v[204:207], 0
	v_mfma_f32_16x16x32_bf16 v[74:77], v[148:151], v[204:207], 0
	v_mfma_f32_16x16x32_bf16 v[126:129], v[144:147], v[176:179], v[126:129]
	v_mfma_f32_16x16x32_bf16 v[122:125], v[152:155], v[176:179], v[122:125]
	v_mfma_f32_16x16x32_bf16 v[110:113], v[144:147], v[184:187], v[110:113]
	v_mfma_f32_16x16x32_bf16 v[106:109], v[152:155], v[184:187], v[106:109]
	v_mfma_f32_16x16x32_bf16 v[94:97], v[144:147], v[200:203], v[94:97]
	v_mfma_f32_16x16x32_bf16 v[90:93], v[152:155], v[200:203], v[90:93]
	v_mfma_f32_16x16x32_bf16 v[78:81], v[144:147], v[208:211], v[78:81]
	v_mfma_f32_16x16x32_bf16 v[74:77], v[152:155], v[208:211], v[74:77]
	v_mfma_f32_16x16x32_bf16 v[118:121], v[156:159], v[172:175], 0
	v_mfma_f32_16x16x32_bf16 v[114:117], v[164:167], v[172:175], 0
	v_mfma_f32_16x16x32_bf16 v[102:105], v[156:159], v[180:183], 0
	v_mfma_f32_16x16x32_bf16 v[98:101], v[164:167], v[180:183], 0
	v_mfma_f32_16x16x32_bf16 v[86:89], v[156:159], v[196:199], 0
	v_mfma_f32_16x16x32_bf16 v[82:85], v[164:167], v[196:199], 0
	v_mfma_f32_16x16x32_bf16 v[70:73], v[156:159], v[204:207], 0
	v_mfma_f32_16x16x32_bf16 v[66:69], v[164:167], v[204:207], 0
	v_mfma_f32_16x16x32_bf16 v[118:121], v[160:163], v[176:179], v[118:121]
	v_mfma_f32_16x16x32_bf16 v[114:117], v[168:171], v[176:179], v[114:117]
	v_mfma_f32_16x16x32_bf16 v[102:105], v[160:163], v[184:187], v[102:105]
	v_mfma_f32_16x16x32_bf16 v[98:101], v[168:171], v[184:187], v[98:101]
	v_mfma_f32_16x16x32_bf16 v[86:89], v[160:163], v[200:203], v[86:89]
	v_mfma_f32_16x16x32_bf16 v[82:85], v[168:171], v[200:203], v[82:85]
	v_mfma_f32_16x16x32_bf16 v[70:73], v[160:163], v[208:211], v[70:73]
	v_mfma_f32_16x16x32_bf16 v[66:69], v[168:171], v[208:211], v[66:69]
	s_barrier
	s_add_i32 s35, s83, s66
	v_lshl_add_u64 v[188:189], s[60:61], 0, v[0:1]
	s_mov_b32 m0, s35
	ds_read_b128 v[172:175], v143 offset:16384
	ds_read_b128 v[176:179], v143 offset:17408
	ds_read_b128 v[180:183], v143 offset:18432
	ds_read_b128 v[184:187], v143 offset:19456
	ds_read_b128 v[196:199], v143 offset:20480
	ds_read_b128 v[200:203], v143 offset:21504
	ds_read_b128 v[204:207], v143 offset:22528
	ds_read_b128 v[208:211], v143 offset:23552
	global_load_lds_dwordx4 v[188:189], off
	s_add_i32 m0, s35, 0x2000
	s_add_u32 vcc_lo, s60, 0x40000
	v_lshl_add_u64 v[212:213], s[60:61], 0, v[130:131]
	s_addc_u32 vcc_hi, s61, 0
	s_add_i32 s34, s34, s66
	global_load_lds_dwordx4 v[212:213], off
	v_lshl_add_u64 v[214:215], vcc, 0, v[0:1]
	s_mov_b32 m0, s34
	v_lshl_add_u64 v[224:225], s[62:63], 0, v[130:131]
	global_load_lds_dwordx4 v[214:215], off
	v_lshl_add_u64 v[214:215], vcc, 0, v[130:131]
	s_add_i32 m0, s34, 0x2000
	s_nop 0
	global_load_lds_dwordx4 v[214:215], off
	v_lshl_add_u64 v[214:215], s[62:63], 0, v[0:1]
	s_mov_b32 m0, s67
	s_nop 0
	global_load_lds_dwordx4 v[214:215], off
	s_mov_b32 m0, s69
	s_nop 0
	global_load_lds_dwordx4 v[224:225], off
	s_waitcnt vmcnt(8)
	s_waitcnt lgkmcnt(0)
	s_barrier
; #define PG8_STAGEA(bufoff, gbase, voff) do { _Pragma("unroll") for (int _i = 0; _i < 2; ++_i) \
;         __builtin_amdgcn_global_load_lds((const unsigned*)((const char*)(gbase) + (voff)[_i]), (LAS unsigned*)(lds + (bufoff) + ldsw + _i * 8192), 16, 0, 0); } while (0)
; #define PG8_LDA(dst, b, h) do { _Pragma("unroll") for (int m = 0; m < 4; ++m) _Pragma("unroll") for (int k = 0; k < 2; ++k) dst[m][k] = *(const LAS bf16x8*)(lds + PG8_SA(b, h) + aoff + m * 2048 + k * 1024); } while (0)
; #define PG8_LDB(dst, b, h) do { _Pragma("unroll") for (int n = 0; n < 2; ++n) _Pragma("unroll") for (int k = 0; k < 2; ++k) dst[n][k] = *(const LAS bf16x8*)(lds + PG8_SB(b, h) + boff + n * 2048 + k * 1024); } while (0)
; #define PG8_MMA(ai, bj, At, Bt) do { __builtin_amdgcn_s_setprio(3); _Pragma("unroll") for (int m = 0; m < 4; ++m) _Pragma("unroll") for (int n = 0; n < 2; ++n) _Pragma("unroll") for (int k = 0; k < 2; ++k) \
;         acc[ai][bj][m][n] = __builtin_amdgcn_mfma_f32_16x16x32_bf16(Bt[n][k], At[m][k], acc[ai][bj][m][n], 0, 0, 0); __builtin_amdgcn_s_setprio(0); } while (0)
; #define PG8_WAIT_V(n) asm volatile("s_waitcnt vmcnt(" #n ")" ::: "memory")
; #define PG8_WAIT_L(n) asm volatile("s_waitcnt lgkmcnt(" #n ")" ::: "memory")
; #define PG8_BAR __builtin_amdgcn_s_barrier()
; #define PG8_SCHED __builtin_amdgcn_sched_barrier(0)
; template <class Epi, int PARTS>
; __device__ __forceinline__ void gemm_phase(LAS unsigned char* lds, const Gemm g, const StaticOrder& S, const Epi& E) {
;     ...
;             PG8_WAIT_V(8); PG8_WAIT_L(0); PG8_BAR; PG8_MMA(1, 0, At, B0); PG8_MMA(1, 1, At, B1); PG8_BAR; PG8_SCHED;
;             PG8_LDB(B0, 1, 0); PG8_LDB(B1, 1, 1); PG8_SCHED; PG8_LDA(At, 1, 0); PG8_STAGEA(PG8_SA(0, 1), a2 + hstepA, voffA);
;             PG8_WAIT_V(8); PG8_WAIT_L(0); PG8_BAR; PG8_MMA(0, 0, At, B0); PG8_MMA(0, 1, At, B1); PG8_BAR; PG8_SCHED;
	s_waitcnt lgkmcnt(0)
	v_mfma_f32_16x16x32_bf16 v[62:65], v[136:139], v[172:175], 0
	v_mfma_f32_16x16x32_bf16 v[58:61], v[148:151], v[172:175], 0
	v_mfma_f32_16x16x32_bf16 v[46:49], v[136:139], v[180:183], 0
	v_mfma_f32_16x16x32_bf16 v[42:45], v[148:151], v[180:183], 0
	v_mfma_f32_16x16x32_bf16 v[30:33], v[136:139], v[196:199], 0
	v_mfma_f32_16x16x32_bf16 v[26:29], v[148:151], v[196:199], 0
	v_mfma_f32_16x16x32_bf16 v[14:17], v[136:139], v[204:207], 0
	v_mfma_f32_16x16x32_bf16 v[10:13], v[148:151], v[204:207], 0
	v_mfma_f32_16x16x32_bf16 v[62:65], v[144:147], v[176:179], v[62:65]
	v_mfma_f32_16x16x32_bf16 v[58:61], v[152:155], v[176:179], v[58:61]
	v_mfma_f32_16x16x32_bf16 v[46:49], v[144:147], v[184:187], v[46:49]
	v_mfma_f32_16x16x32_bf16 v[42:45], v[152:155], v[184:187], v[42:45]
	v_mfma_f32_16x16x32_bf16 v[30:33], v[144:147], v[200:203], v[30:33]
	v_mfma_f32_16x16x32_bf16 v[26:29], v[152:155], v[200:203], v[26:29]
	v_mfma_f32_16x16x32_bf16 v[14:17], v[144:147], v[208:211], v[14:17]
	v_mfma_f32_16x16x32_bf16 v[10:13], v[152:155], v[208:211], v[10:13]
	v_mfma_f32_16x16x32_bf16 v[54:57], v[156:159], v[172:175], 0
	v_mfma_f32_16x16x32_bf16 v[50:53], v[164:167], v[172:175], 0
	v_mfma_f32_16x16x32_bf16 v[38:41], v[156:159], v[180:183], 0
	v_mfma_f32_16x16x32_bf16 v[34:37], v[164:167], v[180:183], 0
	v_mfma_f32_16x16x32_bf16 v[22:25], v[156:159], v[196:199], 0
	v_mfma_f32_16x16x32_bf16 v[18:21], v[164:167], v[196:199], 0
	v_mfma_f32_16x16x32_bf16 v[6:9], v[156:159], v[204:207], 0
	v_mfma_f32_16x16x32_bf16 v[2:5], v[164:167], v[204:207], 0
	v_mfma_f32_16x16x32_bf16 v[54:57], v[160:163], v[176:179], v[54:57]
	v_mfma_f32_16x16x32_bf16 v[50:53], v[168:171], v[176:179], v[50:53]
	v_mfma_f32_16x16x32_bf16 v[38:41], v[160:163], v[184:187], v[38:41]
	v_mfma_f32_16x16x32_bf16 v[34:37], v[168:171], v[184:187], v[34:37]
	v_mfma_f32_16x16x32_bf16 v[22:25], v[160:163], v[200:203], v[22:25]
	v_mfma_f32_16x16x32_bf16 v[18:21], v[168:171], v[200:203], v[18:21]
	v_mfma_f32_16x16x32_bf16 v[6:9], v[160:163], v[208:211], v[6:9]
	v_mfma_f32_16x16x32_bf16 v[2:5], v[168:171], v[208:211], v[2:5]
	s_barrier
	s_add_i32 s34, 0, 0x18000
	s_add_i32 s35, 0, 0x1c000
	v_add_u32_e32 v152, s34, v141
	v_add_u32_e32 v168, s34, v141
	ds_read_b128 v[136:139], v152
	ds_read_b128 v[144:147], v152 offset:1024
	ds_read_b128 v[148:151], v152 offset:2048
	ds_read_b128 v[152:155], v152 offset:3072
	ds_read_b128 v[156:159], v168 offset:4096
	ds_read_b128 v[160:163], v168 offset:5120
	ds_read_b128 v[164:167], v168 offset:6144
	ds_read_b128 v[168:171], v168 offset:7168
	s_add_u32 s62, s62, 0x40000
	s_addc_u32 s63, s63, 0
	s_mov_b32 m0, s74
	v_lshl_add_u64 v[228:229], s[62:63], 0, v[0:1]
	ds_read_b128 v[172:175], v143 offset:32768
	ds_read_b128 v[176:179], v143 offset:33792
	ds_read_b128 v[180:183], v143 offset:34816
	ds_read_b128 v[184:187], v143 offset:35840
	ds_read_b128 v[196:199], v143 offset:36864
	ds_read_b128 v[200:203], v143 offset:37888
	ds_read_b128 v[204:207], v143 offset:38912
	ds_read_b128 v[208:211], v143 offset:39936
	global_load_lds_dwordx4 v[228:229], off
	v_lshl_add_u64 v[228:229], s[62:63], 0, v[130:131]
	s_mov_b32 m0, s75
	s_nop 0
	global_load_lds_dwordx4 v[228:229], off
	s_waitcnt vmcnt(8)
	s_waitcnt lgkmcnt(0)
	s_barrier
	s_waitcnt lgkmcnt(0)
	v_mfma_f32_16x16x32_bf16 v[126:129], v[136:139], v[172:175], v[126:129]
	v_mfma_f32_16x16x32_bf16 v[122:125], v[148:151], v[172:175], v[122:125]
	v_mfma_f32_16x16x32_bf16 v[110:113], v[136:139], v[180:183], v[110:113]
	v_mfma_f32_16x16x32_bf16 v[106:109], v[148:151], v[180:183], v[106:109]
	v_mfma_f32_16x16x32_bf16 v[94:97], v[136:139], v[196:199], v[94:97]
	v_mfma_f32_16x16x32_bf16 v[90:93], v[148:151], v[196:199], v[90:93]
	v_mfma_f32_16x16x32_bf16 v[78:81], v[136:139], v[204:207], v[78:81]
	v_mfma_f32_16x16x32_bf16 v[74:77], v[148:151], v[204:207], v[74:77]
	v_mfma_f32_16x16x32_bf16 v[126:129], v[144:147], v[176:179], v[126:129]
	v_mfma_f32_16x16x32_bf16 v[122:125], v[152:155], v[176:179], v[122:125]
	v_mfma_f32_16x16x32_bf16 v[110:113], v[144:147], v[184:187], v[110:113]
	v_mfma_f32_16x16x32_bf16 v[106:109], v[152:155], v[184:187], v[106:109]
	v_mfma_f32_16x16x32_bf16 v[94:97], v[144:147], v[200:203], v[94:97]
	v_mfma_f32_16x16x32_bf16 v[90:93], v[152:155], v[200:203], v[90:93]
	v_mfma_f32_16x16x32_bf16 v[78:81], v[144:147], v[208:211], v[78:81]
	v_mfma_f32_16x16x32_bf16 v[74:77], v[152:155], v[208:211], v[74:77]
	v_mfma_f32_16x16x32_bf16 v[118:121], v[156:159], v[172:175], v[118:121]
	v_mfma_f32_16x16x32_bf16 v[114:117], v[164:167], v[172:175], v[114:117]
	v_mfma_f32_16x16x32_bf16 v[102:105], v[156:159], v[180:183], v[102:105]
	v_mfma_f32_16x16x32_bf16 v[98:101], v[164:167], v[180:183], v[98:101]
	v_mfma_f32_16x16x32_bf16 v[86:89], v[156:159], v[196:199], v[86:89]
	v_mfma_f32_16x16x32_bf16 v[82:85], v[164:167], v[196:199], v[82:85]
	v_mfma_f32_16x16x32_bf16 v[70:73], v[156:159], v[204:207], v[70:73]
	v_mfma_f32_16x16x32_bf16 v[66:69], v[164:167], v[204:207], v[66:69]
	v_mfma_f32_16x16x32_bf16 v[118:121], v[160:163], v[176:179], v[118:121]
	v_mfma_f32_16x16x32_bf16 v[114:117], v[168:171], v[176:179], v[114:117]
	v_mfma_f32_16x16x32_bf16 v[102:105], v[160:163], v[184:187], v[102:105]
	v_mfma_f32_16x16x32_bf16 v[98:101], v[168:171], v[184:187], v[98:101]
	v_mfma_f32_16x16x32_bf16 v[86:89], v[160:163], v[200:203], v[86:89]
	v_mfma_f32_16x16x32_bf16 v[82:85], v[168:171], v[200:203], v[82:85]
	v_mfma_f32_16x16x32_bf16 v[70:73], v[160:163], v[208:211], v[70:73]
	v_mfma_f32_16x16x32_bf16 v[66:69], v[168:171], v[208:211], v[66:69]
	s_barrier
; #define PG8_STAGE(bufoff, gbase, voff) do { _Pragma("unroll") for (int _i = 0; _i < 2; ++_i) \
;         __builtin_amdgcn_global_load_lds((const unsigned*)((const char*)(gbase) + (voff)[_i]), (LAS unsigned*)(lds + (bufoff) + ldsw + _i * 8192), 16, 0, 0); } while (0)
; #define PG8_STAGEA(bufoff, gbase, voff) do { _Pragma("unroll") for (int _i = 0; _i < 2; ++_i) \
;         __builtin_amdgcn_global_load_lds((const unsigned*)((const char*)(gbase) + (voff)[_i]), (LAS unsigned*)(lds + (bufoff) + ldsw + _i * 8192), 16, 0, 0); } while (0)
; #define PG8_LDA(dst, b, h) do { _Pragma("unroll") for (int m = 0; m < 4; ++m) _Pragma("unroll") for (int k = 0; k < 2; ++k) dst[m][k] = *(const LAS bf16x8*)(lds + PG8_SA(b, h) + aoff + m * 2048 + k * 1024); } while (0)
; #define PG8_LDB(dst, b, h) do { _Pragma("unroll") for (int n = 0; n < 2; ++n) _Pragma("unroll") for (int k = 0; k < 2; ++k) dst[n][k] = *(const LAS bf16x8*)(lds + PG8_SB(b, h) + boff + n * 2048 + k * 1024); } while (0)
; #define PG8_MMA(ai, bj, At, Bt) do { __builtin_amdgcn_s_setprio(3); _Pragma("unroll") for (int m = 0; m < 4; ++m) _Pragma("unroll") for (int n = 0; n < 2; ++n) _Pragma("unroll") for (int k = 0; k < 2; ++k) \
;         acc[ai][bj][m][n] = __builtin_amdgcn_mfma_f32_16x16x32_bf16(Bt[n][k], At[m][k], acc[ai][bj][m][n], 0, 0, 0); __builtin_amdgcn_s_setprio(0); } while (0)
; #define PG8_WAIT_V(n) asm volatile("s_waitcnt vmcnt(" #n ")" ::: "memory")
; #define PG8_WAIT_L(n) asm volatile("s_waitcnt lgkmcnt(" #n ")" ::: "memory")
; #define PG8_BAR __builtin_amdgcn_s_barrier()
; #define PG8_SCHED __builtin_amdgcn_sched_barrier(0)
; template <class Epi, int PARTS>
; __device__ __forceinline__ void gemm_phase(LAS unsigned char* lds, const Gemm g, const StaticOrder& S, const Epi& E) {
;     ...
;             PG8_LDB(B0, 0, 0); PG8_LDB(B1, 0, 1); PG8_SCHED; PG8_LDA(At, 0, 0); PG8_STAGEA(PG8_SA(1, 1), a1 + hstepA, voffA);
;             PG8_WAIT_V(8); PG8_WAIT_L(0); PG8_BAR; PG8_MMA(0, 0, At, B0); PG8_MMA(0, 1, At, B1); PG8_BAR; PG8_SCHED;
;     ...
;             PG8_LDA(At, 1, 1); PG8_STAGE(PG8_SB(1, 0), b3, voffB); PG8_STAGE(PG8_SB(1, 1), b3 + hstepB, voffB); PG8_STAGEA(PG8_SA(1, 0), a3, voffA);
;             PG8_WAIT_V(8); PG8_WAIT_L(0); PG8_BAR; PG8_MMA(1, 0, At, B0); PG8_MMA(1, 1, At, B1); PG8_BAR; PG8_SCHED;
;         }
	s_add_i32 s34, s34, s66
	v_lshl_add_u64 v[188:189], v[188:189], 0, s[72:73]
	s_mov_b32 m0, s34
	ds_read_b128 v[172:175], v143 offset:49152
	ds_read_b128 v[176:179], v143 offset:50176
	ds_read_b128 v[180:183], v143 offset:51200
	ds_read_b128 v[184:187], v143 offset:52224
	ds_read_b128 v[196:199], v143 offset:53248
	ds_read_b128 v[200:203], v143 offset:54272
	ds_read_b128 v[204:207], v143 offset:55296
	ds_read_b128 v[208:211], v143 offset:56320
	global_load_lds_dwordx4 v[188:189], off
	s_add_i32 m0, s34, 0x2000
	s_add_u32 s60, s60, 0x40080
	v_lshl_add_u64 v[188:189], v[212:213], 0, s[72:73]
	s_addc_u32 s61, s61, 0
	s_add_i32 s34, s35, s66
	global_load_lds_dwordx4 v[188:189], off
	v_lshl_add_u64 v[188:189], s[60:61], 0, v[0:1]
	s_mov_b32 m0, s34
	s_nop 0
	global_load_lds_dwordx4 v[188:189], off
	v_lshl_add_u64 v[188:189], s[60:61], 0, v[130:131]
	s_add_i32 m0, s34, 0x2000
	s_nop 0
	global_load_lds_dwordx4 v[188:189], off
	v_lshl_add_u64 v[188:189], v[214:215], 0, s[72:73]
	s_mov_b32 m0, s33
	s_nop 0
	global_load_lds_dwordx4 v[188:189], off
	v_lshl_add_u64 v[188:189], v[224:225], 0, s[72:73]
	s_mov_b32 m0, s36
	s_nop 0
	global_load_lds_dwordx4 v[188:189], off
	s_waitcnt vmcnt(8)
	s_waitcnt lgkmcnt(0)
	s_barrier
	s_waitcnt lgkmcnt(0)
	v_mfma_f32_16x16x32_bf16 v[62:65], v[136:139], v[172:175], v[62:65]
	v_mfma_f32_16x16x32_bf16 v[58:61], v[148:151], v[172:175], v[58:61]
	v_mfma_f32_16x16x32_bf16 v[46:49], v[136:139], v[180:183], v[46:49]
	v_mfma_f32_16x16x32_bf16 v[42:45], v[148:151], v[180:183], v[42:45]
	v_mfma_f32_16x16x32_bf16 v[30:33], v[136:139], v[196:199], v[30:33]
	v_mfma_f32_16x16x32_bf16 v[26:29], v[148:151], v[196:199], v[26:29]
	v_mfma_f32_16x16x32_bf16 v[14:17], v[136:139], v[204:207], v[14:17]
	v_mfma_f32_16x16x32_bf16 v[10:13], v[148:151], v[204:207], v[10:13]
	v_mfma_f32_16x16x32_bf16 v[62:65], v[144:147], v[176:179], v[62:65]
	v_mfma_f32_16x16x32_bf16 v[58:61], v[152:155], v[176:179], v[58:61]
	v_mfma_f32_16x16x32_bf16 v[46:49], v[144:147], v[184:187], v[46:49]
	v_mfma_f32_16x16x32_bf16 v[42:45], v[152:155], v[184:187], v[42:45]
	v_mfma_f32_16x16x32_bf16 v[30:33], v[144:147], v[200:203], v[30:33]
	v_mfma_f32_16x16x32_bf16 v[26:29], v[152:155], v[200:203], v[26:29]
	v_mfma_f32_16x16x32_bf16 v[14:17], v[144:147], v[208:211], v[14:17]
	v_mfma_f32_16x16x32_bf16 v[10:13], v[152:155], v[208:211], v[10:13]
	v_mfma_f32_16x16x32_bf16 v[54:57], v[156:159], v[172:175], v[54:57]
	v_mfma_f32_16x16x32_bf16 v[50:53], v[164:167], v[172:175], v[50:53]
	v_mfma_f32_16x16x32_bf16 v[38:41], v[156:159], v[180:183], v[38:41]
	v_mfma_f32_16x16x32_bf16 v[34:37], v[164:167], v[180:183], v[34:37]
	v_mfma_f32_16x16x32_bf16 v[22:25], v[156:159], v[196:199], v[22:25]
	v_mfma_f32_16x16x32_bf16 v[18:21], v[164:167], v[196:199], v[18:21]
	v_mfma_f32_16x16x32_bf16 v[6:9], v[156:159], v[204:207], v[6:9]
	v_mfma_f32_16x16x32_bf16 v[2:5], v[164:167], v[204:207], v[2:5]
	v_mfma_f32_16x16x32_bf16 v[54:57], v[160:163], v[176:179], v[54:57]
	v_mfma_f32_16x16x32_bf16 v[50:53], v[168:171], v[176:179], v[50:53]
	v_mfma_f32_16x16x32_bf16 v[38:41], v[160:163], v[184:187], v[38:41]
	v_mfma_f32_16x16x32_bf16 v[34:37], v[168:171], v[184:187], v[34:37]
	v_mfma_f32_16x16x32_bf16 v[22:25], v[160:163], v[200:203], v[22:25]
	v_mfma_f32_16x16x32_bf16 v[18:21], v[168:171], v[200:203], v[18:21]
	v_mfma_f32_16x16x32_bf16 v[6:9], v[160:163], v[208:211], v[6:9]
	v_mfma_f32_16x16x32_bf16 v[2:5], v[168:171], v[208:211], v[2:5]
	s_barrier
	s_add_i32 s82, s82, 2
	s_add_u32 s58, s58, 0x100
	s_addc_u32 s59, s59, 0
	s_add_u32 s80, s80, 0x100
	s_addc_u32 s81, s81, 0
	s_cmp_gt_u32 s82, 13
.LBB0_169:
	s_add_u32 s34, s58, 0xfffc0080
	s_addc_u32 s35, s59, -1
	s_add_i32 s83, 0, 0x10000
	s_cmp_eq_u32 s82, 12
	s_cselect_b32 s63, s51, s35
	s_cselect_b32 s62, s57, s34
	s_cselect_b32 s61, s49, s81
	s_cselect_b32 s60, s77, s80
	s_add_i32 s34, 0, 0x14000
	v_add_u32_e32 v152, s83, v141
	v_add_u32_e32 v168, s83, v141
	ds_read_b128 v[136:139], v152
	ds_read_b128 v[144:147], v152 offset:1024
	ds_read_b128 v[148:151], v152 offset:2048
	ds_read_b128 v[152:155], v152 offset:3072
	ds_read_b128 v[156:159], v168 offset:4096
	ds_read_b128 v[160:163], v168 offset:5120
	ds_read_b128 v[164:167], v168 offset:6144
	ds_read_b128 v[168:171], v168 offset:7168
	v_lshl_add_u64 v[188:189], s[58:59], 0, v[132:133]
	s_add_i32 m0, s67, 0xc000
	ds_read_b128 v[172:175], v143
	ds_read_b128 v[176:179], v143 offset:1024
	ds_read_b128 v[180:183], v143 offset:2048
	ds_read_b128 v[184:187], v143 offset:3072
	ds_read_b128 v[196:199], v143 offset:4096
	ds_read_b128 v[200:203], v143 offset:5120
	ds_read_b128 v[204:207], v143 offset:6144
	ds_read_b128 v[208:211], v143 offset:7168
	global_load_lds_dwordx4 v[188:189], off
	v_lshl_add_u64 v[188:189], s[58:59], 0, v[134:135]
	s_add_i32 m0, s67, 0xe000
	s_nop 0
	global_load_lds_dwordx4 v[188:189], off
	s_waitcnt vmcnt(8)
	s_waitcnt lgkmcnt(0)
	s_barrier
; #define PG8_STAGE(bufoff, gbase, voff) do { _Pragma("unroll") for (int _i = 0; _i < 2; ++_i) \
;         __builtin_amdgcn_global_load_lds((const unsigned*)((const char*)(gbase) + (voff)[_i]), (LAS unsigned*)(lds + (bufoff) + ldsw + _i * 8192), 16, 0, 0); } while (0)
; #define PG8_STAGEA(bufoff, gbase, voff) do { _Pragma("unroll") for (int _i = 0; _i < 2; ++_i) \
;         __builtin_amdgcn_global_load_lds((const unsigned*)((const char*)(gbase) + (voff)[_i]), (LAS unsigned*)(lds + (bufoff) + ldsw + _i * 8192), 16, 0, 0); } while (0)
; #define PG8_LDA(dst, b, h) do { _Pragma("unroll") for (int m = 0; m < 4; ++m) _Pragma("unroll") for (int k = 0; k < 2; ++k) dst[m][k] = *(const LAS bf16x8*)(lds + PG8_SA(b, h) + aoff + m * 2048 + k * 1024); } while (0)
; #define PG8_MMA(ai, bj, At, Bt) do { __builtin_amdgcn_s_setprio(3); _Pragma("unroll") for (int m = 0; m < 4; ++m) _Pragma("unroll") for (int n = 0; n < 2; ++n) _Pragma("unroll") for (int k = 0; k < 2; ++k) \
;         acc[ai][bj][m][n] = __builtin_amdgcn_mfma_f32_16x16x32_bf16(Bt[n][k], At[m][k], acc[ai][bj][m][n], 0, 0, 0); __builtin_amdgcn_s_setprio(0); } while (0)
; #define PG8_WAIT_V(n) asm volatile("s_waitcnt vmcnt(" #n ")" ::: "memory")
; #define PG8_WAIT_L(n) asm volatile("s_waitcnt lgkmcnt(" #n ")" ::: "memory")
; #define PG8_BAR __builtin_amdgcn_s_barrier()
; #define PG8_SCHED __builtin_amdgcn_sched_barrier(0)
; template <class Epi, int PARTS>
; __device__ __forceinline__ void gemm_phase(LAS unsigned char* lds, const Gemm g, const StaticOrder& S, const Epi& E) {
;     ...
;             PG8_WAIT_V(8); PG8_WAIT_L(0); PG8_BAR; PG8_MMA(0, 0, At, B0); PG8_MMA(0, 1, At, B1); PG8_BAR; PG8_SCHED;
;             PG8_LDA(At, 0, 1); PG8_STAGE(PG8_SB(0, 0), b2, voffB); PG8_STAGE(PG8_SB(0, 1), b2 + hstepB, voffB); PG8_STAGEA(PG8_SA(0, 0), a2, voffA);
;             PG8_WAIT_V(8); PG8_WAIT_L(0); PG8_BAR; PG8_MMA(1, 0, At, B0); PG8_MMA(1, 1, At, B1); PG8_BAR; PG8_SCHED;
	s_waitcnt lgkmcnt(0)
	v_mfma_f32_16x16x32_bf16 v[126:129], v[136:139], v[172:175], v[126:129]
	v_mfma_f32_16x16x32_bf16 v[122:125], v[148:151], v[172:175], v[122:125]
	v_mfma_f32_16x16x32_bf16 v[110:113], v[136:139], v[180:183], v[110:113]
	v_mfma_f32_16x16x32_bf16 v[106:109], v[148:151], v[180:183], v[106:109]
	v_mfma_f32_16x16x32_bf16 v[94:97], v[136:139], v[196:199], v[94:97]
	v_mfma_f32_16x16x32_bf16 v[90:93], v[148:151], v[196:199], v[90:93]
	v_mfma_f32_16x16x32_bf16 v[78:81], v[136:139], v[204:207], v[78:81]
	v_mfma_f32_16x16x32_bf16 v[74:77], v[148:151], v[204:207], v[74:77]
	v_mfma_f32_16x16x32_bf16 v[126:129], v[144:147], v[176:179], v[126:129]
	v_mfma_f32_16x16x32_bf16 v[122:125], v[152:155], v[176:179], v[122:125]
	v_mfma_f32_16x16x32_bf16 v[110:113], v[144:147], v[184:187], v[110:113]
	v_mfma_f32_16x16x32_bf16 v[106:109], v[152:155], v[184:187], v[106:109]
	v_mfma_f32_16x16x32_bf16 v[94:97], v[144:147], v[200:203], v[94:97]
	v_mfma_f32_16x16x32_bf16 v[90:93], v[152:155], v[200:203], v[90:93]
	v_mfma_f32_16x16x32_bf16 v[78:81], v[144:147], v[208:211], v[78:81]
	v_mfma_f32_16x16x32_bf16 v[74:77], v[152:155], v[208:211], v[74:77]
	v_mfma_f32_16x16x32_bf16 v[118:121], v[156:159], v[172:175], v[118:121]
	v_mfma_f32_16x16x32_bf16 v[114:117], v[164:167], v[172:175], v[114:117]
	v_mfma_f32_16x16x32_bf16 v[102:105], v[156:159], v[180:183], v[102:105]
	v_mfma_f32_16x16x32_bf16 v[98:101], v[164:167], v[180:183], v[98:101]
	v_mfma_f32_16x16x32_bf16 v[86:89], v[156:159], v[196:199], v[86:89]
	v_mfma_f32_16x16x32_bf16 v[82:85], v[164:167], v[196:199], v[82:85]
	v_mfma_f32_16x16x32_bf16 v[70:73], v[156:159], v[204:207], v[70:73]
	v_mfma_f32_16x16x32_bf16 v[66:69], v[164:167], v[204:207], v[66:69]
	v_mfma_f32_16x16x32_bf16 v[118:121], v[160:163], v[176:179], v[118:121]
	v_mfma_f32_16x16x32_bf16 v[114:117], v[168:171], v[176:179], v[114:117]
	v_mfma_f32_16x16x32_bf16 v[102:105], v[160:163], v[184:187], v[102:105]
	v_mfma_f32_16x16x32_bf16 v[98:101], v[168:171], v[184:187], v[98:101]
	v_mfma_f32_16x16x32_bf16 v[86:89], v[160:163], v[200:203], v[86:89]
	v_mfma_f32_16x16x32_bf16 v[82:85], v[168:171], v[200:203], v[82:85]
	v_mfma_f32_16x16x32_bf16 v[70:73], v[160:163], v[208:211], v[70:73]
	v_mfma_f32_16x16x32_bf16 v[66:69], v[168:171], v[208:211], v[66:69]
	s_barrier
	s_add_i32 s35, s83, s66
	v_lshl_add_u64 v[188:189], s[60:61], 0, v[0:1]
	s_mov_b32 m0, s35
	ds_read_b128 v[172:175], v143 offset:16384
	ds_read_b128 v[176:179], v143 offset:17408
	ds_read_b128 v[180:183], v143 offset:18432
	ds_read_b128 v[184:187], v143 offset:19456
	ds_read_b128 v[196:199], v143 offset:20480
	ds_read_b128 v[200:203], v143 offset:21504
	ds_read_b128 v[204:207], v143 offset:22528
	ds_read_b128 v[208:211], v143 offset:23552
	global_load_lds_dwordx4 v[188:189], off
	s_add_i32 m0, s35, 0x2000
	s_add_u32 vcc_lo, s60, 0x40000
	v_lshl_add_u64 v[212:213], s[60:61], 0, v[130:131]
	s_addc_u32 vcc_hi, s61, 0
	s_add_i32 s34, s34, s66
	global_load_lds_dwordx4 v[212:213], off
	v_lshl_add_u64 v[214:215], vcc, 0, v[0:1]
	s_mov_b32 m0, s34
	v_lshl_add_u64 v[224:225], s[62:63], 0, v[130:131]
	global_load_lds_dwordx4 v[214:215], off
	v_lshl_add_u64 v[214:215], vcc, 0, v[130:131]
	s_add_i32 m0, s34, 0x2000
	s_nop 0
	global_load_lds_dwordx4 v[214:215], off
	v_lshl_add_u64 v[214:215], s[62:63], 0, v[0:1]
	s_mov_b32 m0, s67
	s_nop 0
	global_load_lds_dwordx4 v[214:215], off
	s_mov_b32 m0, s69
	s_nop 0
	global_load_lds_dwordx4 v[224:225], off
	s_waitcnt vmcnt(8)
	s_waitcnt lgkmcnt(0)
	s_barrier
	s_waitcnt lgkmcnt(0)
	v_mfma_f32_16x16x32_bf16 v[62:65], v[136:139], v[172:175], v[62:65]
	v_mfma_f32_16x16x32_bf16 v[58:61], v[148:151], v[172:175], v[58:61]
	v_mfma_f32_16x16x32_bf16 v[46:49], v[136:139], v[180:183], v[46:49]
	v_mfma_f32_16x16x32_bf16 v[42:45], v[148:151], v[180:183], v[42:45]
	v_mfma_f32_16x16x32_bf16 v[30:33], v[136:139], v[196:199], v[30:33]
	v_mfma_f32_16x16x32_bf16 v[26:29], v[148:151], v[196:199], v[26:29]
	v_mfma_f32_16x16x32_bf16 v[14:17], v[136:139], v[204:207], v[14:17]
	v_mfma_f32_16x16x32_bf16 v[10:13], v[148:151], v[204:207], v[10:13]
	v_mfma_f32_16x16x32_bf16 v[62:65], v[144:147], v[176:179], v[62:65]
	v_mfma_f32_16x16x32_bf16 v[58:61], v[152:155], v[176:179], v[58:61]
	v_mfma_f32_16x16x32_bf16 v[46:49], v[144:147], v[184:187], v[46:49]
	v_mfma_f32_16x16x32_bf16 v[42:45], v[152:155], v[184:187], v[42:45]
	v_mfma_f32_16x16x32_bf16 v[30:33], v[144:147], v[200:203], v[30:33]
	v_mfma_f32_16x16x32_bf16 v[26:29], v[152:155], v[200:203], v[26:29]
	v_mfma_f32_16x16x32_bf16 v[14:17], v[144:147], v[208:211], v[14:17]
	v_mfma_f32_16x16x32_bf16 v[10:13], v[152:155], v[208:211], v[10:13]
	v_mfma_f32_16x16x32_bf16 v[54:57], v[156:159], v[172:175], v[54:57]
	v_mfma_f32_16x16x32_bf16 v[50:53], v[164:167], v[172:175], v[50:53]
	v_mfma_f32_16x16x32_bf16 v[38:41], v[156:159], v[180:183], v[38:41]
	v_mfma_f32_16x16x32_bf16 v[34:37], v[164:167], v[180:183], v[34:37]
	v_mfma_f32_16x16x32_bf16 v[22:25], v[156:159], v[196:199], v[22:25]
	v_mfma_f32_16x16x32_bf16 v[18:21], v[164:167], v[196:199], v[18:21]
	v_mfma_f32_16x16x32_bf16 v[6:9], v[156:159], v[204:207], v[6:9]
	v_mfma_f32_16x16x32_bf16 v[2:5], v[164:167], v[204:207], v[2:5]
	v_mfma_f32_16x16x32_bf16 v[54:57], v[160:163], v[176:179], v[54:57]
	v_mfma_f32_16x16x32_bf16 v[50:53], v[168:171], v[176:179], v[50:53]
	v_mfma_f32_16x16x32_bf16 v[38:41], v[160:163], v[184:187], v[38:41]
	v_mfma_f32_16x16x32_bf16 v[34:37], v[168:171], v[184:187], v[34:37]
	v_mfma_f32_16x16x32_bf16 v[22:25], v[160:163], v[200:203], v[22:25]
	v_mfma_f32_16x16x32_bf16 v[18:21], v[168:171], v[200:203], v[18:21]
	v_mfma_f32_16x16x32_bf16 v[6:9], v[160:163], v[208:211], v[6:9]
	v_mfma_f32_16x16x32_bf16 v[2:5], v[168:171], v[208:211], v[2:5]
	s_barrier
; #define PG8_STAGE(bufoff, gbase, voff) do { _Pragma("unroll") for (int _i = 0; _i < 2; ++_i) \
;         __builtin_amdgcn_global_load_lds((const unsigned*)((const char*)(gbase) + (voff)[_i]), (LAS unsigned*)(lds + (bufoff) + ldsw + _i * 8192), 16, 0, 0); } while (0)
; #define PG8_STAGEA(bufoff, gbase, voff) do { _Pragma("unroll") for (int _i = 0; _i < 2; ++_i) \
;         __builtin_amdgcn_global_load_lds((const unsigned*)((const char*)(gbase) + (voff)[_i]), (LAS unsigned*)(lds + (bufoff) + ldsw + _i * 8192), 16, 0, 0); } while (0)
; #define PG8_LDA(dst, b, h) do { _Pragma("unroll") for (int m = 0; m < 4; ++m) _Pragma("unroll") for (int k = 0; k < 2; ++k) dst[m][k] = *(const LAS bf16x8*)(lds + PG8_SA(b, h) + aoff + m * 2048 + k * 1024); } while (0)
; #define PG8_LDB(dst, b, h) do { _Pragma("unroll") for (int n = 0; n < 2; ++n) _Pragma("unroll") for (int k = 0; k < 2; ++k) dst[n][k] = *(const LAS bf16x8*)(lds + PG8_SB(b, h) + boff + n * 2048 + k * 1024); } while (0)
; #define PG8_MMA(ai, bj, At, Bt) do { __builtin_amdgcn_s_setprio(3); _Pragma("unroll") for (int m = 0; m < 4; ++m) _Pragma("unroll") for (int n = 0; n < 2; ++n) _Pragma("unroll") for (int k = 0; k < 2; ++k) \
;         acc[ai][bj][m][n] = __builtin_amdgcn_mfma_f32_16x16x32_bf16(Bt[n][k], At[m][k], acc[ai][bj][m][n], 0, 0, 0); __builtin_amdgcn_s_setprio(0); } while (0)
; #define PG8_WAIT_V(n) asm volatile("s_waitcnt vmcnt(" #n ")" ::: "memory")
; #define PG8_WAIT_L(n) asm volatile("s_waitcnt lgkmcnt(" #n ")" ::: "memory")
; #define PG8_BAR __builtin_amdgcn_s_barrier()
; #define PG8_SCHED __builtin_amdgcn_sched_barrier(0)
; template <class Epi, int PARTS>
; __device__ __forceinline__ void gemm_phase(LAS unsigned char* lds, const Gemm g, const StaticOrder& S, const Epi& E) {
;     ...
;             PG8_LDB(B0, 1, 0); PG8_LDB(B1, 1, 1); PG8_SCHED; PG8_LDA(At, 1, 0); PG8_STAGEA(PG8_SA(0, 1), a2 + hstepA, voffA);
;             PG8_WAIT_V(8); PG8_WAIT_L(0); PG8_BAR; PG8_MMA(0, 0, At, B0); PG8_MMA(0, 1, At, B1); PG8_BAR; PG8_SCHED;
;             PG8_LDA(At, 1, 1); PG8_STAGE(PG8_SB(1, 0), b3, voffB); PG8_STAGE(PG8_SB(1, 1), b3 + hstepB, voffB); PG8_STAGEA(PG8_SA(1, 0), a3, voffA);
	s_add_i32 s34, 0, 0x18000
	s_add_i32 s35, 0, 0x1c000
	v_add_u32_e32 v152, s34, v141
	v_add_u32_e32 v168, s34, v141
	ds_read_b128 v[136:139], v152
	ds_read_b128 v[144:147], v152 offset:1024
	ds_read_b128 v[148:151], v152 offset:2048
	ds_read_b128 v[152:155], v152 offset:3072
	ds_read_b128 v[156:159], v168 offset:4096
	ds_read_b128 v[160:163], v168 offset:5120
	ds_read_b128 v[164:167], v168 offset:6144
	ds_read_b128 v[168:171], v168 offset:7168
	s_add_u32 s62, s62, 0x40000
	s_addc_u32 s63, s63, 0
	s_mov_b32 m0, s74
	v_lshl_add_u64 v[228:229], s[62:63], 0, v[0:1]
	ds_read_b128 v[172:175], v143 offset:32768
	ds_read_b128 v[176:179], v143 offset:33792
	ds_read_b128 v[180:183], v143 offset:34816
	ds_read_b128 v[184:187], v143 offset:35840
	ds_read_b128 v[196:199], v143 offset:36864
	ds_read_b128 v[200:203], v143 offset:37888
	ds_read_b128 v[204:207], v143 offset:38912
	ds_read_b128 v[208:211], v143 offset:39936
	global_load_lds_dwordx4 v[228:229], off
	v_lshl_add_u64 v[228:229], s[62:63], 0, v[130:131]
	s_mov_b32 m0, s75
	s_nop 0
	global_load_lds_dwordx4 v[228:229], off
	s_waitcnt vmcnt(8)
	s_waitcnt lgkmcnt(0)
	s_barrier
	s_waitcnt lgkmcnt(0)
	v_mfma_f32_16x16x32_bf16 v[126:129], v[136:139], v[172:175], v[126:129]
	v_mfma_f32_16x16x32_bf16 v[122:125], v[148:151], v[172:175], v[122:125]
	v_mfma_f32_16x16x32_bf16 v[110:113], v[136:139], v[180:183], v[110:113]
	v_mfma_f32_16x16x32_bf16 v[106:109], v[148:151], v[180:183], v[106:109]
	v_mfma_f32_16x16x32_bf16 v[94:97], v[136:139], v[196:199], v[94:97]
	v_mfma_f32_16x16x32_bf16 v[90:93], v[148:151], v[196:199], v[90:93]
	v_mfma_f32_16x16x32_bf16 v[78:81], v[136:139], v[204:207], v[78:81]
	v_mfma_f32_16x16x32_bf16 v[74:77], v[148:151], v[204:207], v[74:77]
	v_mfma_f32_16x16x32_bf16 v[126:129], v[144:147], v[176:179], v[126:129]
	v_mfma_f32_16x16x32_bf16 v[122:125], v[152:155], v[176:179], v[122:125]
	v_mfma_f32_16x16x32_bf16 v[110:113], v[144:147], v[184:187], v[110:113]
	v_mfma_f32_16x16x32_bf16 v[106:109], v[152:155], v[184:187], v[106:109]
	v_mfma_f32_16x16x32_bf16 v[94:97], v[144:147], v[200:203], v[94:97]
	v_mfma_f32_16x16x32_bf16 v[90:93], v[152:155], v[200:203], v[90:93]
	v_mfma_f32_16x16x32_bf16 v[78:81], v[144:147], v[208:211], v[78:81]
	v_mfma_f32_16x16x32_bf16 v[74:77], v[152:155], v[208:211], v[74:77]
	v_mfma_f32_16x16x32_bf16 v[118:121], v[156:159], v[172:175], v[118:121]
	v_mfma_f32_16x16x32_bf16 v[114:117], v[164:167], v[172:175], v[114:117]
	v_mfma_f32_16x16x32_bf16 v[102:105], v[156:159], v[180:183], v[102:105]
	v_mfma_f32_16x16x32_bf16 v[98:101], v[164:167], v[180:183], v[98:101]
	v_mfma_f32_16x16x32_bf16 v[86:89], v[156:159], v[196:199], v[86:89]
	v_mfma_f32_16x16x32_bf16 v[82:85], v[164:167], v[196:199], v[82:85]
	v_mfma_f32_16x16x32_bf16 v[70:73], v[156:159], v[204:207], v[70:73]
	v_mfma_f32_16x16x32_bf16 v[66:69], v[164:167], v[204:207], v[66:69]
	v_mfma_f32_16x16x32_bf16 v[118:121], v[160:163], v[176:179], v[118:121]
	v_mfma_f32_16x16x32_bf16 v[114:117], v[168:171], v[176:179], v[114:117]
	v_mfma_f32_16x16x32_bf16 v[102:105], v[160:163], v[184:187], v[102:105]
	v_mfma_f32_16x16x32_bf16 v[98:101], v[168:171], v[184:187], v[98:101]
	v_mfma_f32_16x16x32_bf16 v[86:89], v[160:163], v[200:203], v[86:89]
	v_mfma_f32_16x16x32_bf16 v[82:85], v[168:171], v[200:203], v[82:85]
	v_mfma_f32_16x16x32_bf16 v[70:73], v[160:163], v[208:211], v[70:73]
	v_mfma_f32_16x16x32_bf16 v[66:69], v[168:171], v[208:211], v[66:69]
	s_barrier
	s_add_i32 s34, s34, s66
	v_lshl_add_u64 v[188:189], v[188:189], 0, s[72:73]
	s_mov_b32 m0, s34
	ds_read_b128 v[172:175], v143 offset:49152
	ds_read_b128 v[176:179], v143 offset:50176
	ds_read_b128 v[180:183], v143 offset:51200
	ds_read_b128 v[184:187], v143 offset:52224
	ds_read_b128 v[196:199], v143 offset:53248
	ds_read_b128 v[200:203], v143 offset:54272
	ds_read_b128 v[204:207], v143 offset:55296
	ds_read_b128 v[208:211], v143 offset:56320
	global_load_lds_dwordx4 v[188:189], off
	s_add_i32 m0, s34, 0x2000
	s_add_u32 s60, s60, 0x40080
	v_lshl_add_u64 v[188:189], v[212:213], 0, s[72:73]
	s_addc_u32 s61, s61, 0
	s_add_i32 s34, s35, s66
	global_load_lds_dwordx4 v[188:189], off
	v_lshl_add_u64 v[188:189], s[60:61], 0, v[0:1]
	s_mov_b32 m0, s34
	s_nop 0
	global_load_lds_dwordx4 v[188:189], off
	v_lshl_add_u64 v[188:189], s[60:61], 0, v[130:131]
	s_add_i32 m0, s34, 0x2000
	s_nop 0
	global_load_lds_dwordx4 v[188:189], off
	v_lshl_add_u64 v[188:189], v[214:215], 0, s[72:73]
	s_mov_b32 m0, s33
	s_nop 0
	global_load_lds_dwordx4 v[188:189], off
	v_lshl_add_u64 v[188:189], v[224:225], 0, s[72:73]
	s_mov_b32 m0, s36
	s_nop 0
	global_load_lds_dwordx4 v[188:189], off
	s_waitcnt vmcnt(8)
	s_waitcnt lgkmcnt(0)
	s_barrier
; __device__ __forceinline__ unsigned cvt_pk_bf16(float lo, float hi) { f32x2 v = {lo, hi}; bf16x2_t_ b = __builtin_convertvector(v, bf16x2_t_); return __builtin_bit_cast(unsigned, b); }
; __device__ __forceinline__ float bf_lo(unsigned w) { return __uint_as_float(w << 16); }
; __device__ __forceinline__ float bf_hi(unsigned w) { return __uint_as_float(w & 0xffff0000u); }
; #define PG8_WAIT_V(n) asm volatile("s_waitcnt vmcnt(" #n ")" ::: "memory")
; #define PG8_WAIT_L(n) asm volatile("s_waitcnt lgkmcnt(" #n ")" ::: "memory")
; #define PG8_BAR __builtin_amdgcn_s_barrier()
; template <class Epi, int PARTS>
; __device__ __forceinline__ void gemm_phase(LAS unsigned char* lds, const Gemm g, const StaticOrder& S, const Epi& E) {
;     ...
;             PG8_WAIT_V(8); PG8_WAIT_L(0); PG8_BAR; PG8_MMA(1, 0, At, B0); PG8_MMA(1, 1, At, B1); PG8_BAR; PG8_SCHED;
;         }
;         if (wr == 0) PG8_BAR;
;     __device__ __forceinline__ void operator()(f32x4 (&acc)[2][2][4][2], const Unit& u, int wr, int wc, int fr, int fq) const {
;         const int t0 = u.pm * 256 + wr * 64 + fr;
;         const int col0 = 256 * u.pn + 32 * wc + 8 * fq;
;         const float* bp0 = first ? ((t0 < NPROMPT) ? xp + (size_t)t0 * 1024 : xs + (size_t)(t0 - NPROMPT) * 1024) : out + (size_t)t0 * 1024;
; #pragma unroll
;         for (int ai = 0; ai < 2; ++ai)
; #pragma unroll
;             for (int m = 0; m < 4; ++m) {
;                 const int j = 128 * ai + 16 * m; float sq = 0.f;
; #pragma unroll
;                 for (int bj = 0; bj < 2; ++bj) {
;                     const size_t o = (size_t)j * 1024 + col0 + 128 * bj;
;                     f32x4 a, b;
;                     if (bb) { const u32x4 w = *(const u32x4*)(xb + (size_t)t0 * 1024 + o);
;                         a = (f32x4){bf_lo(w.x), bf_hi(w.x), bf_lo(w.y), bf_hi(w.y)}; b = (f32x4){bf_lo(w.z), bf_hi(w.z), bf_lo(w.w), bf_hi(w.w)}; }
;                     else { a = *(const f32x4*)(bp0 + o); b = *(const f32x4*)(bp0 + o + 4); }
;                     a = a + acc[ai][bj][m][0]; b = b + acc[ai][bj][m][1];
;                     if (wout) { float* op = out + (size_t)t0 * 1024 + o; *(f32x4*)op = a; *(f32x4*)(op + 4) = b; }
;                     u32x4 w; w.x = cvt_pk_bf16(a.x, a.y); w.y = cvt_pk_bf16(a.z, a.w); w.z = cvt_pk_bf16(b.x, b.y); w.w = cvt_pk_bf16(b.z, b.w);
;                     *(u32x4*)(xb + (size_t)t0 * 1024 + o) = w;
	s_waitcnt lgkmcnt(0)
	v_mfma_f32_16x16x32_bf16 v[62:65], v[136:139], v[172:175], v[62:65]
	v_mfma_f32_16x16x32_bf16 v[58:61], v[148:151], v[172:175], v[58:61]
	v_mfma_f32_16x16x32_bf16 v[46:49], v[136:139], v[180:183], v[46:49]
	v_mfma_f32_16x16x32_bf16 v[42:45], v[148:151], v[180:183], v[42:45]
	v_mfma_f32_16x16x32_bf16 v[30:33], v[136:139], v[196:199], v[30:33]
	v_mfma_f32_16x16x32_bf16 v[26:29], v[148:151], v[196:199], v[26:29]
	v_mfma_f32_16x16x32_bf16 v[14:17], v[136:139], v[204:207], v[14:17]
	v_mfma_f32_16x16x32_bf16 v[10:13], v[148:151], v[204:207], v[10:13]
	v_mfma_f32_16x16x32_bf16 v[62:65], v[144:147], v[176:179], v[62:65]
	v_mfma_f32_16x16x32_bf16 v[58:61], v[152:155], v[176:179], v[58:61]
	v_mfma_f32_16x16x32_bf16 v[46:49], v[144:147], v[184:187], v[46:49]
	v_mfma_f32_16x16x32_bf16 v[42:45], v[152:155], v[184:187], v[42:45]
	v_mfma_f32_16x16x32_bf16 v[30:33], v[144:147], v[200:203], v[30:33]
	v_mfma_f32_16x16x32_bf16 v[26:29], v[152:155], v[200:203], v[26:29]
	v_mfma_f32_16x16x32_bf16 v[14:17], v[144:147], v[208:211], v[14:17]
	v_mfma_f32_16x16x32_bf16 v[10:13], v[152:155], v[208:211], v[10:13]
	v_mfma_f32_16x16x32_bf16 v[54:57], v[156:159], v[172:175], v[54:57]
	v_mfma_f32_16x16x32_bf16 v[50:53], v[164:167], v[172:175], v[50:53]
	v_mfma_f32_16x16x32_bf16 v[38:41], v[156:159], v[180:183], v[38:41]
	v_mfma_f32_16x16x32_bf16 v[34:37], v[164:167], v[180:183], v[34:37]
	v_mfma_f32_16x16x32_bf16 v[22:25], v[156:159], v[196:199], v[22:25]
	v_mfma_f32_16x16x32_bf16 v[18:21], v[164:167], v[196:199], v[18:21]
	v_mfma_f32_16x16x32_bf16 v[6:9], v[156:159], v[204:207], v[6:9]
	v_mfma_f32_16x16x32_bf16 v[2:5], v[164:167], v[204:207], v[2:5]
	v_mfma_f32_16x16x32_bf16 v[54:57], v[160:163], v[176:179], v[54:57]
	v_mfma_f32_16x16x32_bf16 v[50:53], v[168:171], v[176:179], v[50:53]
	v_mfma_f32_16x16x32_bf16 v[38:41], v[160:163], v[184:187], v[38:41]
	v_mfma_f32_16x16x32_bf16 v[34:37], v[168:171], v[184:187], v[34:37]
	v_mfma_f32_16x16x32_bf16 v[22:25], v[160:163], v[200:203], v[22:25]
	v_mfma_f32_16x16x32_bf16 v[18:21], v[168:171], v[200:203], v[18:21]
	v_mfma_f32_16x16x32_bf16 v[6:9], v[160:163], v[208:211], v[6:9]
	v_mfma_f32_16x16x32_bf16 v[2:5], v[168:171], v[208:211], v[2:5]
	s_barrier
	s_add_i32 s82, s82, 2
	s_add_u32 s58, s58, 0x100
	s_addc_u32 s59, s59, 0
	s_add_u32 s80, s80, 0x100
	s_addc_u32 s81, s81, 0
	s_cmp_gt_u32 s82, 13
	s_cbranch_scc0 .LBB0_169
	s_setprio 0
	s_and_b64 vcc, exec, s[46:47]
	s_cbranch_vccz .LBB0_172
	s_barrier
.LBB0_172:
	v_lshl_add_u32 v138, s56, 8, v140
	v_and_b32_e32 v145, 64, v219
	v_ashrrev_i32_e32 v139, 31, v138
	v_xor_b32_e32 v144, 16, v219
	v_add_u32_e32 v148, 64, v145
	v_lshl_or_b32 v136, s20, 8, v142
	v_lshlrev_b64 v[146:147], 11, v[138:139]
	v_cmp_lt_i32_e32 vcc, v144, v148
	v_ashrrev_i32_e32 v137, 31, v136
	v_lshl_add_u64 v[146:147], s[24:25], 0, v[146:147]
	v_cndmask_b32_e32 v144, v219, v144, vcc
	v_lshlrev_b32_e32 v145, 2, v144
	v_xor_b32_e32 v144, 32, v219
	v_lshl_add_u64 v[136:137], v[136:137], 1, v[146:147]
	v_cmp_lt_i32_e32 vcc, v144, v148
	global_load_dwordx4 v[146:149], v[136:137], off
	s_mov_b32 s101, 0
	global_load_dwordx4 v[154:157], v[136:137], off offset:64
	s_mov_b32 s100, 0x8000
	v_lshl_add_u64 v[240:241], v[136:137], 0, s[100:101]
	global_load_dwordx4 v[158:161], v[240:241], off
	global_load_dwordx4 v[162:165], v[240:241], off offset:64
	s_mov_b32 s100, 0x10000
	v_lshl_add_u64 v[240:241], v[136:137], 0, s[100:101]
	global_load_dwordx4 v[166:169], v[240:241], off
	global_load_dwordx4 v[170:173], v[240:241], off offset:64
	s_mov_b32 s100, 0x18000
	v_lshl_add_u64 v[240:241], v[136:137], 0, s[100:101]
	global_load_dwordx4 v[174:177], v[240:241], off
	global_load_dwordx4 v[178:181], v[240:241], off offset:64
	s_mov_b32 s100, 0x40000
	v_lshl_add_u64 v[240:241], v[136:137], 0, s[100:101]
	global_load_dwordx4 v[182:185], v[240:241], off
	global_load_dwordx4 v[186:189], v[240:241], off offset:64
	s_mov_b32 s100, 0x48000
	v_lshl_add_u64 v[240:241], v[136:137], 0, s[100:101]
	global_load_dwordx4 v[196:199], v[240:241], off
	global_load_dwordx4 v[200:203], v[240:241], off offset:64
	s_mov_b32 s100, 0x50000
	v_lshl_add_u64 v[240:241], v[136:137], 0, s[100:101]
	global_load_dwordx4 v[204:207], v[240:241], off
	global_load_dwordx4 v[208:211], v[240:241], off offset:64
	s_mov_b32 s100, 0x58000
	v_lshl_add_u64 v[240:241], v[136:137], 0, s[100:101]
	global_load_dwordx4 v[212:215], v[240:241], off
	global_load_dwordx4 v[236:239], v[240:241], off offset:64
	v_readlane_b32 s80, v254, 33
	v_cndmask_b32_e32 v144, v219, v144, vcc
	v_lshlrev_b32_e32 v144, 2, v144
	s_lshl_b32 s56, s20, 2
	v_readlane_b32 s81, v254, 34
	s_ashr_i32 s57, s56, 31
	s_waitcnt vmcnt(15)
	v_lshlrev_b32_e32 v150, 16, v146
	v_and_b32_e32 v151, 0xffff0000, v146
	v_lshlrev_b32_e32 v146, 16, v147
	v_and_b32_e32 v147, 0xffff0000, v147
	v_lshlrev_b32_e32 v152, 16, v148
	v_and_b32_e32 v153, 0xffff0000, v148
	v_lshlrev_b32_e32 v148, 16, v149
	v_and_b32_e32 v149, 0xffff0000, v149
	v_pk_add_f32 v[128:129], v[128:129], v[146:147]
	v_pk_add_f32 v[126:127], v[126:127], v[150:151]
	v_pk_add_f32 v[146:147], v[124:125], v[148:149]
	v_pk_add_f32 v[148:149], v[122:123], v[152:153]
	v_cvt_pk_bf16_f32 v122, v126, v127
	v_cvt_pk_bf16_f32 v123, v128, v129
	v_cvt_pk_bf16_f32 v124, v148, v149
	v_cvt_pk_bf16_f32 v125, v146, v147
	global_store_dwordx4 v[136:137], v[122:125], off
	s_nop 1
	v_mul_f32_e32 v122, v127, v127
	v_mul_f32_e32 v123, v129, v129
	v_fmac_f32_e32 v122, v126, v126
	v_fmac_f32_e32 v123, v128, v128
	v_add_f32_e32 v122, v122, v123
	v_mul_f32_e32 v123, v149, v149
	v_fmac_f32_e32 v123, v148, v148
	v_add_f32_e32 v122, v123, v122
	v_mul_f32_e32 v123, v147, v147
	v_fmac_f32_e32 v123, v146, v146
	v_add_f32_e32 v146, v123, v122
	s_waitcnt vmcnt(15)
; __device__ __forceinline__ unsigned cvt_pk_bf16(float lo, float hi) { f32x2 v = {lo, hi}; bf16x2_t_ b = __builtin_convertvector(v, bf16x2_t_); return __builtin_bit_cast(unsigned, b); }
; __device__ __forceinline__ float bf_lo(unsigned w) { return __uint_as_float(w << 16); }
; __device__ __forceinline__ float bf_hi(unsigned w) { return __uint_as_float(w & 0xffff0000u); }
;     __device__ __forceinline__ void operator()(f32x4 (&acc)[2][2][4][2], const Unit& u, int wr, int wc, int fr, int fq) const {
;     ...
;         for (int ai = 0; ai < 2; ++ai)
; #pragma unroll
;             for (int m = 0; m < 4; ++m) {
;                 const int j = 128 * ai + 16 * m; float sq = 0.f;
; #pragma unroll
;                 for (int bj = 0; bj < 2; ++bj) {
;                     const size_t o = (size_t)j * 1024 + col0 + 128 * bj;
;                     f32x4 a, b;
;                     if (bb) { const u32x4 w = *(const u32x4*)(xb + (size_t)t0 * 1024 + o);
;                         a = (f32x4){bf_lo(w.x), bf_hi(w.x), bf_lo(w.y), bf_hi(w.y)}; b = (f32x4){bf_lo(w.z), bf_hi(w.z), bf_lo(w.w), bf_hi(w.w)}; }
;                     else { a = *(const f32x4*)(bp0 + o); b = *(const f32x4*)(bp0 + o + 4); }
;                     a = a + acc[ai][bj][m][0]; b = b + acc[ai][bj][m][1];
;                     if (wout) { float* op = out + (size_t)t0 * 1024 + o; *(f32x4*)op = a; *(f32x4*)(op + 4) = b; }
;                     u32x4 w; w.x = cvt_pk_bf16(a.x, a.y); w.y = cvt_pk_bf16(a.z, a.w); w.z = cvt_pk_bf16(b.x, b.y); w.w = cvt_pk_bf16(b.z, b.w);
;                     *(u32x4*)(xb + (size_t)t0 * 1024 + o) = w;
;                     sq += (a.x * a.x + a.y * a.y) + (a.z * a.z + a.w * a.w) + (b.x * b.x + b.y * b.y) + (b.z * b.z + b.w * b.w);
;                 }
;                 sq += __shfl_xor(sq, 16); sq += __shfl_xor(sq, 32);
;                 if (fq == 0) ss[(size_t)(t0 + j) * 16 + 4 * u.pn + wc] = sq;
	v_mov_b64_e32 v[122:123], v[154:155]
	v_mov_b64_e32 v[124:125], v[156:157]
	v_lshlrev_b32_e32 v126, 16, v122
	v_and_b32_e32 v127, 0xffff0000, v122
	v_lshlrev_b32_e32 v122, 16, v123
	v_and_b32_e32 v123, 0xffff0000, v123
	v_lshlrev_b32_e32 v128, 16, v124
	v_and_b32_e32 v129, 0xffff0000, v124
	v_lshlrev_b32_e32 v124, 16, v125
	v_and_b32_e32 v125, 0xffff0000, v125
	v_pk_add_f32 v[120:121], v[120:121], v[122:123]
	v_pk_add_f32 v[118:119], v[118:119], v[126:127]
	v_pk_add_f32 v[122:123], v[116:117], v[124:125]
	v_pk_add_f32 v[124:125], v[114:115], v[128:129]
	v_cvt_pk_bf16_f32 v114, v118, v119
	v_cvt_pk_bf16_f32 v115, v120, v121
	v_cvt_pk_bf16_f32 v116, v124, v125
	v_cvt_pk_bf16_f32 v117, v122, v123
	global_store_dwordx4 v[136:137], v[114:117], off offset:64
	s_nop 1
	v_mul_f32_e32 v114, v119, v119
	v_mul_f32_e32 v115, v121, v121
	v_fmac_f32_e32 v114, v118, v118
	v_fmac_f32_e32 v115, v120, v120
	v_add_f32_e32 v114, v114, v115
	v_mul_f32_e32 v115, v125, v125
	v_fmac_f32_e32 v115, v124, v124
	v_add_f32_e32 v114, v115, v114
	v_mul_f32_e32 v115, v123, v123
	v_fmac_f32_e32 v115, v122, v122
	v_add_f32_e32 v114, v115, v114
	v_add_f32_e32 v114, v146, v114
	ds_bpermute_b32 v115, v145, v114
	s_waitcnt lgkmcnt(0)
	v_add_f32_e32 v116, v114, v115
	ds_bpermute_b32 v117, v144, v116
	v_lshlrev_b64 v[114:115], 6, v[138:139]
	v_lshl_add_u64 v[114:115], s[80:81], 0, v[114:115]
	s_and_saveexec_b64 s[58:59], s[38:39]
	s_cbranch_execz .LBB0_174
	v_lshl_add_u64 v[118:119], s[56:57], 2, v[114:115]
	s_lshl_b32 s20, s76, 2
	v_lshl_add_u64 v[118:119], v[118:119], 0, s[20:21]
	s_waitcnt lgkmcnt(0)
	v_add_f32_e32 v116, v116, v117
	global_store_dword v[118:119], v116, off
.LBB0_174:
	s_or_b64 exec, exec, s[58:59]
	v_add_co_u32_e32 v120, vcc, 0x8000, v136
	s_nop 1
	v_addc_co_u32_e32 v121, vcc, 0, v137, vcc
	s_waitcnt lgkmcnt(0)
	s_waitcnt vmcnt(15)
	v_mov_b64_e32 v[116:117], v[158:159]
	v_mov_b64_e32 v[118:119], v[160:161]
	v_lshlrev_b32_e32 v122, 16, v116
	v_and_b32_e32 v123, 0xffff0000, v116
	v_lshlrev_b32_e32 v116, 16, v117
	v_and_b32_e32 v117, 0xffff0000, v117
	v_lshlrev_b32_e32 v124, 16, v118
	v_and_b32_e32 v125, 0xffff0000, v118
	v_lshlrev_b32_e32 v118, 16, v119
	v_and_b32_e32 v119, 0xffff0000, v119
	v_pk_add_f32 v[112:113], v[112:113], v[116:117]
	v_pk_add_f32 v[110:111], v[110:111], v[122:123]
	v_pk_add_f32 v[116:117], v[108:109], v[118:119]
	v_pk_add_f32 v[118:119], v[106:107], v[124:125]
	v_cvt_pk_bf16_f32 v106, v110, v111
	v_cvt_pk_bf16_f32 v107, v112, v113
	v_cvt_pk_bf16_f32 v108, v118, v119
	v_cvt_pk_bf16_f32 v109, v116, v117
	global_store_dwordx4 v[120:121], v[106:109], off
	s_nop 1
	v_mul_f32_e32 v106, v111, v111
	v_mul_f32_e32 v107, v113, v113
	v_fmac_f32_e32 v106, v110, v110
	v_fmac_f32_e32 v107, v112, v112
	v_add_f32_e32 v106, v106, v107
	v_mul_f32_e32 v107, v119, v119
	v_fmac_f32_e32 v107, v118, v118
	v_add_f32_e32 v106, v107, v106
	v_mul_f32_e32 v107, v117, v117
	v_fmac_f32_e32 v107, v116, v116
	v_add_f32_e32 v116, v107, v106
	s_waitcnt vmcnt(15)
	v_mov_b64_e32 v[106:107], v[162:163]
	v_mov_b64_e32 v[108:109], v[164:165]
	v_lshlrev_b32_e32 v110, 16, v106
	v_and_b32_e32 v111, 0xffff0000, v106
	v_lshlrev_b32_e32 v106, 16, v107
	v_and_b32_e32 v107, 0xffff0000, v107
	v_lshlrev_b32_e32 v112, 16, v108
	v_and_b32_e32 v113, 0xffff0000, v108
	v_lshlrev_b32_e32 v108, 16, v109
	v_and_b32_e32 v109, 0xffff0000, v109
	v_pk_add_f32 v[104:105], v[104:105], v[106:107]
	v_pk_add_f32 v[102:103], v[102:103], v[110:111]
	v_pk_add_f32 v[106:107], v[100:101], v[108:109]
	v_pk_add_f32 v[108:109], v[98:99], v[112:113]
	v_cvt_pk_bf16_f32 v98, v102, v103
	v_cvt_pk_bf16_f32 v99, v104, v105
	v_cvt_pk_bf16_f32 v100, v108, v109
	v_cvt_pk_bf16_f32 v101, v106, v107
	global_store_dwordx4 v[120:121], v[98:101], off offset:64
	s_nop 1
	v_mul_f32_e32 v98, v103, v103
	v_mul_f32_e32 v99, v105, v105
	v_fmac_f32_e32 v98, v102, v102
	v_fmac_f32_e32 v99, v104, v104
	v_add_f32_e32 v98, v98, v99
	v_mul_f32_e32 v99, v109, v109
	v_fmac_f32_e32 v99, v108, v108
	v_add_f32_e32 v98, v99, v98
	v_mul_f32_e32 v99, v107, v107
	v_fmac_f32_e32 v99, v106, v106
	v_add_f32_e32 v98, v99, v98
	v_add_f32_e32 v98, v116, v98
	ds_bpermute_b32 v99, v145, v98
	s_waitcnt lgkmcnt(0)
	v_add_f32_e32 v98, v98, v99
	ds_bpermute_b32 v99, v144, v98
	s_and_saveexec_b64 s[58:59], s[38:39]
	s_cbranch_execz .LBB0_176
	s_waitcnt lgkmcnt(0)
	v_add_f32_e32 v100, v98, v99
	v_or_b32_e32 v98, 16, v138
	v_ashrrev_i32_e32 v99, 31, v98
	v_lshlrev_b64 v[98:99], 6, v[98:99]
	v_lshl_add_u64 v[98:99], s[80:81], 0, v[98:99]
	v_lshl_add_u64 v[98:99], s[56:57], 2, v[98:99]
	s_lshl_b32 s20, s76, 2
	v_lshl_add_u64 v[98:99], v[98:99], 0, s[20:21]
	global_store_dword v[98:99], v100, off
; __device__ __forceinline__ unsigned cvt_pk_bf16(float lo, float hi) { f32x2 v = {lo, hi}; bf16x2_t_ b = __builtin_convertvector(v, bf16x2_t_); return __builtin_bit_cast(unsigned, b); }
; __device__ __forceinline__ float bf_lo(unsigned w) { return __uint_as_float(w << 16); }
; __device__ __forceinline__ float bf_hi(unsigned w) { return __uint_as_float(w & 0xffff0000u); }
;     __device__ __forceinline__ void operator()(f32x4 (&acc)[2][2][4][2], const Unit& u, int wr, int wc, int fr, int fq) const {
;     ...
;         for (int ai = 0; ai < 2; ++ai)
; #pragma unroll
;             for (int m = 0; m < 4; ++m) {
;                 const int j = 128 * ai + 16 * m; float sq = 0.f;
; #pragma unroll
;                 for (int bj = 0; bj < 2; ++bj) {
;                     const size_t o = (size_t)j * 1024 + col0 + 128 * bj;
;                     f32x4 a, b;
;                     if (bb) { const u32x4 w = *(const u32x4*)(xb + (size_t)t0 * 1024 + o);
;                         a = (f32x4){bf_lo(w.x), bf_hi(w.x), bf_lo(w.y), bf_hi(w.y)}; b = (f32x4){bf_lo(w.z), bf_hi(w.z), bf_lo(w.w), bf_hi(w.w)}; }
;                     else { a = *(const f32x4*)(bp0 + o); b = *(const f32x4*)(bp0 + o + 4); }
;                     a = a + acc[ai][bj][m][0]; b = b + acc[ai][bj][m][1];
;                     if (wout) { float* op = out + (size_t)t0 * 1024 + o; *(f32x4*)op = a; *(f32x4*)(op + 4) = b; }
;                     u32x4 w; w.x = cvt_pk_bf16(a.x, a.y); w.y = cvt_pk_bf16(a.z, a.w); w.z = cvt_pk_bf16(b.x, b.y); w.w = cvt_pk_bf16(b.z, b.w);
;                     *(u32x4*)(xb + (size_t)t0 * 1024 + o) = w;
;                     sq += (a.x * a.x + a.y * a.y) + (a.z * a.z + a.w * a.w) + (b.x * b.x + b.y * b.y) + (b.z * b.z + b.w * b.w);
;                 }
;                 sq += __shfl_xor(sq, 16); sq += __shfl_xor(sq, 32);
;                 if (fq == 0) ss[(size_t)(t0 + j) * 16 + 4 * u.pn + wc] = sq;
.LBB0_176:
	s_or_b64 exec, exec, s[58:59]
	v_add_co_u32_e32 v102, vcc, 0x10000, v136
	s_nop 1
	v_addc_co_u32_e32 v103, vcc, 0, v137, vcc
	s_waitcnt lgkmcnt(0)
	s_waitcnt vmcnt(15)
	v_mov_b64_e32 v[98:99], v[166:167]
	v_mov_b64_e32 v[100:101], v[168:169]
	v_lshlrev_b32_e32 v104, 16, v98
	v_and_b32_e32 v105, 0xffff0000, v98
	v_lshlrev_b32_e32 v98, 16, v99
	v_and_b32_e32 v99, 0xffff0000, v99
	v_lshlrev_b32_e32 v106, 16, v100
	v_and_b32_e32 v107, 0xffff0000, v100
	v_lshlrev_b32_e32 v100, 16, v101
	v_and_b32_e32 v101, 0xffff0000, v101
	v_pk_add_f32 v[96:97], v[96:97], v[98:99]
	v_pk_add_f32 v[94:95], v[94:95], v[104:105]
	v_pk_add_f32 v[98:99], v[92:93], v[100:101]
	v_pk_add_f32 v[100:101], v[90:91], v[106:107]
	v_cvt_pk_bf16_f32 v90, v94, v95
	v_cvt_pk_bf16_f32 v91, v96, v97
	v_cvt_pk_bf16_f32 v92, v100, v101
	v_cvt_pk_bf16_f32 v93, v98, v99
	global_store_dwordx4 v[102:103], v[90:93], off
	s_nop 1
	v_mul_f32_e32 v90, v95, v95
	v_mul_f32_e32 v91, v97, v97
	v_fmac_f32_e32 v90, v94, v94
	v_fmac_f32_e32 v91, v96, v96
	v_add_f32_e32 v90, v90, v91
	v_mul_f32_e32 v91, v101, v101
	v_fmac_f32_e32 v91, v100, v100
	v_add_f32_e32 v90, v91, v90
	v_mul_f32_e32 v91, v99, v99
	v_fmac_f32_e32 v91, v98, v98
	v_add_f32_e32 v98, v91, v90
	s_waitcnt vmcnt(15)
	v_mov_b64_e32 v[90:91], v[170:171]
	v_mov_b64_e32 v[92:93], v[172:173]
	v_lshlrev_b32_e32 v94, 16, v90
	v_and_b32_e32 v95, 0xffff0000, v90
	v_lshlrev_b32_e32 v90, 16, v91
	v_and_b32_e32 v91, 0xffff0000, v91
	v_lshlrev_b32_e32 v96, 16, v92
	v_and_b32_e32 v97, 0xffff0000, v92
	v_lshlrev_b32_e32 v92, 16, v93
	v_and_b32_e32 v93, 0xffff0000, v93
	v_pk_add_f32 v[88:89], v[88:89], v[90:91]
	v_pk_add_f32 v[86:87], v[86:87], v[94:95]
	v_pk_add_f32 v[90:91], v[84:85], v[92:93]
	v_pk_add_f32 v[92:93], v[82:83], v[96:97]
	v_cvt_pk_bf16_f32 v82, v86, v87
	v_cvt_pk_bf16_f32 v83, v88, v89
	v_cvt_pk_bf16_f32 v84, v92, v93
	v_cvt_pk_bf16_f32 v85, v90, v91
	global_store_dwordx4 v[102:103], v[82:85], off offset:64
	s_nop 1
	v_mul_f32_e32 v82, v87, v87
	v_mul_f32_e32 v83, v89, v89
	v_fmac_f32_e32 v82, v86, v86
	v_fmac_f32_e32 v83, v88, v88
	v_add_f32_e32 v82, v82, v83
	v_mul_f32_e32 v83, v93, v93
	v_fmac_f32_e32 v83, v92, v92
	v_add_f32_e32 v82, v83, v82
	v_mul_f32_e32 v83, v91, v91
	v_fmac_f32_e32 v83, v90, v90
	v_add_f32_e32 v82, v83, v82
	v_add_f32_e32 v82, v98, v82
	ds_bpermute_b32 v83, v145, v82
	s_waitcnt lgkmcnt(0)
	v_add_f32_e32 v82, v82, v83
	ds_bpermute_b32 v83, v144, v82
	s_and_saveexec_b64 s[58:59], s[38:39]
	s_movk_i32 s49, 0xc1
	s_cbranch_execz .LBB0_178
	s_waitcnt lgkmcnt(0)
	v_add_f32_e32 v84, v82, v83
	v_or_b32_e32 v82, 32, v138
	v_ashrrev_i32_e32 v83, 31, v82
	v_lshlrev_b64 v[82:83], 6, v[82:83]
	v_lshl_add_u64 v[82:83], s[80:81], 0, v[82:83]
	v_lshl_add_u64 v[82:83], s[56:57], 2, v[82:83]
	s_lshl_b32 s20, s76, 2
	v_lshl_add_u64 v[82:83], v[82:83], 0, s[20:21]
	global_store_dword v[82:83], v84, off
.LBB0_178:
	s_or_b64 exec, exec, s[58:59]
	v_add_co_u32_e32 v86, vcc, 0x18000, v136
	s_nop 1
	v_addc_co_u32_e32 v87, vcc, 0, v137, vcc
	s_waitcnt lgkmcnt(0)
	s_waitcnt vmcnt(15)
	v_mov_b64_e32 v[82:83], v[174:175]
	v_mov_b64_e32 v[84:85], v[176:177]
	v_lshlrev_b32_e32 v88, 16, v82
	v_and_b32_e32 v89, 0xffff0000, v82
	v_lshlrev_b32_e32 v82, 16, v83
	v_and_b32_e32 v83, 0xffff0000, v83
	v_lshlrev_b32_e32 v90, 16, v84
	v_and_b32_e32 v91, 0xffff0000, v84
	v_lshlrev_b32_e32 v84, 16, v85
	v_and_b32_e32 v85, 0xffff0000, v85
	v_pk_add_f32 v[80:81], v[80:81], v[82:83]
	v_pk_add_f32 v[78:79], v[78:79], v[88:89]
	v_pk_add_f32 v[82:83], v[76:77], v[84:85]
	v_pk_add_f32 v[84:85], v[74:75], v[90:91]
	v_cvt_pk_bf16_f32 v74, v78, v79
	v_cvt_pk_bf16_f32 v75, v80, v81
	v_cvt_pk_bf16_f32 v76, v84, v85
	v_cvt_pk_bf16_f32 v77, v82, v83
	global_store_dwordx4 v[86:87], v[74:77], off
	s_nop 1
	v_mul_f32_e32 v74, v79, v79
	v_mul_f32_e32 v75, v81, v81
	v_fmac_f32_e32 v74, v78, v78
	v_fmac_f32_e32 v75, v80, v80
	v_add_f32_e32 v74, v74, v75
	v_mul_f32_e32 v75, v85, v85
	v_fmac_f32_e32 v75, v84, v84
	v_add_f32_e32 v74, v75, v74
	v_mul_f32_e32 v75, v83, v83
	v_fmac_f32_e32 v75, v82, v82
	v_add_f32_e32 v82, v75, v74
	s_waitcnt vmcnt(15)
	v_mov_b64_e32 v[74:75], v[178:179]
	v_mov_b64_e32 v[76:77], v[180:181]
	v_lshlrev_b32_e32 v78, 16, v74
	v_and_b32_e32 v79, 0xffff0000, v74
	v_lshlrev_b32_e32 v74, 16, v75
	v_and_b32_e32 v75, 0xffff0000, v75
	v_lshlrev_b32_e32 v80, 16, v76
	v_and_b32_e32 v81, 0xffff0000, v76
	v_lshlrev_b32_e32 v76, 16, v77
	v_and_b32_e32 v77, 0xffff0000, v77
	v_pk_add_f32 v[72:73], v[72:73], v[74:75]
	v_pk_add_f32 v[70:71], v[70:71], v[78:79]
	v_pk_add_f32 v[74:75], v[68:69], v[76:77]
	v_pk_add_f32 v[76:77], v[66:67], v[80:81]
	v_cvt_pk_bf16_f32 v66, v70, v71
	v_cvt_pk_bf16_f32 v67, v72, v73
	v_cvt_pk_bf16_f32 v68, v76, v77
	v_cvt_pk_bf16_f32 v69, v74, v75
	global_store_dwordx4 v[86:87], v[66:69], off offset:64
	s_nop 1
	v_mul_f32_e32 v66, v71, v71
	v_mul_f32_e32 v67, v73, v73
	v_fmac_f32_e32 v66, v70, v70
	v_fmac_f32_e32 v67, v72, v72
	v_add_f32_e32 v66, v66, v67
	v_mul_f32_e32 v67, v77, v77
	v_fmac_f32_e32 v67, v76, v76
	v_add_f32_e32 v66, v67, v66
	v_mul_f32_e32 v67, v75, v75
	v_fmac_f32_e32 v67, v74, v74
	v_add_f32_e32 v66, v67, v66
	v_add_f32_e32 v66, v82, v66
	ds_bpermute_b32 v67, v145, v66
	s_waitcnt lgkmcnt(0)
	v_add_f32_e32 v66, v66, v67
	ds_bpermute_b32 v67, v144, v66
	s_and_saveexec_b64 s[58:59], s[38:39]
	s_cbranch_execz .LBB0_180
	s_waitcnt lgkmcnt(0)
	v_add_f32_e32 v68, v66, v67
	v_or_b32_e32 v66, 48, v138
	v_ashrrev_i32_e32 v67, 31, v66
	v_lshlrev_b64 v[66:67], 6, v[66:67]
	v_lshl_add_u64 v[66:67], s[80:81], 0, v[66:67]
	v_lshl_add_u64 v[66:67], s[56:57], 2, v[66:67]
	s_lshl_b32 s20, s76, 2
	v_lshl_add_u64 v[66:67], v[66:67], 0, s[20:21]
	global_store_dword v[66:67], v68, off
; __device__ __forceinline__ unsigned cvt_pk_bf16(float lo, float hi) { f32x2 v = {lo, hi}; bf16x2_t_ b = __builtin_convertvector(v, bf16x2_t_); return __builtin_bit_cast(unsigned, b); }
; __device__ __forceinline__ float bf_lo(unsigned w) { return __uint_as_float(w << 16); }
; __device__ __forceinline__ float bf_hi(unsigned w) { return __uint_as_float(w & 0xffff0000u); }
;     __device__ __forceinline__ void operator()(f32x4 (&acc)[2][2][4][2], const Unit& u, int wr, int wc, int fr, int fq) const {
;     ...
;         for (int ai = 0; ai < 2; ++ai)
; #pragma unroll
;             for (int m = 0; m < 4; ++m) {
;                 const int j = 128 * ai + 16 * m; float sq = 0.f;
; #pragma unroll
;                 for (int bj = 0; bj < 2; ++bj) {
;                     const size_t o = (size_t)j * 1024 + col0 + 128 * bj;
;                     f32x4 a, b;
;                     if (bb) { const u32x4 w = *(const u32x4*)(xb + (size_t)t0 * 1024 + o);
;                         a = (f32x4){bf_lo(w.x), bf_hi(w.x), bf_lo(w.y), bf_hi(w.y)}; b = (f32x4){bf_lo(w.z), bf_hi(w.z), bf_lo(w.w), bf_hi(w.w)}; }
;                     else { a = *(const f32x4*)(bp0 + o); b = *(const f32x4*)(bp0 + o + 4); }
;                     a = a + acc[ai][bj][m][0]; b = b + acc[ai][bj][m][1];
;                     if (wout) { float* op = out + (size_t)t0 * 1024 + o; *(f32x4*)op = a; *(f32x4*)(op + 4) = b; }
;                     u32x4 w; w.x = cvt_pk_bf16(a.x, a.y); w.y = cvt_pk_bf16(a.z, a.w); w.z = cvt_pk_bf16(b.x, b.y); w.w = cvt_pk_bf16(b.z, b.w);
;                     *(u32x4*)(xb + (size_t)t0 * 1024 + o) = w;
;                     sq += (a.x * a.x + a.y * a.y) + (a.z * a.z + a.w * a.w) + (b.x * b.x + b.y * b.y) + (b.z * b.z + b.w * b.w);
;                 }
;                 sq += __shfl_xor(sq, 16); sq += __shfl_xor(sq, 32);
;                 if (fq == 0) ss[(size_t)(t0 + j) * 16 + 4 * u.pn + wc] = sq;
.LBB0_180:
	s_or_b64 exec, exec, s[58:59]
	v_add_co_u32_e32 v70, vcc, 0x40000, v136
	s_nop 1
	v_addc_co_u32_e32 v71, vcc, 0, v137, vcc
	s_waitcnt lgkmcnt(0)
	s_waitcnt vmcnt(15)
	v_mov_b64_e32 v[66:67], v[182:183]
	v_mov_b64_e32 v[68:69], v[184:185]
	v_lshlrev_b32_e32 v72, 16, v66
	v_and_b32_e32 v73, 0xffff0000, v66
	v_lshlrev_b32_e32 v66, 16, v67
	v_and_b32_e32 v67, 0xffff0000, v67
	v_lshlrev_b32_e32 v74, 16, v68
	v_and_b32_e32 v75, 0xffff0000, v68
	v_lshlrev_b32_e32 v68, 16, v69
	v_and_b32_e32 v69, 0xffff0000, v69
	v_pk_add_f32 v[64:65], v[64:65], v[66:67]
	v_pk_add_f32 v[62:63], v[62:63], v[72:73]
	v_pk_add_f32 v[66:67], v[60:61], v[68:69]
	v_pk_add_f32 v[68:69], v[58:59], v[74:75]
	v_cvt_pk_bf16_f32 v58, v62, v63
	v_cvt_pk_bf16_f32 v59, v64, v65
	v_cvt_pk_bf16_f32 v60, v68, v69
	v_cvt_pk_bf16_f32 v61, v66, v67
	global_store_dwordx4 v[70:71], v[58:61], off
	s_nop 1
	v_mul_f32_e32 v58, v63, v63
	v_mul_f32_e32 v59, v65, v65
	v_fmac_f32_e32 v58, v62, v62
	v_fmac_f32_e32 v59, v64, v64
	v_add_f32_e32 v58, v58, v59
	v_mul_f32_e32 v59, v69, v69
	v_fmac_f32_e32 v59, v68, v68
	v_add_f32_e32 v58, v59, v58
	v_mul_f32_e32 v59, v67, v67
	v_fmac_f32_e32 v59, v66, v66
	v_add_f32_e32 v66, v59, v58
	s_waitcnt vmcnt(15)
	v_mov_b64_e32 v[58:59], v[186:187]
	v_mov_b64_e32 v[60:61], v[188:189]
	v_lshlrev_b32_e32 v62, 16, v58
	v_and_b32_e32 v63, 0xffff0000, v58
	v_lshlrev_b32_e32 v58, 16, v59
	v_and_b32_e32 v59, 0xffff0000, v59
	v_lshlrev_b32_e32 v64, 16, v60
	v_and_b32_e32 v65, 0xffff0000, v60
	v_lshlrev_b32_e32 v60, 16, v61
	v_and_b32_e32 v61, 0xffff0000, v61
	v_pk_add_f32 v[56:57], v[56:57], v[58:59]
	v_pk_add_f32 v[54:55], v[54:55], v[62:63]
	v_pk_add_f32 v[58:59], v[52:53], v[60:61]
	v_pk_add_f32 v[60:61], v[50:51], v[64:65]
	v_cvt_pk_bf16_f32 v50, v54, v55
	v_cvt_pk_bf16_f32 v51, v56, v57
	v_cvt_pk_bf16_f32 v52, v60, v61
	v_cvt_pk_bf16_f32 v53, v58, v59
	global_store_dwordx4 v[70:71], v[50:53], off offset:64
	s_nop 1
	v_mul_f32_e32 v50, v55, v55
	v_mul_f32_e32 v51, v57, v57
	v_fmac_f32_e32 v50, v54, v54
	v_fmac_f32_e32 v51, v56, v56
	v_add_f32_e32 v50, v50, v51
	v_mul_f32_e32 v51, v61, v61
	v_fmac_f32_e32 v51, v60, v60
	v_add_f32_e32 v50, v51, v50
	v_mul_f32_e32 v51, v59, v59
	v_fmac_f32_e32 v51, v58, v58
	v_add_f32_e32 v50, v51, v50
	v_add_f32_e32 v50, v66, v50
	ds_bpermute_b32 v51, v145, v50
	s_waitcnt lgkmcnt(0)
	v_add_f32_e32 v50, v50, v51
	ds_bpermute_b32 v51, v144, v50
	s_and_saveexec_b64 s[58:59], s[38:39]
	s_cbranch_execz .LBB0_182
	s_waitcnt lgkmcnt(0)
	v_add_f32_e32 v52, v50, v51
	v_lshl_add_u64 v[50:51], s[56:57], 2, v[114:115]
	s_lshl_b32 s20, s76, 2
	v_lshl_add_u64 v[50:51], v[50:51], 0, s[20:21]
	v_add_co_u32_e32 v50, vcc, 0x2000, v50
	s_nop 1
	v_addc_co_u32_e32 v51, vcc, 0, v51, vcc
	global_store_dword v[50:51], v52, off
.LBB0_182:
	s_or_b64 exec, exec, s[58:59]
	v_add_co_u32_e32 v54, vcc, 0x48000, v136
	s_nop 1
	v_addc_co_u32_e32 v55, vcc, 0, v137, vcc
	s_waitcnt lgkmcnt(0)
	s_waitcnt vmcnt(15)
	v_mov_b64_e32 v[50:51], v[196:197]
	v_mov_b64_e32 v[52:53], v[198:199]
	v_lshlrev_b32_e32 v56, 16, v50
	v_and_b32_e32 v57, 0xffff0000, v50
	v_lshlrev_b32_e32 v50, 16, v51
	v_and_b32_e32 v51, 0xffff0000, v51
	v_lshlrev_b32_e32 v58, 16, v52
	v_and_b32_e32 v59, 0xffff0000, v52
	v_lshlrev_b32_e32 v52, 16, v53
	v_and_b32_e32 v53, 0xffff0000, v53
	v_pk_add_f32 v[48:49], v[48:49], v[50:51]
	v_pk_add_f32 v[46:47], v[46:47], v[56:57]
	v_pk_add_f32 v[50:51], v[44:45], v[52:53]
	v_pk_add_f32 v[52:53], v[42:43], v[58:59]
	v_cvt_pk_bf16_f32 v42, v46, v47
	v_cvt_pk_bf16_f32 v43, v48, v49
	v_cvt_pk_bf16_f32 v44, v52, v53
	v_cvt_pk_bf16_f32 v45, v50, v51
	global_store_dwordx4 v[54:55], v[42:45], off
	s_nop 1
	v_mul_f32_e32 v42, v47, v47
	v_mul_f32_e32 v43, v49, v49
	v_fmac_f32_e32 v42, v46, v46
	v_fmac_f32_e32 v43, v48, v48
	v_add_f32_e32 v42, v42, v43
	v_mul_f32_e32 v43, v53, v53
	v_fmac_f32_e32 v43, v52, v52
	v_add_f32_e32 v42, v43, v42
	v_mul_f32_e32 v43, v51, v51
	v_fmac_f32_e32 v43, v50, v50
	v_add_f32_e32 v50, v43, v42
	s_waitcnt vmcnt(15)
	v_mov_b64_e32 v[42:43], v[200:201]
	v_mov_b64_e32 v[44:45], v[202:203]
	v_lshlrev_b32_e32 v46, 16, v42
	v_and_b32_e32 v47, 0xffff0000, v42
	v_lshlrev_b32_e32 v42, 16, v43
	v_and_b32_e32 v43, 0xffff0000, v43
	v_lshlrev_b32_e32 v48, 16, v44
	v_and_b32_e32 v49, 0xffff0000, v44
	v_lshlrev_b32_e32 v44, 16, v45
	v_and_b32_e32 v45, 0xffff0000, v45
	v_pk_add_f32 v[40:41], v[40:41], v[42:43]
	v_pk_add_f32 v[38:39], v[38:39], v[46:47]
	v_pk_add_f32 v[42:43], v[36:37], v[44:45]
	v_pk_add_f32 v[44:45], v[34:35], v[48:49]
	v_cvt_pk_bf16_f32 v34, v38, v39
	v_cvt_pk_bf16_f32 v35, v40, v41
	v_cvt_pk_bf16_f32 v36, v44, v45
	v_cvt_pk_bf16_f32 v37, v42, v43
	global_store_dwordx4 v[54:55], v[34:37], off offset:64
	s_nop 1
	v_mul_f32_e32 v34, v39, v39
	v_mul_f32_e32 v35, v41, v41
	v_fmac_f32_e32 v34, v38, v38
	v_fmac_f32_e32 v35, v40, v40
	v_add_f32_e32 v34, v34, v35
	v_mul_f32_e32 v35, v45, v45
	v_fmac_f32_e32 v35, v44, v44
	v_add_f32_e32 v34, v35, v34
	v_mul_f32_e32 v35, v43, v43
	v_fmac_f32_e32 v35, v42, v42
	v_add_f32_e32 v34, v35, v34
	v_add_f32_e32 v34, v50, v34
	ds_bpermute_b32 v35, v145, v34
	s_waitcnt lgkmcnt(0)
	v_add_f32_e32 v34, v34, v35
	ds_bpermute_b32 v35, v144, v34
	s_and_saveexec_b64 s[58:59], s[38:39]
	s_cbranch_execz .LBB0_184
	s_waitcnt lgkmcnt(0)
	v_add_f32_e32 v36, v34, v35
	v_lshl_add_u64 v[34:35], s[56:57], 2, v[114:115]
	s_lshl_b32 s20, s76, 2
	v_lshl_add_u64 v[34:35], v[34:35], 0, s[20:21]
	v_add_co_u32_e32 v34, vcc, 0x2000, v34
	s_nop 1
	v_addc_co_u32_e32 v35, vcc, 0, v35, vcc
	global_store_dword v[34:35], v36, off offset:1024
; __device__ __forceinline__ unsigned cvt_pk_bf16(float lo, float hi) { f32x2 v = {lo, hi}; bf16x2_t_ b = __builtin_convertvector(v, bf16x2_t_); return __builtin_bit_cast(unsigned, b); }
; __device__ __forceinline__ float bf_lo(unsigned w) { return __uint_as_float(w << 16); }
; __device__ __forceinline__ float bf_hi(unsigned w) { return __uint_as_float(w & 0xffff0000u); }
;     __device__ __forceinline__ void operator()(f32x4 (&acc)[2][2][4][2], const Unit& u, int wr, int wc, int fr, int fq) const {
;     ...
;         for (int ai = 0; ai < 2; ++ai)
; #pragma unroll
;             for (int m = 0; m < 4; ++m) {
;                 const int j = 128 * ai + 16 * m; float sq = 0.f;
; #pragma unroll
;                 for (int bj = 0; bj < 2; ++bj) {
;                     const size_t o = (size_t)j * 1024 + col0 + 128 * bj;
;                     f32x4 a, b;
;                     if (bb) { const u32x4 w = *(const u32x4*)(xb + (size_t)t0 * 1024 + o);
;                         a = (f32x4){bf_lo(w.x), bf_hi(w.x), bf_lo(w.y), bf_hi(w.y)}; b = (f32x4){bf_lo(w.z), bf_hi(w.z), bf_lo(w.w), bf_hi(w.w)}; }
;                     else { a = *(const f32x4*)(bp0 + o); b = *(const f32x4*)(bp0 + o + 4); }
;                     a = a + acc[ai][bj][m][0]; b = b + acc[ai][bj][m][1];
;                     if (wout) { float* op = out + (size_t)t0 * 1024 + o; *(f32x4*)op = a; *(f32x4*)(op + 4) = b; }
;                     u32x4 w; w.x = cvt_pk_bf16(a.x, a.y); w.y = cvt_pk_bf16(a.z, a.w); w.z = cvt_pk_bf16(b.x, b.y); w.w = cvt_pk_bf16(b.z, b.w);
;                     *(u32x4*)(xb + (size_t)t0 * 1024 + o) = w;
;                     sq += (a.x * a.x + a.y * a.y) + (a.z * a.z + a.w * a.w) + (b.x * b.x + b.y * b.y) + (b.z * b.z + b.w * b.w);
;                 }
;                 sq += __shfl_xor(sq, 16); sq += __shfl_xor(sq, 32);
;                 if (fq == 0) ss[(size_t)(t0 + j) * 16 + 4 * u.pn + wc] = sq;
.LBB0_184:
	s_or_b64 exec, exec, s[58:59]
	v_add_co_u32_e32 v38, vcc, 0x50000, v136
	s_nop 1
	v_addc_co_u32_e32 v39, vcc, 0, v137, vcc
	s_waitcnt lgkmcnt(0)
	s_waitcnt vmcnt(15)
	v_mov_b64_e32 v[34:35], v[204:205]
	v_mov_b64_e32 v[36:37], v[206:207]
	v_lshlrev_b32_e32 v40, 16, v34
	v_and_b32_e32 v41, 0xffff0000, v34
	v_lshlrev_b32_e32 v34, 16, v35
	v_and_b32_e32 v35, 0xffff0000, v35
	v_lshlrev_b32_e32 v42, 16, v36
	v_and_b32_e32 v43, 0xffff0000, v36
	v_lshlrev_b32_e32 v36, 16, v37
	v_and_b32_e32 v37, 0xffff0000, v37
	v_pk_add_f32 v[32:33], v[32:33], v[34:35]
	v_pk_add_f32 v[30:31], v[30:31], v[40:41]
	v_pk_add_f32 v[34:35], v[28:29], v[36:37]
	v_pk_add_f32 v[36:37], v[26:27], v[42:43]
	v_cvt_pk_bf16_f32 v26, v30, v31
	v_cvt_pk_bf16_f32 v27, v32, v33
	v_cvt_pk_bf16_f32 v28, v36, v37
	v_cvt_pk_bf16_f32 v29, v34, v35
	global_store_dwordx4 v[38:39], v[26:29], off
	s_nop 1
	v_mul_f32_e32 v26, v31, v31
	v_mul_f32_e32 v27, v33, v33
	v_fmac_f32_e32 v26, v30, v30
	v_fmac_f32_e32 v27, v32, v32
	v_add_f32_e32 v26, v26, v27
	v_mul_f32_e32 v27, v37, v37
	v_fmac_f32_e32 v27, v36, v36
	v_add_f32_e32 v26, v27, v26
	v_mul_f32_e32 v27, v35, v35
	v_fmac_f32_e32 v27, v34, v34
	v_add_f32_e32 v34, v27, v26
	s_waitcnt vmcnt(15)
	v_mov_b64_e32 v[26:27], v[208:209]
	v_mov_b64_e32 v[28:29], v[210:211]
	v_lshlrev_b32_e32 v30, 16, v26
	v_and_b32_e32 v31, 0xffff0000, v26
	v_lshlrev_b32_e32 v26, 16, v27
	v_and_b32_e32 v27, 0xffff0000, v27
	v_lshlrev_b32_e32 v32, 16, v28
	v_and_b32_e32 v33, 0xffff0000, v28
	v_lshlrev_b32_e32 v28, 16, v29
	v_and_b32_e32 v29, 0xffff0000, v29
	v_pk_add_f32 v[24:25], v[24:25], v[26:27]
	v_pk_add_f32 v[22:23], v[22:23], v[30:31]
	v_pk_add_f32 v[26:27], v[20:21], v[28:29]
	v_pk_add_f32 v[28:29], v[18:19], v[32:33]
	v_cvt_pk_bf16_f32 v18, v22, v23
	v_cvt_pk_bf16_f32 v19, v24, v25
	v_cvt_pk_bf16_f32 v20, v28, v29
	v_cvt_pk_bf16_f32 v21, v26, v27
	global_store_dwordx4 v[38:39], v[18:21], off offset:64
	s_nop 1
	v_mul_f32_e32 v18, v23, v23
	v_mul_f32_e32 v19, v25, v25
	v_fmac_f32_e32 v18, v22, v22
	v_fmac_f32_e32 v19, v24, v24
	v_add_f32_e32 v18, v18, v19
	v_mul_f32_e32 v19, v29, v29
	v_fmac_f32_e32 v19, v28, v28
	v_add_f32_e32 v18, v19, v18
	v_mul_f32_e32 v19, v27, v27
	v_fmac_f32_e32 v19, v26, v26
	v_add_f32_e32 v18, v19, v18
	v_add_f32_e32 v18, v34, v18
	ds_bpermute_b32 v19, v145, v18
	s_waitcnt lgkmcnt(0)
	v_add_f32_e32 v18, v18, v19
	ds_bpermute_b32 v19, v144, v18
	s_and_saveexec_b64 s[58:59], s[38:39]
	s_cbranch_execz .LBB0_186
	s_waitcnt lgkmcnt(0)
	v_add_f32_e32 v20, v18, v19
	v_lshl_add_u64 v[18:19], s[56:57], 2, v[114:115]
	s_lshl_b32 s20, s76, 2
	v_lshl_add_u64 v[18:19], v[18:19], 0, s[20:21]
	v_add_co_u32_e32 v18, vcc, 0x2000, v18
	s_nop 1
	v_addc_co_u32_e32 v19, vcc, 0, v19, vcc
	global_store_dword v[18:19], v20, off offset:2048
.LBB0_186:
	s_or_b64 exec, exec, s[58:59]
	v_add_co_u32_e32 v22, vcc, 0x58000, v136
	s_nop 1
	v_addc_co_u32_e32 v23, vcc, 0, v137, vcc
	s_waitcnt lgkmcnt(0)
	s_waitcnt vmcnt(15)
	v_mov_b64_e32 v[18:19], v[212:213]
	v_mov_b64_e32 v[20:21], v[214:215]
	v_lshlrev_b32_e32 v24, 16, v18
	v_and_b32_e32 v25, 0xffff0000, v18
	v_lshlrev_b32_e32 v18, 16, v19
	v_and_b32_e32 v19, 0xffff0000, v19
	v_lshlrev_b32_e32 v26, 16, v20
	v_and_b32_e32 v27, 0xffff0000, v20
	v_lshlrev_b32_e32 v20, 16, v21
	v_and_b32_e32 v21, 0xffff0000, v21
	v_pk_add_f32 v[16:17], v[16:17], v[18:19]
	v_pk_add_f32 v[14:15], v[14:15], v[24:25]
	v_pk_add_f32 v[18:19], v[12:13], v[20:21]
	v_pk_add_f32 v[20:21], v[10:11], v[26:27]
	v_cvt_pk_bf16_f32 v10, v14, v15
	v_cvt_pk_bf16_f32 v11, v16, v17
	v_cvt_pk_bf16_f32 v12, v20, v21
	v_cvt_pk_bf16_f32 v13, v18, v19
	global_store_dwordx4 v[22:23], v[10:13], off
	s_nop 1
	v_mul_f32_e32 v10, v15, v15
	v_mul_f32_e32 v11, v17, v17
	v_fmac_f32_e32 v10, v14, v14
	v_fmac_f32_e32 v11, v16, v16
	v_add_f32_e32 v10, v10, v11
	v_mul_f32_e32 v11, v21, v21
	v_fmac_f32_e32 v11, v20, v20
	v_add_f32_e32 v10, v11, v10
	v_mul_f32_e32 v11, v19, v19
	v_fmac_f32_e32 v11, v18, v18
	v_add_f32_e32 v18, v11, v10
	s_waitcnt vmcnt(15)
	v_mov_b64_e32 v[10:11], v[236:237]
	v_mov_b64_e32 v[12:13], v[238:239]
	v_lshlrev_b32_e32 v14, 16, v10
	v_and_b32_e32 v15, 0xffff0000, v10
	v_lshlrev_b32_e32 v10, 16, v11
	v_and_b32_e32 v11, 0xffff0000, v11
	v_lshlrev_b32_e32 v16, 16, v12
	v_and_b32_e32 v17, 0xffff0000, v12
	v_lshlrev_b32_e32 v12, 16, v13
	v_and_b32_e32 v13, 0xffff0000, v13
	v_pk_add_f32 v[8:9], v[8:9], v[10:11]
	v_pk_add_f32 v[6:7], v[6:7], v[14:15]
	v_pk_add_f32 v[10:11], v[4:5], v[12:13]
	v_pk_add_f32 v[12:13], v[2:3], v[16:17]
	v_cvt_pk_bf16_f32 v2, v6, v7
	v_cvt_pk_bf16_f32 v3, v8, v9
	v_cvt_pk_bf16_f32 v4, v12, v13
	v_cvt_pk_bf16_f32 v5, v10, v11
	global_store_dwordx4 v[22:23], v[2:5], off offset:64
	s_nop 1
	v_mul_f32_e32 v2, v7, v7
	v_mul_f32_e32 v3, v9, v9
	v_fmac_f32_e32 v2, v6, v6
	v_fmac_f32_e32 v3, v8, v8
	v_add_f32_e32 v2, v2, v3
	v_mul_f32_e32 v3, v13, v13
	v_fmac_f32_e32 v3, v12, v12
	v_add_f32_e32 v2, v3, v2
	v_mul_f32_e32 v3, v11, v11
	v_fmac_f32_e32 v3, v10, v10
	v_add_f32_e32 v2, v3, v2
	v_add_f32_e32 v2, v18, v2
	ds_bpermute_b32 v3, v145, v2
	s_waitcnt lgkmcnt(0)
	v_add_f32_e32 v2, v2, v3
	ds_bpermute_b32 v3, v144, v2
	s_and_saveexec_b64 s[58:59], s[38:39]
	s_cbranch_execz .LBB0_188
	s_waitcnt lgkmcnt(0)
	v_add_f32_e32 v4, v2, v3
	v_lshl_add_u64 v[2:3], s[56:57], 2, v[114:115]
	s_lshl_b32 s20, s76, 2
	v_lshl_add_u64 v[2:3], v[2:3], 0, s[20:21]
	v_add_co_u32_e32 v2, vcc, 0x2000, v2
	s_nop 1
	v_addc_co_u32_e32 v3, vcc, 0, v3, vcc
	global_store_dword v[2:3], v4, off offset:3072

; #define PG8_STAGE(bufoff, gbase, voff) do { _Pragma("unroll") for (int _i = 0; _i < 2; ++_i) \
;         __builtin_amdgcn_global_load_lds((const unsigned*)((const char*)(gbase) + (voff)[_i]), (LAS unsigned*)(lds + (bufoff) + ldsw + _i * 8192), 16, 0, 0); } while (0)
; #define PG8_STAGEA(bufoff, gbase, voff) do { _Pragma("unroll") for (int _i = 0; _i < 2; ++_i) \
;         __builtin_amdgcn_global_load_lds((const unsigned*)((const char*)(gbase) + (voff)[_i]), (LAS unsigned*)(lds + (bufoff) + ldsw + _i * 8192), 16, 0, 0); } while (0)
; #define PG8_WAIT_V(n) asm volatile("s_waitcnt vmcnt(" #n ")" ::: "memory")
; #define PG8_BAR __builtin_amdgcn_s_barrier()
; template <class Epi, int PARTS>
; __device__ __forceinline__ void gemm_phase(LAS unsigned char* lds, const Gemm g, const StaticOrder& S, const Epi& E) {
;     ...
;     for (int i = 0; i < 2; ++i) { int R, C; stage_rc(tid * 16 + i * 8192, R, C);
;         const int TR = g.wstride ? g.wstride * (R >> 6) + 8 * (R & 15) + ((R >> 4) & 3) : R;
;         voffA[i] = (unsigned)(TR * g.lda + C) * 2u; voffB[i] = (unsigned)(R * g.ldb + C) * 2u; }
;     const size_t kstep = (size_t)(BK * 2);
;     const size_t hstepA = (size_t)(g.wstride ? 4 : HALF) * g.lda * 2, hstepB = (size_t)HALF * g.ldb * 2;
;     const unsigned ldsw = (unsigned)wid * 1024u;
;     const int aoff = lds_byte(wr * 64 + fr, fq * 8), boff = lds_byte(wc * 32 + fr, fq * 8);
;     ...
;     PG8_STAGE(PG8_SB(1, 0), cB + kstep, voffB); PG8_STAGEA(PG8_SA(1, 0), cA + kstep, voffA); PG8_STAGE(PG8_SB(1, 1), cB + hstepB + kstep, voffB);
;     PG8_WAIT_V(6); PG8_BAR;
.LBB0_263:
	v_lshl_add_u64 v[10:11], s[58:59], 0, v[0:1]
	v_mov_b32_e32 v131, v1
	v_lshl_add_u64 v[12:13], s[58:59], 0, v[130:131]
	s_and_b32 s74, s33, 3
	s_add_i32 m0, s65, 0x18000
	v_lshl_add_u64 v[10:11], v[10:11], 0, s[72:73]
	v_lshl_add_u64 v[14:15], s[56:57], 0, v[0:1]
	s_lshl_b32 s38, s37, 13
	s_lshl_b32 s39, s74, 13
	s_waitcnt vmcnt(2)
	s_barrier
	global_load_lds_dwordx4 v[10:11], off
	v_lshl_add_u64 v[10:11], v[12:13], 0, s[72:73]
	s_add_i32 m0, s65, 0x1a000
	s_add_i32 s33, s65, 0x8000
	s_add_i32 s36, s65, 0xa000
	v_lshl_add_u64 v[16:17], s[56:57], 0, v[130:131]
	global_load_lds_dwordx4 v[10:11], off
	v_lshl_add_u64 v[10:11], v[14:15], 0, s[72:73]
	s_mov_b32 m0, s33
	s_add_u32 s34, s58, 0x80080
	global_load_lds_dwordx4 v[10:11], off
	v_lshl_add_u64 v[10:11], v[16:17], 0, s[72:73]
	s_mov_b32 m0, s36
	s_addc_u32 s35, s59, 0
	global_load_lds_dwordx4 v[10:11], off
	s_add_i32 m0, s65, 0x1c000
	v_lshl_add_u64 v[10:11], s[34:35], 0, v[0:1]
	global_load_lds_dwordx4 v[10:11], off
	v_lshl_add_u64 v[10:11], s[34:35], 0, v[130:131]
	s_add_i32 m0, s65, 0x1e000
	v_bfe_u32 v9, v2, 4, 2
	global_load_lds_dwordx4 v[10:11], off
	v_and_b32_e32 v10, 15, v2
	v_lshlrev_b32_e32 v12, 4, v9
	v_lshlrev_b32_e32 v2, 2, v2
	v_lshl_or_b32 v140, s37, 6, v10
	v_lshl_or_b32 v10, v10, 6, v12
	v_and_b32_e32 v2, 32, v2
	v_bitop3_b32 v12, v10, s38, v2 bitop3:0xde
	v_bitop3_b32 v141, v10, s39, v2 bitop3:0xde
	v_lshlrev_b32_e32 v2, 15, v6
	v_and_b32_e32 v2, 0xffff0000, v2
	v_lshl_add_u32 v2, v7, 12, v2
	v_and_b32_e32 v6, 1, v6
	v_lshl_or_b32 v2, v6, 6, v2
	v_lshl_add_u32 v132, v8, 1, v2
	v_lshlrev_b32_e32 v2, 15, v3
	v_and_b32_e32 v2, 0xffff0000, v2
	s_waitcnt vmcnt(6)
	v_lshl_add_u32 v2, v4, 12, v2
	v_and_b32_e32 v3, 1, v3
	v_lshlrev_b32_e32 v11, 3, v9
	s_cmpk_lt_u32 s20, 0x100
	v_lshl_or_b32 v2, v3, 6, v2
	v_lshl_or_b32 v142, s74, 6, v11
	s_cselect_b64 s[44:45], -1, 0
	s_mov_b32 s37, 0
	v_cmp_eq_u32_e64 s[38:39], 0, v9
	v_mov_b32_e32 v133, v1
	v_lshl_add_u32 v134, v5, 1, v2
	v_mov_b32_e32 v135, v1
	v_add_u32_e32 v143, 0, v12
	v_readlane_b32 s20, v253, 59
	s_movk_i32 s68, 0xc1
	s_barrier
	s_branch .LBB0_342

; #define PG8_STAGE(bufoff, gbase, voff) do { _Pragma("unroll") for (int _i = 0; _i < 2; ++_i) \
;         __builtin_amdgcn_global_load_lds((const unsigned*)((const char*)(gbase) + (voff)[_i]), (LAS unsigned*)(lds + (bufoff) + ldsw + _i * 8192), 16, 0, 0); } while (0)
; #define PG8_STAGEA(bufoff, gbase, voff) do { _Pragma("unroll") for (int _i = 0; _i < 2; ++_i) \
;         __builtin_amdgcn_global_load_lds((const unsigned*)((const char*)(gbase) + (voff)[_i]), (LAS unsigned*)(lds + (bufoff) + ldsw + _i * 8192), 16, 0, 0); } while (0)
; #define PG8_LDA(dst, b, h) do { _Pragma("unroll") for (int m = 0; m < 4; ++m) _Pragma("unroll") for (int k = 0; k < 2; ++k) dst[m][k] = *(const LAS bf16x8*)(lds + PG8_SA(b, h) + aoff + m * 2048 + k * 1024); } while (0)
; #define PG8_LDB(dst, b, h) do { _Pragma("unroll") for (int n = 0; n < 2; ++n) _Pragma("unroll") for (int k = 0; k < 2; ++k) dst[n][k] = *(const LAS bf16x8*)(lds + PG8_SB(b, h) + boff + n * 2048 + k * 1024); } while (0)
; #define PG8_MMA(ai, bj, At, Bt) do { __builtin_amdgcn_s_setprio(3); _Pragma("unroll") for (int m = 0; m < 4; ++m) _Pragma("unroll") for (int n = 0; n < 2; ++n) _Pragma("unroll") for (int k = 0; k < 2; ++k) \
;         acc[ai][bj][m][n] = __builtin_amdgcn_mfma_f32_16x16x32_bf16(Bt[n][k], At[m][k], acc[ai][bj][m][n], 0, 0, 0); __builtin_amdgcn_s_setprio(0); } while (0)
; template <class Epi, int PARTS>
; __device__ __forceinline__ void gemm_phase(LAS unsigned char* lds, const Gemm g, const StaticOrder& S, const Epi& E) {
;     ...
;         for (int t = 0; t < nt; t += 2) {
;             const bool last = (t == nt - 2);
;             const char* a1 = cA + (size_t)(t + 1) * kstep;
;             const char* a2 = last ? nA : cA + (size_t)(t + 2) * kstep; const char* b2 = last ? nB : cB + (size_t)(t + 2) * kstep;
;             const char* a3 = a2 + kstep; const char* b3 = b2 + kstep;
;             PG8_LDB(B0, 0, 0); PG8_LDB(B1, 0, 1); PG8_SCHED; PG8_LDA(At, 0, 0); PG8_STAGEA(PG8_SA(1, 1), a1 + hstepA, voffA);
;             PG8_WAIT_V(8); PG8_WAIT_L(0); PG8_BAR; PG8_MMA(0, 0, At, B0); PG8_MMA(0, 1, At, B1); PG8_BAR; PG8_SCHED;
;             PG8_LDA(At, 0, 1); PG8_STAGE(PG8_SB(0, 0), b2, voffB); PG8_STAGE(PG8_SB(0, 1), b2 + hstepB, voffB); PG8_STAGEA(PG8_SA(0, 0), a2, voffA);
;             PG8_WAIT_V(8); PG8_WAIT_L(0); PG8_BAR; PG8_MMA(1, 0, At, B0); PG8_MMA(1, 1, At, B1); PG8_BAR; PG8_SCHED;
.Lgprio3:
	s_add_u32 s34, s56, 0xfff80080
	s_addc_u32 s35, s57, -1
	s_add_i32 s81, 0, 0x10000
	s_cmp_eq_u32 s80, 28
	s_cselect_b32 s61, s49, s35
	s_cselect_b32 s60, s55, s34
	s_cselect_b32 s59, s47, s77
	s_cselect_b32 s58, s75, s76
	s_add_i32 s82, 0, 0x14000
	v_add_u32_e32 v152, s81, v141
	v_add_u32_e32 v168, s81, v141
	ds_read_b128 v[136:139], v152
	ds_read_b128 v[144:147], v152 offset:1024
	ds_read_b128 v[148:151], v152 offset:2048
	ds_read_b128 v[152:155], v152 offset:3072
	ds_read_b128 v[156:159], v168 offset:4096
	ds_read_b128 v[160:163], v168 offset:5120
	ds_read_b128 v[164:167], v168 offset:6144
	ds_read_b128 v[168:171], v168 offset:7168
	v_lshl_add_u64 v[188:189], s[56:57], 0, v[132:133]
	s_add_i32 m0, s65, 0xc000
	ds_read_b128 v[172:175], v143
	ds_read_b128 v[176:179], v143 offset:1024
	ds_read_b128 v[180:183], v143 offset:2048
	ds_read_b128 v[184:187], v143 offset:3072
	ds_read_b128 v[196:199], v143 offset:4096
	ds_read_b128 v[200:203], v143 offset:5120
	ds_read_b128 v[204:207], v143 offset:6144
	ds_read_b128 v[208:211], v143 offset:7168
	global_load_lds_dwordx4 v[188:189], off
	v_lshl_add_u64 v[188:189], s[56:57], 0, v[134:135]
	s_add_i32 m0, s65, 0xe000
	s_nop 0
	global_load_lds_dwordx4 v[188:189], off
	s_waitcnt vmcnt(8)
	s_waitcnt lgkmcnt(0)
	s_barrier
	s_waitcnt lgkmcnt(0)
	v_mfma_f32_16x16x32_bf16 v[126:129], v[136:139], v[172:175], 0
	v_mfma_f32_16x16x32_bf16 v[122:125], v[148:151], v[172:175], 0
	v_mfma_f32_16x16x32_bf16 v[110:113], v[136:139], v[180:183], 0
	v_mfma_f32_16x16x32_bf16 v[106:109], v[148:151], v[180:183], 0
	v_mfma_f32_16x16x32_bf16 v[94:97], v[136:139], v[196:199], 0
	v_mfma_f32_16x16x32_bf16 v[90:93], v[148:151], v[196:199], 0
	v_mfma_f32_16x16x32_bf16 v[78:81], v[136:139], v[204:207], 0
	v_mfma_f32_16x16x32_bf16 v[74:77], v[148:151], v[204:207], 0
	v_mfma_f32_16x16x32_bf16 v[126:129], v[144:147], v[176:179], v[126:129]
	v_mfma_f32_16x16x32_bf16 v[122:125], v[152:155], v[176:179], v[122:125]
	v_mfma_f32_16x16x32_bf16 v[110:113], v[144:147], v[184:187], v[110:113]
	v_mfma_f32_16x16x32_bf16 v[106:109], v[152:155], v[184:187], v[106:109]
	v_mfma_f32_16x16x32_bf16 v[94:97], v[144:147], v[200:203], v[94:97]
	v_mfma_f32_16x16x32_bf16 v[90:93], v[152:155], v[200:203], v[90:93]
	v_mfma_f32_16x16x32_bf16 v[78:81], v[144:147], v[208:211], v[78:81]
	v_mfma_f32_16x16x32_bf16 v[74:77], v[152:155], v[208:211], v[74:77]
	v_mfma_f32_16x16x32_bf16 v[118:121], v[156:159], v[172:175], 0
	v_mfma_f32_16x16x32_bf16 v[114:117], v[164:167], v[172:175], 0
	v_mfma_f32_16x16x32_bf16 v[102:105], v[156:159], v[180:183], 0
	v_mfma_f32_16x16x32_bf16 v[98:101], v[164:167], v[180:183], 0
	v_mfma_f32_16x16x32_bf16 v[86:89], v[156:159], v[196:199], 0
	v_mfma_f32_16x16x32_bf16 v[82:85], v[164:167], v[196:199], 0
	v_mfma_f32_16x16x32_bf16 v[70:73], v[156:159], v[204:207], 0
	v_mfma_f32_16x16x32_bf16 v[66:69], v[164:167], v[204:207], 0
	v_mfma_f32_16x16x32_bf16 v[118:121], v[160:163], v[176:179], v[118:121]
	v_mfma_f32_16x16x32_bf16 v[114:117], v[168:171], v[176:179], v[114:117]
	v_mfma_f32_16x16x32_bf16 v[102:105], v[160:163], v[184:187], v[102:105]
	v_mfma_f32_16x16x32_bf16 v[98:101], v[168:171], v[184:187], v[98:101]
	v_mfma_f32_16x16x32_bf16 v[86:89], v[160:163], v[200:203], v[86:89]
	v_mfma_f32_16x16x32_bf16 v[82:85], v[168:171], v[200:203], v[82:85]
	v_mfma_f32_16x16x32_bf16 v[70:73], v[160:163], v[208:211], v[70:73]
	v_mfma_f32_16x16x32_bf16 v[66:69], v[168:171], v[208:211], v[66:69]
	s_barrier
	s_add_i32 s34, s81, s64
	v_lshl_add_u64 v[188:189], s[58:59], 0, v[0:1]
	s_mov_b32 m0, s34
	ds_read_b128 v[172:175], v143 offset:16384
	ds_read_b128 v[176:179], v143 offset:17408
	ds_read_b128 v[180:183], v143 offset:18432
	ds_read_b128 v[184:187], v143 offset:19456
	ds_read_b128 v[196:199], v143 offset:20480
	ds_read_b128 v[200:203], v143 offset:21504
	ds_read_b128 v[204:207], v143 offset:22528
	ds_read_b128 v[208:211], v143 offset:23552
	global_load_lds_dwordx4 v[188:189], off
	s_add_i32 m0, s34, 0x2000
	s_add_u32 s34, s58, 0x80000
	v_lshl_add_u64 v[212:213], s[58:59], 0, v[130:131]
	s_addc_u32 s35, s59, 0
	s_add_i32 s81, s82, s64
	global_load_lds_dwordx4 v[212:213], off
	v_lshl_add_u64 v[214:215], s[34:35], 0, v[0:1]
	s_mov_b32 m0, s81
	v_lshl_add_u64 v[224:225], s[60:61], 0, v[130:131]
	global_load_lds_dwordx4 v[214:215], off
	v_lshl_add_u64 v[214:215], s[34:35], 0, v[130:131]
	s_add_i32 m0, s81, 0x2000
	s_nop 0
	global_load_lds_dwordx4 v[214:215], off
	v_lshl_add_u64 v[214:215], s[60:61], 0, v[0:1]
	s_mov_b32 m0, s65
	s_nop 0
	global_load_lds_dwordx4 v[214:215], off
	s_mov_b32 m0, s66
	s_nop 0
	global_load_lds_dwordx4 v[224:225], off
	s_waitcnt vmcnt(8)
	s_waitcnt lgkmcnt(0)
	s_barrier
; #define PG8_STAGE(bufoff, gbase, voff) do { _Pragma("unroll") for (int _i = 0; _i < 2; ++_i) \
;         __builtin_amdgcn_global_load_lds((const unsigned*)((const char*)(gbase) + (voff)[_i]), (LAS unsigned*)(lds + (bufoff) + ldsw + _i * 8192), 16, 0, 0); } while (0)
; #define PG8_STAGEA(bufoff, gbase, voff) do { _Pragma("unroll") for (int _i = 0; _i < 2; ++_i) \
;         __builtin_amdgcn_global_load_lds((const unsigned*)((const char*)(gbase) + (voff)[_i]), (LAS unsigned*)(lds + (bufoff) + ldsw + _i * 8192), 16, 0, 0); } while (0)
; #define PG8_LDA(dst, b, h) do { _Pragma("unroll") for (int m = 0; m < 4; ++m) _Pragma("unroll") for (int k = 0; k < 2; ++k) dst[m][k] = *(const LAS bf16x8*)(lds + PG8_SA(b, h) + aoff + m * 2048 + k * 1024); } while (0)
; #define PG8_LDB(dst, b, h) do { _Pragma("unroll") for (int n = 0; n < 2; ++n) _Pragma("unroll") for (int k = 0; k < 2; ++k) dst[n][k] = *(const LAS bf16x8*)(lds + PG8_SB(b, h) + boff + n * 2048 + k * 1024); } while (0)
; #define PG8_MMA(ai, bj, At, Bt) do { __builtin_amdgcn_s_setprio(3); _Pragma("unroll") for (int m = 0; m < 4; ++m) _Pragma("unroll") for (int n = 0; n < 2; ++n) _Pragma("unroll") for (int k = 0; k < 2; ++k) \
;         acc[ai][bj][m][n] = __builtin_amdgcn_mfma_f32_16x16x32_bf16(Bt[n][k], At[m][k], acc[ai][bj][m][n], 0, 0, 0); __builtin_amdgcn_s_setprio(0); } while (0)
; #define PG8_WAIT_V(n) asm volatile("s_waitcnt vmcnt(" #n ")" ::: "memory")
; #define PG8_WAIT_L(n) asm volatile("s_waitcnt lgkmcnt(" #n ")" ::: "memory")
; #define PG8_BAR __builtin_amdgcn_s_barrier()
; #define PG8_SCHED __builtin_amdgcn_sched_barrier(0)
; template <class Epi, int PARTS>
; __device__ __forceinline__ void gemm_phase(LAS unsigned char* lds, const Gemm g, const StaticOrder& S, const Epi& E) {
;     ...
;             PG8_WAIT_V(8); PG8_WAIT_L(0); PG8_BAR; PG8_MMA(1, 0, At, B0); PG8_MMA(1, 1, At, B1); PG8_BAR; PG8_SCHED;
;             PG8_LDB(B0, 1, 0); PG8_LDB(B1, 1, 1); PG8_SCHED; PG8_LDA(At, 1, 0); PG8_STAGEA(PG8_SA(0, 1), a2 + hstepA, voffA);
;             PG8_WAIT_V(8); PG8_WAIT_L(0); PG8_BAR; PG8_MMA(0, 0, At, B0); PG8_MMA(0, 1, At, B1); PG8_BAR; PG8_SCHED;
;             PG8_LDA(At, 1, 1); PG8_STAGE(PG8_SB(1, 0), b3, voffB); PG8_STAGE(PG8_SB(1, 1), b3 + hstepB, voffB); PG8_STAGEA(PG8_SA(1, 0), a3, voffA);
	s_waitcnt lgkmcnt(0)
	v_mfma_f32_16x16x32_bf16 v[62:65], v[136:139], v[172:175], 0
	v_mfma_f32_16x16x32_bf16 v[58:61], v[148:151], v[172:175], 0
	v_mfma_f32_16x16x32_bf16 v[46:49], v[136:139], v[180:183], 0
	v_mfma_f32_16x16x32_bf16 v[42:45], v[148:151], v[180:183], 0
	v_mfma_f32_16x16x32_bf16 v[30:33], v[136:139], v[196:199], 0
	v_mfma_f32_16x16x32_bf16 v[26:29], v[148:151], v[196:199], 0
	v_mfma_f32_16x16x32_bf16 v[14:17], v[136:139], v[204:207], 0
	v_mfma_f32_16x16x32_bf16 v[10:13], v[148:151], v[204:207], 0
	v_mfma_f32_16x16x32_bf16 v[62:65], v[144:147], v[176:179], v[62:65]
	v_mfma_f32_16x16x32_bf16 v[58:61], v[152:155], v[176:179], v[58:61]
	v_mfma_f32_16x16x32_bf16 v[46:49], v[144:147], v[184:187], v[46:49]
	v_mfma_f32_16x16x32_bf16 v[42:45], v[152:155], v[184:187], v[42:45]
	v_mfma_f32_16x16x32_bf16 v[30:33], v[144:147], v[200:203], v[30:33]
	v_mfma_f32_16x16x32_bf16 v[26:29], v[152:155], v[200:203], v[26:29]
	v_mfma_f32_16x16x32_bf16 v[14:17], v[144:147], v[208:211], v[14:17]
	v_mfma_f32_16x16x32_bf16 v[10:13], v[152:155], v[208:211], v[10:13]
	v_mfma_f32_16x16x32_bf16 v[54:57], v[156:159], v[172:175], 0
	v_mfma_f32_16x16x32_bf16 v[50:53], v[164:167], v[172:175], 0
	v_mfma_f32_16x16x32_bf16 v[38:41], v[156:159], v[180:183], 0
	v_mfma_f32_16x16x32_bf16 v[34:37], v[164:167], v[180:183], 0
	v_mfma_f32_16x16x32_bf16 v[22:25], v[156:159], v[196:199], 0
	v_mfma_f32_16x16x32_bf16 v[18:21], v[164:167], v[196:199], 0
	v_mfma_f32_16x16x32_bf16 v[6:9], v[156:159], v[204:207], 0
	v_mfma_f32_16x16x32_bf16 v[2:5], v[164:167], v[204:207], 0
	v_mfma_f32_16x16x32_bf16 v[54:57], v[160:163], v[176:179], v[54:57]
	v_mfma_f32_16x16x32_bf16 v[50:53], v[168:171], v[176:179], v[50:53]
	v_mfma_f32_16x16x32_bf16 v[38:41], v[160:163], v[184:187], v[38:41]
	v_mfma_f32_16x16x32_bf16 v[34:37], v[168:171], v[184:187], v[34:37]
	v_mfma_f32_16x16x32_bf16 v[22:25], v[160:163], v[200:203], v[22:25]
	v_mfma_f32_16x16x32_bf16 v[18:21], v[168:171], v[200:203], v[18:21]
	v_mfma_f32_16x16x32_bf16 v[6:9], v[160:163], v[208:211], v[6:9]
	v_mfma_f32_16x16x32_bf16 v[2:5], v[168:171], v[208:211], v[2:5]
	s_barrier
	s_add_i32 s81, 0, 0x18000
	s_add_i32 s82, 0, 0x1c000
	v_add_u32_e32 v152, s81, v141
	v_add_u32_e32 v168, s81, v141
	ds_read_b128 v[136:139], v152
	ds_read_b128 v[144:147], v152 offset:1024
	ds_read_b128 v[148:151], v152 offset:2048
	ds_read_b128 v[152:155], v152 offset:3072
	ds_read_b128 v[156:159], v168 offset:4096
	ds_read_b128 v[160:163], v168 offset:5120
	ds_read_b128 v[164:167], v168 offset:6144
	ds_read_b128 v[168:171], v168 offset:7168
	s_add_u32 s34, s60, 0x80000
	s_addc_u32 s35, s61, 0
	s_mov_b32 m0, s67
	v_lshl_add_u64 v[228:229], s[34:35], 0, v[0:1]
	ds_read_b128 v[172:175], v143 offset:32768
	ds_read_b128 v[176:179], v143 offset:33792
	ds_read_b128 v[180:183], v143 offset:34816
	ds_read_b128 v[184:187], v143 offset:35840
	ds_read_b128 v[196:199], v143 offset:36864
	ds_read_b128 v[200:203], v143 offset:37888
	ds_read_b128 v[204:207], v143 offset:38912
	ds_read_b128 v[208:211], v143 offset:39936
	global_load_lds_dwordx4 v[228:229], off
	v_lshl_add_u64 v[228:229], s[34:35], 0, v[130:131]
	s_mov_b32 m0, s69
	s_nop 0
	global_load_lds_dwordx4 v[228:229], off
	s_waitcnt vmcnt(8)
	s_waitcnt lgkmcnt(0)
	s_barrier
	s_waitcnt lgkmcnt(0)
	v_mfma_f32_16x16x32_bf16 v[126:129], v[136:139], v[172:175], v[126:129]
	v_mfma_f32_16x16x32_bf16 v[122:125], v[148:151], v[172:175], v[122:125]
	v_mfma_f32_16x16x32_bf16 v[110:113], v[136:139], v[180:183], v[110:113]
	v_mfma_f32_16x16x32_bf16 v[106:109], v[148:151], v[180:183], v[106:109]
	v_mfma_f32_16x16x32_bf16 v[94:97], v[136:139], v[196:199], v[94:97]
	v_mfma_f32_16x16x32_bf16 v[90:93], v[148:151], v[196:199], v[90:93]
	v_mfma_f32_16x16x32_bf16 v[78:81], v[136:139], v[204:207], v[78:81]
	v_mfma_f32_16x16x32_bf16 v[74:77], v[148:151], v[204:207], v[74:77]
	v_mfma_f32_16x16x32_bf16 v[126:129], v[144:147], v[176:179], v[126:129]
	v_mfma_f32_16x16x32_bf16 v[122:125], v[152:155], v[176:179], v[122:125]
	v_mfma_f32_16x16x32_bf16 v[110:113], v[144:147], v[184:187], v[110:113]
	v_mfma_f32_16x16x32_bf16 v[106:109], v[152:155], v[184:187], v[106:109]
	v_mfma_f32_16x16x32_bf16 v[94:97], v[144:147], v[200:203], v[94:97]
	v_mfma_f32_16x16x32_bf16 v[90:93], v[152:155], v[200:203], v[90:93]
	v_mfma_f32_16x16x32_bf16 v[78:81], v[144:147], v[208:211], v[78:81]
	v_mfma_f32_16x16x32_bf16 v[74:77], v[152:155], v[208:211], v[74:77]
	v_mfma_f32_16x16x32_bf16 v[118:121], v[156:159], v[172:175], v[118:121]
	v_mfma_f32_16x16x32_bf16 v[114:117], v[164:167], v[172:175], v[114:117]
	v_mfma_f32_16x16x32_bf16 v[102:105], v[156:159], v[180:183], v[102:105]
	v_mfma_f32_16x16x32_bf16 v[98:101], v[164:167], v[180:183], v[98:101]
	v_mfma_f32_16x16x32_bf16 v[86:89], v[156:159], v[196:199], v[86:89]
	v_mfma_f32_16x16x32_bf16 v[82:85], v[164:167], v[196:199], v[82:85]
	v_mfma_f32_16x16x32_bf16 v[70:73], v[156:159], v[204:207], v[70:73]
	v_mfma_f32_16x16x32_bf16 v[66:69], v[164:167], v[204:207], v[66:69]
	v_mfma_f32_16x16x32_bf16 v[118:121], v[160:163], v[176:179], v[118:121]
	v_mfma_f32_16x16x32_bf16 v[114:117], v[168:171], v[176:179], v[114:117]
	v_mfma_f32_16x16x32_bf16 v[102:105], v[160:163], v[184:187], v[102:105]
	v_mfma_f32_16x16x32_bf16 v[98:101], v[168:171], v[184:187], v[98:101]
	v_mfma_f32_16x16x32_bf16 v[86:89], v[160:163], v[200:203], v[86:89]
	v_mfma_f32_16x16x32_bf16 v[82:85], v[168:171], v[200:203], v[82:85]
	v_mfma_f32_16x16x32_bf16 v[70:73], v[160:163], v[208:211], v[70:73]
	v_mfma_f32_16x16x32_bf16 v[66:69], v[168:171], v[208:211], v[66:69]
	s_barrier
; #define PG8_STAGE(bufoff, gbase, voff) do { _Pragma("unroll") for (int _i = 0; _i < 2; ++_i) \
;         __builtin_amdgcn_global_load_lds((const unsigned*)((const char*)(gbase) + (voff)[_i]), (LAS unsigned*)(lds + (bufoff) + ldsw + _i * 8192), 16, 0, 0); } while (0)
; #define PG8_STAGEA(bufoff, gbase, voff) do { _Pragma("unroll") for (int _i = 0; _i < 2; ++_i) \
;         __builtin_amdgcn_global_load_lds((const unsigned*)((const char*)(gbase) + (voff)[_i]), (LAS unsigned*)(lds + (bufoff) + ldsw + _i * 8192), 16, 0, 0); } while (0)
; #define PG8_LDA(dst, b, h) do { _Pragma("unroll") for (int m = 0; m < 4; ++m) _Pragma("unroll") for (int k = 0; k < 2; ++k) dst[m][k] = *(const LAS bf16x8*)(lds + PG8_SA(b, h) + aoff + m * 2048 + k * 1024); } while (0)
; #define PG8_LDB(dst, b, h) do { _Pragma("unroll") for (int n = 0; n < 2; ++n) _Pragma("unroll") for (int k = 0; k < 2; ++k) dst[n][k] = *(const LAS bf16x8*)(lds + PG8_SB(b, h) + boff + n * 2048 + k * 1024); } while (0)
; #define PG8_WAIT_V(n) asm volatile("s_waitcnt vmcnt(" #n ")" ::: "memory")
; #define PG8_WAIT_L(n) asm volatile("s_waitcnt lgkmcnt(" #n ")" ::: "memory")
; #define PG8_BAR __builtin_amdgcn_s_barrier()
; template <class Epi, int PARTS>
; __device__ __forceinline__ void gemm_phase(LAS unsigned char* lds, const Gemm g, const StaticOrder& S, const Epi& E) {
;     ...
;             PG8_LDB(B0, 0, 0); PG8_LDB(B1, 0, 1); PG8_SCHED; PG8_LDA(At, 0, 0); PG8_STAGEA(PG8_SA(1, 1), a1 + hstepA, voffA);
;             PG8_WAIT_V(8); PG8_WAIT_L(0); PG8_BAR; PG8_MMA(0, 0, At, B0); PG8_MMA(0, 1, At, B1); PG8_BAR; PG8_SCHED;
;             PG8_LDA(At, 0, 1); PG8_STAGE(PG8_SB(0, 0), b2, voffB); PG8_STAGE(PG8_SB(0, 1), b2 + hstepB, voffB); PG8_STAGEA(PG8_SA(0, 0), a2, voffA);
;             PG8_WAIT_V(8); PG8_WAIT_L(0); PG8_BAR; PG8_MMA(1, 0, At, B0); PG8_MMA(1, 1, At, B1); PG8_BAR; PG8_SCHED;
;             PG8_LDB(B0, 1, 0); PG8_LDB(B1, 1, 1); PG8_SCHED; PG8_LDA(At, 1, 0); PG8_STAGEA(PG8_SA(0, 1), a2 + hstepA, voffA);
;             PG8_WAIT_V(8); PG8_WAIT_L(0); PG8_BAR; PG8_MMA(0, 0, At, B0); PG8_MMA(0, 1, At, B1); PG8_BAR; PG8_SCHED;
;             PG8_LDA(At, 1, 1); PG8_STAGE(PG8_SB(1, 0), b3, voffB); PG8_STAGE(PG8_SB(1, 1), b3 + hstepB, voffB); PG8_STAGEA(PG8_SA(1, 0), a3, voffA);
;             PG8_WAIT_V(8); PG8_WAIT_L(0); PG8_BAR; PG8_MMA(1, 0, At, B0); PG8_MMA(1, 1, At, B1); PG8_BAR; PG8_SCHED;
	s_add_i32 s34, s81, s64
	v_lshl_add_u64 v[188:189], v[188:189], 0, s[72:73]
	s_mov_b32 m0, s34
	ds_read_b128 v[172:175], v143 offset:49152
	ds_read_b128 v[176:179], v143 offset:50176
	ds_read_b128 v[180:183], v143 offset:51200
	ds_read_b128 v[184:187], v143 offset:52224
	ds_read_b128 v[196:199], v143 offset:53248
	ds_read_b128 v[200:203], v143 offset:54272
	ds_read_b128 v[204:207], v143 offset:55296
	ds_read_b128 v[208:211], v143 offset:56320
	global_load_lds_dwordx4 v[188:189], off
	s_add_i32 m0, s34, 0x2000
	s_add_u32 s34, s58, 0x80080
	v_lshl_add_u64 v[188:189], v[212:213], 0, s[72:73]
	s_addc_u32 s35, s59, 0
	s_add_i32 s58, s82, s64
	global_load_lds_dwordx4 v[188:189], off
	v_lshl_add_u64 v[188:189], s[34:35], 0, v[0:1]
	s_mov_b32 m0, s58
	s_nop 0
	global_load_lds_dwordx4 v[188:189], off
	v_lshl_add_u64 v[188:189], s[34:35], 0, v[130:131]
	s_add_i32 m0, s58, 0x2000
	s_nop 0
	global_load_lds_dwordx4 v[188:189], off
	v_lshl_add_u64 v[188:189], v[214:215], 0, s[72:73]
	s_mov_b32 m0, s33
	s_nop 0
	global_load_lds_dwordx4 v[188:189], off
	v_lshl_add_u64 v[188:189], v[224:225], 0, s[72:73]
	s_mov_b32 m0, s36
	s_nop 0
	global_load_lds_dwordx4 v[188:189], off
	s_waitcnt vmcnt(8)
	s_waitcnt lgkmcnt(0)
	s_barrier
	s_waitcnt lgkmcnt(0)
	v_mfma_f32_16x16x32_bf16 v[62:65], v[136:139], v[172:175], v[62:65]
	v_mfma_f32_16x16x32_bf16 v[58:61], v[148:151], v[172:175], v[58:61]
	v_mfma_f32_16x16x32_bf16 v[46:49], v[136:139], v[180:183], v[46:49]
	v_mfma_f32_16x16x32_bf16 v[42:45], v[148:151], v[180:183], v[42:45]
	v_mfma_f32_16x16x32_bf16 v[30:33], v[136:139], v[196:199], v[30:33]
	v_mfma_f32_16x16x32_bf16 v[26:29], v[148:151], v[196:199], v[26:29]
	v_mfma_f32_16x16x32_bf16 v[14:17], v[136:139], v[204:207], v[14:17]
	v_mfma_f32_16x16x32_bf16 v[10:13], v[148:151], v[204:207], v[10:13]
	v_mfma_f32_16x16x32_bf16 v[62:65], v[144:147], v[176:179], v[62:65]
	v_mfma_f32_16x16x32_bf16 v[58:61], v[152:155], v[176:179], v[58:61]
	v_mfma_f32_16x16x32_bf16 v[46:49], v[144:147], v[184:187], v[46:49]
	v_mfma_f32_16x16x32_bf16 v[42:45], v[152:155], v[184:187], v[42:45]
	v_mfma_f32_16x16x32_bf16 v[30:33], v[144:147], v[200:203], v[30:33]
	v_mfma_f32_16x16x32_bf16 v[26:29], v[152:155], v[200:203], v[26:29]
	v_mfma_f32_16x16x32_bf16 v[14:17], v[144:147], v[208:211], v[14:17]
	v_mfma_f32_16x16x32_bf16 v[10:13], v[152:155], v[208:211], v[10:13]
	v_mfma_f32_16x16x32_bf16 v[54:57], v[156:159], v[172:175], v[54:57]
	v_mfma_f32_16x16x32_bf16 v[50:53], v[164:167], v[172:175], v[50:53]
	v_mfma_f32_16x16x32_bf16 v[38:41], v[156:159], v[180:183], v[38:41]
	v_mfma_f32_16x16x32_bf16 v[34:37], v[164:167], v[180:183], v[34:37]
	v_mfma_f32_16x16x32_bf16 v[22:25], v[156:159], v[196:199], v[22:25]
	v_mfma_f32_16x16x32_bf16 v[18:21], v[164:167], v[196:199], v[18:21]
	v_mfma_f32_16x16x32_bf16 v[6:9], v[156:159], v[204:207], v[6:9]
	v_mfma_f32_16x16x32_bf16 v[2:5], v[164:167], v[204:207], v[2:5]
	v_mfma_f32_16x16x32_bf16 v[54:57], v[160:163], v[176:179], v[54:57]
	v_mfma_f32_16x16x32_bf16 v[50:53], v[168:171], v[176:179], v[50:53]
	v_mfma_f32_16x16x32_bf16 v[38:41], v[160:163], v[184:187], v[38:41]
	v_mfma_f32_16x16x32_bf16 v[34:37], v[168:171], v[184:187], v[34:37]
	v_mfma_f32_16x16x32_bf16 v[22:25], v[160:163], v[200:203], v[22:25]
	v_mfma_f32_16x16x32_bf16 v[18:21], v[168:171], v[200:203], v[18:21]
	v_mfma_f32_16x16x32_bf16 v[6:9], v[160:163], v[208:211], v[6:9]
	v_mfma_f32_16x16x32_bf16 v[2:5], v[168:171], v[208:211], v[2:5]
	s_barrier
	s_add_i32 s80, s80, 2
	s_add_u32 s56, s56, 0x100
	s_addc_u32 s57, s57, 0
	s_add_u32 s76, s76, 0x100
	s_addc_u32 s77, s77, 0
	s_cmp_gt_u32 s80, 29
.LBB0_345:
	s_add_u32 s34, s56, 0xfff80080
	s_addc_u32 s35, s57, -1
	s_add_i32 s81, 0, 0x10000
	s_cmp_eq_u32 s80, 28
	s_cselect_b32 s61, s49, s35
	s_cselect_b32 s60, s55, s34
	s_cselect_b32 s59, s47, s77
	s_cselect_b32 s58, s75, s76
	s_add_i32 s82, 0, 0x14000
	v_add_u32_e32 v152, s81, v141
	v_add_u32_e32 v168, s81, v141
	ds_read_b128 v[136:139], v152
	ds_read_b128 v[144:147], v152 offset:1024
	ds_read_b128 v[148:151], v152 offset:2048
	ds_read_b128 v[152:155], v152 offset:3072
	ds_read_b128 v[156:159], v168 offset:4096
	ds_read_b128 v[160:163], v168 offset:5120
	ds_read_b128 v[164:167], v168 offset:6144
	ds_read_b128 v[168:171], v168 offset:7168
	v_lshl_add_u64 v[188:189], s[56:57], 0, v[132:133]
	s_add_i32 m0, s65, 0xc000
	ds_read_b128 v[172:175], v143
	ds_read_b128 v[176:179], v143 offset:1024
	ds_read_b128 v[180:183], v143 offset:2048
	ds_read_b128 v[184:187], v143 offset:3072
	ds_read_b128 v[196:199], v143 offset:4096
	ds_read_b128 v[200:203], v143 offset:5120
	ds_read_b128 v[204:207], v143 offset:6144
	ds_read_b128 v[208:211], v143 offset:7168
	global_load_lds_dwordx4 v[188:189], off
	v_lshl_add_u64 v[188:189], s[56:57], 0, v[134:135]
	s_add_i32 m0, s65, 0xe000
	s_nop 0
	global_load_lds_dwordx4 v[188:189], off
	s_waitcnt vmcnt(8)
	s_waitcnt lgkmcnt(0)
	s_barrier
; #define PG8_STAGE(bufoff, gbase, voff) do { _Pragma("unroll") for (int _i = 0; _i < 2; ++_i) \
;         __builtin_amdgcn_global_load_lds((const unsigned*)((const char*)(gbase) + (voff)[_i]), (LAS unsigned*)(lds + (bufoff) + ldsw + _i * 8192), 16, 0, 0); } while (0)
; #define PG8_STAGEA(bufoff, gbase, voff) do { _Pragma("unroll") for (int _i = 0; _i < 2; ++_i) \
;         __builtin_amdgcn_global_load_lds((const unsigned*)((const char*)(gbase) + (voff)[_i]), (LAS unsigned*)(lds + (bufoff) + ldsw + _i * 8192), 16, 0, 0); } while (0)
; #define PG8_LDA(dst, b, h) do { _Pragma("unroll") for (int m = 0; m < 4; ++m) _Pragma("unroll") for (int k = 0; k < 2; ++k) dst[m][k] = *(const LAS bf16x8*)(lds + PG8_SA(b, h) + aoff + m * 2048 + k * 1024); } while (0)
; #define PG8_LDB(dst, b, h) do { _Pragma("unroll") for (int n = 0; n < 2; ++n) _Pragma("unroll") for (int k = 0; k < 2; ++k) dst[n][k] = *(const LAS bf16x8*)(lds + PG8_SB(b, h) + boff + n * 2048 + k * 1024); } while (0)
; #define PG8_MMA(ai, bj, At, Bt) do { __builtin_amdgcn_s_setprio(3); _Pragma("unroll") for (int m = 0; m < 4; ++m) _Pragma("unroll") for (int n = 0; n < 2; ++n) _Pragma("unroll") for (int k = 0; k < 2; ++k) \
;         acc[ai][bj][m][n] = __builtin_amdgcn_mfma_f32_16x16x32_bf16(Bt[n][k], At[m][k], acc[ai][bj][m][n], 0, 0, 0); __builtin_amdgcn_s_setprio(0); } while (0)
; #define PG8_WAIT_V(n) asm volatile("s_waitcnt vmcnt(" #n ")" ::: "memory")
; #define PG8_WAIT_L(n) asm volatile("s_waitcnt lgkmcnt(" #n ")" ::: "memory")
; #define PG8_BAR __builtin_amdgcn_s_barrier()
; #define PG8_SCHED __builtin_amdgcn_sched_barrier(0)
; template <class Epi, int PARTS>
; __device__ __forceinline__ void gemm_phase(LAS unsigned char* lds, const Gemm g, const StaticOrder& S, const Epi& E) {
;     ...
;             PG8_WAIT_V(8); PG8_WAIT_L(0); PG8_BAR; PG8_MMA(0, 0, At, B0); PG8_MMA(0, 1, At, B1); PG8_BAR; PG8_SCHED;
;             PG8_LDA(At, 0, 1); PG8_STAGE(PG8_SB(0, 0), b2, voffB); PG8_STAGE(PG8_SB(0, 1), b2 + hstepB, voffB); PG8_STAGEA(PG8_SA(0, 0), a2, voffA);
;             PG8_WAIT_V(8); PG8_WAIT_L(0); PG8_BAR; PG8_MMA(1, 0, At, B0); PG8_MMA(1, 1, At, B1); PG8_BAR; PG8_SCHED;
;             PG8_LDB(B0, 1, 0); PG8_LDB(B1, 1, 1); PG8_SCHED; PG8_LDA(At, 1, 0); PG8_STAGEA(PG8_SA(0, 1), a2 + hstepA, voffA);
	s_waitcnt lgkmcnt(0)
	v_mfma_f32_16x16x32_bf16 v[126:129], v[136:139], v[172:175], v[126:129]
	v_mfma_f32_16x16x32_bf16 v[122:125], v[148:151], v[172:175], v[122:125]
	v_mfma_f32_16x16x32_bf16 v[110:113], v[136:139], v[180:183], v[110:113]
	v_mfma_f32_16x16x32_bf16 v[106:109], v[148:151], v[180:183], v[106:109]
	v_mfma_f32_16x16x32_bf16 v[94:97], v[136:139], v[196:199], v[94:97]
	v_mfma_f32_16x16x32_bf16 v[90:93], v[148:151], v[196:199], v[90:93]
	v_mfma_f32_16x16x32_bf16 v[78:81], v[136:139], v[204:207], v[78:81]
	v_mfma_f32_16x16x32_bf16 v[74:77], v[148:151], v[204:207], v[74:77]
	v_mfma_f32_16x16x32_bf16 v[126:129], v[144:147], v[176:179], v[126:129]
	v_mfma_f32_16x16x32_bf16 v[122:125], v[152:155], v[176:179], v[122:125]
	v_mfma_f32_16x16x32_bf16 v[110:113], v[144:147], v[184:187], v[110:113]
	v_mfma_f32_16x16x32_bf16 v[106:109], v[152:155], v[184:187], v[106:109]
	v_mfma_f32_16x16x32_bf16 v[94:97], v[144:147], v[200:203], v[94:97]
	v_mfma_f32_16x16x32_bf16 v[90:93], v[152:155], v[200:203], v[90:93]
	v_mfma_f32_16x16x32_bf16 v[78:81], v[144:147], v[208:211], v[78:81]
	v_mfma_f32_16x16x32_bf16 v[74:77], v[152:155], v[208:211], v[74:77]
	v_mfma_f32_16x16x32_bf16 v[118:121], v[156:159], v[172:175], v[118:121]
	v_mfma_f32_16x16x32_bf16 v[114:117], v[164:167], v[172:175], v[114:117]
	v_mfma_f32_16x16x32_bf16 v[102:105], v[156:159], v[180:183], v[102:105]
	v_mfma_f32_16x16x32_bf16 v[98:101], v[164:167], v[180:183], v[98:101]
	v_mfma_f32_16x16x32_bf16 v[86:89], v[156:159], v[196:199], v[86:89]
	v_mfma_f32_16x16x32_bf16 v[82:85], v[164:167], v[196:199], v[82:85]
	v_mfma_f32_16x16x32_bf16 v[70:73], v[156:159], v[204:207], v[70:73]
	v_mfma_f32_16x16x32_bf16 v[66:69], v[164:167], v[204:207], v[66:69]
	v_mfma_f32_16x16x32_bf16 v[118:121], v[160:163], v[176:179], v[118:121]
	v_mfma_f32_16x16x32_bf16 v[114:117], v[168:171], v[176:179], v[114:117]
	v_mfma_f32_16x16x32_bf16 v[102:105], v[160:163], v[184:187], v[102:105]
	v_mfma_f32_16x16x32_bf16 v[98:101], v[168:171], v[184:187], v[98:101]
	v_mfma_f32_16x16x32_bf16 v[86:89], v[160:163], v[200:203], v[86:89]
	v_mfma_f32_16x16x32_bf16 v[82:85], v[168:171], v[200:203], v[82:85]
	v_mfma_f32_16x16x32_bf16 v[70:73], v[160:163], v[208:211], v[70:73]
	v_mfma_f32_16x16x32_bf16 v[66:69], v[168:171], v[208:211], v[66:69]
	s_barrier
	s_add_i32 s34, s81, s64
	v_lshl_add_u64 v[188:189], s[58:59], 0, v[0:1]
	s_mov_b32 m0, s34
	ds_read_b128 v[172:175], v143 offset:16384
	ds_read_b128 v[176:179], v143 offset:17408
	ds_read_b128 v[180:183], v143 offset:18432
	ds_read_b128 v[184:187], v143 offset:19456
	ds_read_b128 v[196:199], v143 offset:20480
	ds_read_b128 v[200:203], v143 offset:21504
	ds_read_b128 v[204:207], v143 offset:22528
	ds_read_b128 v[208:211], v143 offset:23552
	global_load_lds_dwordx4 v[188:189], off
	s_add_i32 m0, s34, 0x2000
	s_add_u32 s34, s58, 0x80000
	v_lshl_add_u64 v[212:213], s[58:59], 0, v[130:131]
	s_addc_u32 s35, s59, 0
	s_add_i32 s81, s82, s64
	global_load_lds_dwordx4 v[212:213], off
	v_lshl_add_u64 v[214:215], s[34:35], 0, v[0:1]
	s_mov_b32 m0, s81
	v_lshl_add_u64 v[224:225], s[60:61], 0, v[130:131]
	global_load_lds_dwordx4 v[214:215], off
	v_lshl_add_u64 v[214:215], s[34:35], 0, v[130:131]
	s_add_i32 m0, s81, 0x2000
	s_nop 0
	global_load_lds_dwordx4 v[214:215], off
	v_lshl_add_u64 v[214:215], s[60:61], 0, v[0:1]
	s_mov_b32 m0, s65
	s_nop 0
	global_load_lds_dwordx4 v[214:215], off
	s_mov_b32 m0, s66
	s_nop 0
	global_load_lds_dwordx4 v[224:225], off
	s_waitcnt vmcnt(8)
	s_waitcnt lgkmcnt(0)
	s_barrier
	s_waitcnt lgkmcnt(0)
	v_mfma_f32_16x16x32_bf16 v[62:65], v[136:139], v[172:175], v[62:65]
	v_mfma_f32_16x16x32_bf16 v[58:61], v[148:151], v[172:175], v[58:61]
	v_mfma_f32_16x16x32_bf16 v[46:49], v[136:139], v[180:183], v[46:49]
	v_mfma_f32_16x16x32_bf16 v[42:45], v[148:151], v[180:183], v[42:45]
	v_mfma_f32_16x16x32_bf16 v[30:33], v[136:139], v[196:199], v[30:33]
	v_mfma_f32_16x16x32_bf16 v[26:29], v[148:151], v[196:199], v[26:29]
	v_mfma_f32_16x16x32_bf16 v[14:17], v[136:139], v[204:207], v[14:17]
	v_mfma_f32_16x16x32_bf16 v[10:13], v[148:151], v[204:207], v[10:13]
	v_mfma_f32_16x16x32_bf16 v[62:65], v[144:147], v[176:179], v[62:65]
	v_mfma_f32_16x16x32_bf16 v[58:61], v[152:155], v[176:179], v[58:61]
	v_mfma_f32_16x16x32_bf16 v[46:49], v[144:147], v[184:187], v[46:49]
	v_mfma_f32_16x16x32_bf16 v[42:45], v[152:155], v[184:187], v[42:45]
	v_mfma_f32_16x16x32_bf16 v[30:33], v[144:147], v[200:203], v[30:33]
	v_mfma_f32_16x16x32_bf16 v[26:29], v[152:155], v[200:203], v[26:29]
	v_mfma_f32_16x16x32_bf16 v[14:17], v[144:147], v[208:211], v[14:17]
	v_mfma_f32_16x16x32_bf16 v[10:13], v[152:155], v[208:211], v[10:13]
	v_mfma_f32_16x16x32_bf16 v[54:57], v[156:159], v[172:175], v[54:57]
	v_mfma_f32_16x16x32_bf16 v[50:53], v[164:167], v[172:175], v[50:53]
	v_mfma_f32_16x16x32_bf16 v[38:41], v[156:159], v[180:183], v[38:41]
	v_mfma_f32_16x16x32_bf16 v[34:37], v[164:167], v[180:183], v[34:37]
	v_mfma_f32_16x16x32_bf16 v[22:25], v[156:159], v[196:199], v[22:25]
	v_mfma_f32_16x16x32_bf16 v[18:21], v[164:167], v[196:199], v[18:21]
	v_mfma_f32_16x16x32_bf16 v[6:9], v[156:159], v[204:207], v[6:9]
	v_mfma_f32_16x16x32_bf16 v[2:5], v[164:167], v[204:207], v[2:5]
	v_mfma_f32_16x16x32_bf16 v[54:57], v[160:163], v[176:179], v[54:57]
	v_mfma_f32_16x16x32_bf16 v[50:53], v[168:171], v[176:179], v[50:53]
	v_mfma_f32_16x16x32_bf16 v[38:41], v[160:163], v[184:187], v[38:41]
	v_mfma_f32_16x16x32_bf16 v[34:37], v[168:171], v[184:187], v[34:37]
	v_mfma_f32_16x16x32_bf16 v[22:25], v[160:163], v[200:203], v[22:25]
	v_mfma_f32_16x16x32_bf16 v[18:21], v[168:171], v[200:203], v[18:21]
	v_mfma_f32_16x16x32_bf16 v[6:9], v[160:163], v[208:211], v[6:9]
	v_mfma_f32_16x16x32_bf16 v[2:5], v[168:171], v[208:211], v[2:5]
	s_barrier
; #define PG8_STAGE(bufoff, gbase, voff) do { _Pragma("unroll") for (int _i = 0; _i < 2; ++_i) \
;         __builtin_amdgcn_global_load_lds((const unsigned*)((const char*)(gbase) + (voff)[_i]), (LAS unsigned*)(lds + (bufoff) + ldsw + _i * 8192), 16, 0, 0); } while (0)
; #define PG8_STAGEA(bufoff, gbase, voff) do { _Pragma("unroll") for (int _i = 0; _i < 2; ++_i) \
;         __builtin_amdgcn_global_load_lds((const unsigned*)((const char*)(gbase) + (voff)[_i]), (LAS unsigned*)(lds + (bufoff) + ldsw + _i * 8192), 16, 0, 0); } while (0)
; #define PG8_LDA(dst, b, h) do { _Pragma("unroll") for (int m = 0; m < 4; ++m) _Pragma("unroll") for (int k = 0; k < 2; ++k) dst[m][k] = *(const LAS bf16x8*)(lds + PG8_SA(b, h) + aoff + m * 2048 + k * 1024); } while (0)
; #define PG8_LDB(dst, b, h) do { _Pragma("unroll") for (int n = 0; n < 2; ++n) _Pragma("unroll") for (int k = 0; k < 2; ++k) dst[n][k] = *(const LAS bf16x8*)(lds + PG8_SB(b, h) + boff + n * 2048 + k * 1024); } while (0)
; #define PG8_MMA(ai, bj, At, Bt) do { __builtin_amdgcn_s_setprio(3); _Pragma("unroll") for (int m = 0; m < 4; ++m) _Pragma("unroll") for (int n = 0; n < 2; ++n) _Pragma("unroll") for (int k = 0; k < 2; ++k) \
;         acc[ai][bj][m][n] = __builtin_amdgcn_mfma_f32_16x16x32_bf16(Bt[n][k], At[m][k], acc[ai][bj][m][n], 0, 0, 0); __builtin_amdgcn_s_setprio(0); } while (0)
; #define PG8_WAIT_V(n) asm volatile("s_waitcnt vmcnt(" #n ")" ::: "memory")
; #define PG8_WAIT_L(n) asm volatile("s_waitcnt lgkmcnt(" #n ")" ::: "memory")
; #define PG8_BAR __builtin_amdgcn_s_barrier()
; #define PG8_SCHED __builtin_amdgcn_sched_barrier(0)
; template <class Epi, int PARTS>
; __device__ __forceinline__ void gemm_phase(LAS unsigned char* lds, const Gemm g, const StaticOrder& S, const Epi& E) {
;     ...
;             PG8_LDB(B0, 1, 0); PG8_LDB(B1, 1, 1); PG8_SCHED; PG8_LDA(At, 1, 0); PG8_STAGEA(PG8_SA(0, 1), a2 + hstepA, voffA);
;             PG8_WAIT_V(8); PG8_WAIT_L(0); PG8_BAR; PG8_MMA(0, 0, At, B0); PG8_MMA(0, 1, At, B1); PG8_BAR; PG8_SCHED;
;             PG8_LDA(At, 1, 1); PG8_STAGE(PG8_SB(1, 0), b3, voffB); PG8_STAGE(PG8_SB(1, 1), b3 + hstepB, voffB); PG8_STAGEA(PG8_SA(1, 0), a3, voffA);
;             PG8_WAIT_V(8); PG8_WAIT_L(0); PG8_BAR; PG8_MMA(1, 0, At, B0); PG8_MMA(1, 1, At, B1); PG8_BAR; PG8_SCHED;
	s_add_i32 s81, 0, 0x18000
	s_add_i32 s82, 0, 0x1c000
	v_add_u32_e32 v152, s81, v141
	v_add_u32_e32 v168, s81, v141
	ds_read_b128 v[136:139], v152
	ds_read_b128 v[144:147], v152 offset:1024
	ds_read_b128 v[148:151], v152 offset:2048
	ds_read_b128 v[152:155], v152 offset:3072
	ds_read_b128 v[156:159], v168 offset:4096
	ds_read_b128 v[160:163], v168 offset:5120
	ds_read_b128 v[164:167], v168 offset:6144
	ds_read_b128 v[168:171], v168 offset:7168
	s_add_u32 s34, s60, 0x80000
	s_addc_u32 s35, s61, 0
	s_mov_b32 m0, s67
	v_lshl_add_u64 v[228:229], s[34:35], 0, v[0:1]
	ds_read_b128 v[172:175], v143 offset:32768
	ds_read_b128 v[176:179], v143 offset:33792
	ds_read_b128 v[180:183], v143 offset:34816
	ds_read_b128 v[184:187], v143 offset:35840
	ds_read_b128 v[196:199], v143 offset:36864
	ds_read_b128 v[200:203], v143 offset:37888
	ds_read_b128 v[204:207], v143 offset:38912
	ds_read_b128 v[208:211], v143 offset:39936
	global_load_lds_dwordx4 v[228:229], off
	v_lshl_add_u64 v[228:229], s[34:35], 0, v[130:131]
	s_mov_b32 m0, s69
	s_nop 0
	global_load_lds_dwordx4 v[228:229], off
	s_waitcnt vmcnt(8)
	s_waitcnt lgkmcnt(0)
	s_barrier
	s_waitcnt lgkmcnt(0)
	v_mfma_f32_16x16x32_bf16 v[126:129], v[136:139], v[172:175], v[126:129]
	v_mfma_f32_16x16x32_bf16 v[122:125], v[148:151], v[172:175], v[122:125]
	v_mfma_f32_16x16x32_bf16 v[110:113], v[136:139], v[180:183], v[110:113]
	v_mfma_f32_16x16x32_bf16 v[106:109], v[148:151], v[180:183], v[106:109]
	v_mfma_f32_16x16x32_bf16 v[94:97], v[136:139], v[196:199], v[94:97]
	v_mfma_f32_16x16x32_bf16 v[90:93], v[148:151], v[196:199], v[90:93]
	v_mfma_f32_16x16x32_bf16 v[78:81], v[136:139], v[204:207], v[78:81]
	v_mfma_f32_16x16x32_bf16 v[74:77], v[148:151], v[204:207], v[74:77]
	v_mfma_f32_16x16x32_bf16 v[126:129], v[144:147], v[176:179], v[126:129]
	v_mfma_f32_16x16x32_bf16 v[122:125], v[152:155], v[176:179], v[122:125]
	v_mfma_f32_16x16x32_bf16 v[110:113], v[144:147], v[184:187], v[110:113]
	v_mfma_f32_16x16x32_bf16 v[106:109], v[152:155], v[184:187], v[106:109]
	v_mfma_f32_16x16x32_bf16 v[94:97], v[144:147], v[200:203], v[94:97]
	v_mfma_f32_16x16x32_bf16 v[90:93], v[152:155], v[200:203], v[90:93]
	v_mfma_f32_16x16x32_bf16 v[78:81], v[144:147], v[208:211], v[78:81]
	v_mfma_f32_16x16x32_bf16 v[74:77], v[152:155], v[208:211], v[74:77]
	v_mfma_f32_16x16x32_bf16 v[118:121], v[156:159], v[172:175], v[118:121]
	v_mfma_f32_16x16x32_bf16 v[114:117], v[164:167], v[172:175], v[114:117]
	v_mfma_f32_16x16x32_bf16 v[102:105], v[156:159], v[180:183], v[102:105]
	v_mfma_f32_16x16x32_bf16 v[98:101], v[164:167], v[180:183], v[98:101]
	v_mfma_f32_16x16x32_bf16 v[86:89], v[156:159], v[196:199], v[86:89]
	v_mfma_f32_16x16x32_bf16 v[82:85], v[164:167], v[196:199], v[82:85]
	v_mfma_f32_16x16x32_bf16 v[70:73], v[156:159], v[204:207], v[70:73]
	v_mfma_f32_16x16x32_bf16 v[66:69], v[164:167], v[204:207], v[66:69]
	v_mfma_f32_16x16x32_bf16 v[118:121], v[160:163], v[176:179], v[118:121]
	v_mfma_f32_16x16x32_bf16 v[114:117], v[168:171], v[176:179], v[114:117]
	v_mfma_f32_16x16x32_bf16 v[102:105], v[160:163], v[184:187], v[102:105]
	v_mfma_f32_16x16x32_bf16 v[98:101], v[168:171], v[184:187], v[98:101]
	v_mfma_f32_16x16x32_bf16 v[86:89], v[160:163], v[200:203], v[86:89]
	v_mfma_f32_16x16x32_bf16 v[82:85], v[168:171], v[200:203], v[82:85]
	v_mfma_f32_16x16x32_bf16 v[70:73], v[160:163], v[208:211], v[70:73]
	v_mfma_f32_16x16x32_bf16 v[66:69], v[168:171], v[208:211], v[66:69]
	s_barrier
	s_add_i32 s34, s81, s64
	v_lshl_add_u64 v[188:189], v[188:189], 0, s[72:73]
	s_mov_b32 m0, s34
	ds_read_b128 v[172:175], v143 offset:49152
	ds_read_b128 v[176:179], v143 offset:50176
	ds_read_b128 v[180:183], v143 offset:51200
	ds_read_b128 v[184:187], v143 offset:52224
	ds_read_b128 v[196:199], v143 offset:53248
	ds_read_b128 v[200:203], v143 offset:54272
	ds_read_b128 v[204:207], v143 offset:55296
	ds_read_b128 v[208:211], v143 offset:56320
	global_load_lds_dwordx4 v[188:189], off
	s_add_i32 m0, s34, 0x2000
	s_add_u32 s34, s58, 0x80080
	v_lshl_add_u64 v[188:189], v[212:213], 0, s[72:73]
	s_addc_u32 s35, s59, 0
	s_add_i32 s58, s82, s64
	global_load_lds_dwordx4 v[188:189], off
	v_lshl_add_u64 v[188:189], s[34:35], 0, v[0:1]
	s_mov_b32 m0, s58
	s_nop 0
	global_load_lds_dwordx4 v[188:189], off
	v_lshl_add_u64 v[188:189], s[34:35], 0, v[130:131]
	s_add_i32 m0, s58, 0x2000
	s_nop 0
	global_load_lds_dwordx4 v[188:189], off
	v_lshl_add_u64 v[188:189], v[214:215], 0, s[72:73]
	s_mov_b32 m0, s33
	s_nop 0
	global_load_lds_dwordx4 v[188:189], off
	v_lshl_add_u64 v[188:189], v[224:225], 0, s[72:73]
	s_mov_b32 m0, s36
	s_nop 0
	global_load_lds_dwordx4 v[188:189], off
	s_waitcnt vmcnt(8)
	s_waitcnt lgkmcnt(0)
	s_barrier
; __device__ __forceinline__ unsigned cvt_pk_bf16(float lo, float hi) { f32x2 v = {lo, hi}; bf16x2_t_ b = __builtin_convertvector(v, bf16x2_t_); return __builtin_bit_cast(unsigned, b); }
; __device__ __forceinline__ float bf_lo(unsigned w) { return __uint_as_float(w << 16); }
; __device__ __forceinline__ float bf_hi(unsigned w) { return __uint_as_float(w & 0xffff0000u); }
; #define PG8_WAIT_V(n) asm volatile("s_waitcnt vmcnt(" #n ")" ::: "memory")
; template <class Epi, int PARTS>
; __device__ __forceinline__ void gemm_phase(LAS unsigned char* lds, const Gemm g, const StaticOrder& S, const Epi& E) {
;     ...
;             PG8_WAIT_V(8); PG8_WAIT_L(0); PG8_BAR; PG8_MMA(1, 0, At, B0); PG8_MMA(1, 1, At, B1); PG8_BAR; PG8_SCHED;
;         }
;         if (wr == 0) PG8_BAR;
;     __device__ __forceinline__ void operator()(f32x4 (&acc)[2][2][4][2], const Unit& u, int wr, int wc, int fr, int fq) const {
;         const int t0 = u.pm * 256 + wr * 64 + fr;
;         const int col0 = 256 * u.pn + 32 * wc + 8 * fq;
;         const float* bp0 = first ? ((t0 < NPROMPT) ? xp + (size_t)t0 * 1024 : xs + (size_t)(t0 - NPROMPT) * 1024) : out + (size_t)t0 * 1024;
; #pragma unroll
;         for (int ai = 0; ai < 2; ++ai)
; #pragma unroll
;             for (int m = 0; m < 4; ++m) {
;                 const int j = 128 * ai + 16 * m; float sq = 0.f;
; #pragma unroll
;                 for (int bj = 0; bj < 2; ++bj) {
;                     const size_t o = (size_t)j * 1024 + col0 + 128 * bj;
;                     f32x4 a, b;
;                     if (bb) { const u32x4 w = *(const u32x4*)(xb + (size_t)t0 * 1024 + o);
;                         a = (f32x4){bf_lo(w.x), bf_hi(w.x), bf_lo(w.y), bf_hi(w.y)}; b = (f32x4){bf_lo(w.z), bf_hi(w.z), bf_lo(w.w), bf_hi(w.w)}; }
;                     else { a = *(const f32x4*)(bp0 + o); b = *(const f32x4*)(bp0 + o + 4); }
;                     a = a + acc[ai][bj][m][0]; b = b + acc[ai][bj][m][1];
;                     if (wout) { float* op = out + (size_t)t0 * 1024 + o; *(f32x4*)op = a; *(f32x4*)(op + 4) = b; }
;                     u32x4 w; w.x = cvt_pk_bf16(a.x, a.y); w.y = cvt_pk_bf16(a.z, a.w); w.z = cvt_pk_bf16(b.x, b.y); w.w = cvt_pk_bf16(b.z, b.w);
;                     *(u32x4*)(xb + (size_t)t0 * 1024 + o) = w;
;                     sq += (a.x * a.x + a.y * a.y) + (a.z * a.z + a.w * a.w) + (b.x * b.x + b.y * b.y) + (b.z * b.z + b.w * b.w);
	s_waitcnt lgkmcnt(0)
	v_mfma_f32_16x16x32_bf16 v[62:65], v[136:139], v[172:175], v[62:65]
	v_mfma_f32_16x16x32_bf16 v[58:61], v[148:151], v[172:175], v[58:61]
	v_mfma_f32_16x16x32_bf16 v[46:49], v[136:139], v[180:183], v[46:49]
	v_mfma_f32_16x16x32_bf16 v[42:45], v[148:151], v[180:183], v[42:45]
	v_mfma_f32_16x16x32_bf16 v[30:33], v[136:139], v[196:199], v[30:33]
	v_mfma_f32_16x16x32_bf16 v[26:29], v[148:151], v[196:199], v[26:29]
	v_mfma_f32_16x16x32_bf16 v[14:17], v[136:139], v[204:207], v[14:17]
	v_mfma_f32_16x16x32_bf16 v[10:13], v[148:151], v[204:207], v[10:13]
	v_mfma_f32_16x16x32_bf16 v[62:65], v[144:147], v[176:179], v[62:65]
	v_mfma_f32_16x16x32_bf16 v[58:61], v[152:155], v[176:179], v[58:61]
	v_mfma_f32_16x16x32_bf16 v[46:49], v[144:147], v[184:187], v[46:49]
	v_mfma_f32_16x16x32_bf16 v[42:45], v[152:155], v[184:187], v[42:45]
	v_mfma_f32_16x16x32_bf16 v[30:33], v[144:147], v[200:203], v[30:33]
	v_mfma_f32_16x16x32_bf16 v[26:29], v[152:155], v[200:203], v[26:29]
	v_mfma_f32_16x16x32_bf16 v[14:17], v[144:147], v[208:211], v[14:17]
	v_mfma_f32_16x16x32_bf16 v[10:13], v[152:155], v[208:211], v[10:13]
	v_mfma_f32_16x16x32_bf16 v[54:57], v[156:159], v[172:175], v[54:57]
	v_mfma_f32_16x16x32_bf16 v[50:53], v[164:167], v[172:175], v[50:53]
	v_mfma_f32_16x16x32_bf16 v[38:41], v[156:159], v[180:183], v[38:41]
	v_mfma_f32_16x16x32_bf16 v[34:37], v[164:167], v[180:183], v[34:37]
	v_mfma_f32_16x16x32_bf16 v[22:25], v[156:159], v[196:199], v[22:25]
	v_mfma_f32_16x16x32_bf16 v[18:21], v[164:167], v[196:199], v[18:21]
	v_mfma_f32_16x16x32_bf16 v[6:9], v[156:159], v[204:207], v[6:9]
	v_mfma_f32_16x16x32_bf16 v[2:5], v[164:167], v[204:207], v[2:5]
	v_mfma_f32_16x16x32_bf16 v[54:57], v[160:163], v[176:179], v[54:57]
	v_mfma_f32_16x16x32_bf16 v[50:53], v[168:171], v[176:179], v[50:53]
	v_mfma_f32_16x16x32_bf16 v[38:41], v[160:163], v[184:187], v[38:41]
	v_mfma_f32_16x16x32_bf16 v[34:37], v[168:171], v[184:187], v[34:37]
	v_mfma_f32_16x16x32_bf16 v[22:25], v[160:163], v[200:203], v[22:25]
	v_mfma_f32_16x16x32_bf16 v[18:21], v[168:171], v[200:203], v[18:21]
	v_mfma_f32_16x16x32_bf16 v[6:9], v[160:163], v[208:211], v[6:9]
	v_mfma_f32_16x16x32_bf16 v[2:5], v[168:171], v[208:211], v[2:5]
	s_barrier
	s_add_i32 s80, s80, 2
	s_add_u32 s56, s56, 0x100
	s_addc_u32 s57, s57, 0
	s_add_u32 s76, s76, 0x100
	s_addc_u32 s77, s77, 0
	s_cmp_gt_u32 s80, 29
	s_cbranch_scc0 .LBB0_345
	s_setprio 0
	s_and_b64 vcc, exec, s[44:45]
	s_cbranch_vccz .LBB0_348
	s_barrier
.LBB0_348:
	v_lshl_add_u32 v138, s54, 8, v140
	v_and_b32_e32 v145, 64, v219
	v_ashrrev_i32_e32 v139, 31, v138
	v_xor_b32_e32 v144, 16, v219
	v_add_u32_e32 v148, 64, v145
	v_lshl_or_b32 v136, s20, 8, v142
	v_lshlrev_b64 v[146:147], 11, v[138:139]
	v_cmp_lt_i32_e32 vcc, v144, v148
	v_ashrrev_i32_e32 v137, 31, v136
	v_lshl_add_u64 v[146:147], s[24:25], 0, v[146:147]
	v_cndmask_b32_e32 v144, v219, v144, vcc
	v_lshlrev_b32_e32 v145, 2, v144
	v_xor_b32_e32 v144, 32, v219
	v_lshl_add_u64 v[136:137], v[136:137], 1, v[146:147]
	v_cmp_lt_i32_e32 vcc, v144, v148
	global_load_dwordx4 v[146:149], v[136:137], off
	s_mov_b32 s101, 0
	global_load_dwordx4 v[154:157], v[136:137], off offset:64
	s_mov_b32 s100, 0x8000
	v_lshl_add_u64 v[240:241], v[136:137], 0, s[100:101]
	global_load_dwordx4 v[158:161], v[240:241], off
	global_load_dwordx4 v[162:165], v[240:241], off offset:64
	s_mov_b32 s100, 0x10000
	v_lshl_add_u64 v[240:241], v[136:137], 0, s[100:101]
	global_load_dwordx4 v[166:169], v[240:241], off
	global_load_dwordx4 v[170:173], v[240:241], off offset:64
	s_mov_b32 s100, 0x18000
	v_lshl_add_u64 v[240:241], v[136:137], 0, s[100:101]
	global_load_dwordx4 v[174:177], v[240:241], off
	global_load_dwordx4 v[178:181], v[240:241], off offset:64
	s_mov_b32 s100, 0x40000
	v_lshl_add_u64 v[240:241], v[136:137], 0, s[100:101]
	global_load_dwordx4 v[182:185], v[240:241], off
	global_load_dwordx4 v[186:189], v[240:241], off offset:64
	s_mov_b32 s100, 0x48000
	v_lshl_add_u64 v[240:241], v[136:137], 0, s[100:101]
	global_load_dwordx4 v[196:199], v[240:241], off
	global_load_dwordx4 v[200:203], v[240:241], off offset:64
	s_mov_b32 s100, 0x50000
	v_lshl_add_u64 v[240:241], v[136:137], 0, s[100:101]
	global_load_dwordx4 v[204:207], v[240:241], off
	global_load_dwordx4 v[208:211], v[240:241], off offset:64
	s_mov_b32 s100, 0x58000
	v_lshl_add_u64 v[240:241], v[136:137], 0, s[100:101]
	global_load_dwordx4 v[212:215], v[240:241], off
	global_load_dwordx4 v[236:239], v[240:241], off offset:64
	v_readlane_b32 s80, v254, 33
	v_cndmask_b32_e32 v144, v219, v144, vcc
	v_lshlrev_b32_e32 v144, 2, v144
	s_lshl_b32 s54, s20, 2
	v_readlane_b32 s81, v254, 34
	s_ashr_i32 s55, s54, 31
	s_waitcnt vmcnt(15)
	v_lshlrev_b32_e32 v150, 16, v146
	v_and_b32_e32 v151, 0xffff0000, v146
	v_lshlrev_b32_e32 v146, 16, v147
	v_and_b32_e32 v147, 0xffff0000, v147
	v_lshlrev_b32_e32 v152, 16, v148
	v_and_b32_e32 v153, 0xffff0000, v148
	v_lshlrev_b32_e32 v148, 16, v149
	v_and_b32_e32 v149, 0xffff0000, v149
	v_pk_add_f32 v[128:129], v[128:129], v[146:147]
	v_pk_add_f32 v[126:127], v[126:127], v[150:151]
	v_pk_add_f32 v[146:147], v[124:125], v[148:149]
	v_pk_add_f32 v[148:149], v[122:123], v[152:153]
	v_cvt_pk_bf16_f32 v122, v126, v127
	v_cvt_pk_bf16_f32 v123, v128, v129
	v_cvt_pk_bf16_f32 v124, v148, v149
	v_cvt_pk_bf16_f32 v125, v146, v147
	global_store_dwordx4 v[136:137], v[122:125], off
	s_nop 1
	v_mul_f32_e32 v122, v127, v127
	v_mul_f32_e32 v123, v129, v129
	v_fmac_f32_e32 v122, v126, v126
	v_fmac_f32_e32 v123, v128, v128
	v_add_f32_e32 v122, v122, v123
	v_mul_f32_e32 v123, v149, v149
	v_fmac_f32_e32 v123, v148, v148
	v_add_f32_e32 v122, v123, v122
	v_mul_f32_e32 v123, v147, v147
	v_fmac_f32_e32 v123, v146, v146
	v_add_f32_e32 v146, v123, v122
	s_waitcnt vmcnt(15)
; __device__ __forceinline__ unsigned cvt_pk_bf16(float lo, float hi) { f32x2 v = {lo, hi}; bf16x2_t_ b = __builtin_convertvector(v, bf16x2_t_); return __builtin_bit_cast(unsigned, b); }
; __device__ __forceinline__ float bf_lo(unsigned w) { return __uint_as_float(w << 16); }
; __device__ __forceinline__ float bf_hi(unsigned w) { return __uint_as_float(w & 0xffff0000u); }
;     __device__ __forceinline__ void operator()(f32x4 (&acc)[2][2][4][2], const Unit& u, int wr, int wc, int fr, int fq) const {
;     ...
;                 const int j = 128 * ai + 16 * m; float sq = 0.f;
; #pragma unroll
;                 for (int bj = 0; bj < 2; ++bj) {
;                     const size_t o = (size_t)j * 1024 + col0 + 128 * bj;
;                     f32x4 a, b;
;                     if (bb) { const u32x4 w = *(const u32x4*)(xb + (size_t)t0 * 1024 + o);
;                         a = (f32x4){bf_lo(w.x), bf_hi(w.x), bf_lo(w.y), bf_hi(w.y)}; b = (f32x4){bf_lo(w.z), bf_hi(w.z), bf_lo(w.w), bf_hi(w.w)}; }
;                     else { a = *(const f32x4*)(bp0 + o); b = *(const f32x4*)(bp0 + o + 4); }
;                     a = a + acc[ai][bj][m][0]; b = b + acc[ai][bj][m][1];
;                     if (wout) { float* op = out + (size_t)t0 * 1024 + o; *(f32x4*)op = a; *(f32x4*)(op + 4) = b; }
;                     u32x4 w; w.x = cvt_pk_bf16(a.x, a.y); w.y = cvt_pk_bf16(a.z, a.w); w.z = cvt_pk_bf16(b.x, b.y); w.w = cvt_pk_bf16(b.z, b.w);
;                     *(u32x4*)(xb + (size_t)t0 * 1024 + o) = w;
;                     sq += (a.x * a.x + a.y * a.y) + (a.z * a.z + a.w * a.w) + (b.x * b.x + b.y * b.y) + (b.z * b.z + b.w * b.w);
;                 }
;                 sq += __shfl_xor(sq, 16); sq += __shfl_xor(sq, 32);
;                 if (fq == 0) ss[(size_t)(t0 + j) * 16 + 4 * u.pn + wc] = sq;
	v_mov_b64_e32 v[122:123], v[154:155]
	v_mov_b64_e32 v[124:125], v[156:157]
	v_lshlrev_b32_e32 v126, 16, v122
	v_and_b32_e32 v127, 0xffff0000, v122
	v_lshlrev_b32_e32 v122, 16, v123
	v_and_b32_e32 v123, 0xffff0000, v123
	v_lshlrev_b32_e32 v128, 16, v124
	v_and_b32_e32 v129, 0xffff0000, v124
	v_lshlrev_b32_e32 v124, 16, v125
	v_and_b32_e32 v125, 0xffff0000, v125
	v_pk_add_f32 v[120:121], v[120:121], v[122:123]
	v_pk_add_f32 v[118:119], v[118:119], v[126:127]
	v_pk_add_f32 v[122:123], v[116:117], v[124:125]
	v_pk_add_f32 v[124:125], v[114:115], v[128:129]
	v_cvt_pk_bf16_f32 v114, v118, v119
	v_cvt_pk_bf16_f32 v115, v120, v121
	v_cvt_pk_bf16_f32 v116, v124, v125
	v_cvt_pk_bf16_f32 v117, v122, v123
	global_store_dwordx4 v[136:137], v[114:117], off offset:64
	s_nop 1
	v_mul_f32_e32 v114, v119, v119
	v_mul_f32_e32 v115, v121, v121
	v_fmac_f32_e32 v114, v118, v118
	v_fmac_f32_e32 v115, v120, v120
	v_add_f32_e32 v114, v114, v115
	v_mul_f32_e32 v115, v125, v125
	v_fmac_f32_e32 v115, v124, v124
	v_add_f32_e32 v114, v115, v114
	v_mul_f32_e32 v115, v123, v123
	v_fmac_f32_e32 v115, v122, v122
	v_add_f32_e32 v114, v115, v114
	v_add_f32_e32 v114, v146, v114
	ds_bpermute_b32 v115, v145, v114
	s_waitcnt lgkmcnt(0)
	v_add_f32_e32 v116, v114, v115
	ds_bpermute_b32 v117, v144, v116
	v_lshlrev_b64 v[114:115], 6, v[138:139]
	v_lshl_add_u64 v[114:115], s[80:81], 0, v[114:115]
	s_and_saveexec_b64 s[56:57], s[38:39]
	s_cbranch_execz .LBB0_350
	v_lshl_add_u64 v[118:119], s[54:55], 2, v[114:115]
	s_lshl_b32 s20, s74, 2
	v_lshl_add_u64 v[118:119], v[118:119], 0, s[20:21]
	s_waitcnt lgkmcnt(0)
	v_add_f32_e32 v116, v116, v117
	global_store_dword v[118:119], v116, off
.LBB0_350:
	s_or_b64 exec, exec, s[56:57]
	v_add_co_u32_e32 v120, vcc, 0x8000, v136
	s_nop 1
	v_addc_co_u32_e32 v121, vcc, 0, v137, vcc
	s_waitcnt lgkmcnt(0)
	s_waitcnt vmcnt(15)
	v_mov_b64_e32 v[116:117], v[158:159]
	v_mov_b64_e32 v[118:119], v[160:161]
	v_lshlrev_b32_e32 v122, 16, v116
	v_and_b32_e32 v123, 0xffff0000, v116
	v_lshlrev_b32_e32 v116, 16, v117
	v_and_b32_e32 v117, 0xffff0000, v117
	v_lshlrev_b32_e32 v124, 16, v118
	v_and_b32_e32 v125, 0xffff0000, v118
	v_lshlrev_b32_e32 v118, 16, v119
	v_and_b32_e32 v119, 0xffff0000, v119
	v_pk_add_f32 v[112:113], v[112:113], v[116:117]
	v_pk_add_f32 v[110:111], v[110:111], v[122:123]
	v_pk_add_f32 v[116:117], v[108:109], v[118:119]
	v_pk_add_f32 v[118:119], v[106:107], v[124:125]
	v_cvt_pk_bf16_f32 v106, v110, v111
	v_cvt_pk_bf16_f32 v107, v112, v113
	v_cvt_pk_bf16_f32 v108, v118, v119
	v_cvt_pk_bf16_f32 v109, v116, v117
	global_store_dwordx4 v[120:121], v[106:109], off
	s_nop 1
	v_mul_f32_e32 v106, v111, v111
	v_mul_f32_e32 v107, v113, v113
	v_fmac_f32_e32 v106, v110, v110
	v_fmac_f32_e32 v107, v112, v112
	v_add_f32_e32 v106, v106, v107
	v_mul_f32_e32 v107, v119, v119
	v_fmac_f32_e32 v107, v118, v118
	v_add_f32_e32 v106, v107, v106
	v_mul_f32_e32 v107, v117, v117
	v_fmac_f32_e32 v107, v116, v116
	v_add_f32_e32 v116, v107, v106
	s_waitcnt vmcnt(15)
	v_mov_b64_e32 v[106:107], v[162:163]
	v_mov_b64_e32 v[108:109], v[164:165]
	v_lshlrev_b32_e32 v110, 16, v106
	v_and_b32_e32 v111, 0xffff0000, v106
	v_lshlrev_b32_e32 v106, 16, v107
	v_and_b32_e32 v107, 0xffff0000, v107
	v_lshlrev_b32_e32 v112, 16, v108
	v_and_b32_e32 v113, 0xffff0000, v108
	v_lshlrev_b32_e32 v108, 16, v109
	v_and_b32_e32 v109, 0xffff0000, v109
	v_pk_add_f32 v[104:105], v[104:105], v[106:107]
	v_pk_add_f32 v[102:103], v[102:103], v[110:111]
	v_pk_add_f32 v[106:107], v[100:101], v[108:109]
	v_pk_add_f32 v[108:109], v[98:99], v[112:113]
	v_cvt_pk_bf16_f32 v98, v102, v103
	v_cvt_pk_bf16_f32 v99, v104, v105
	v_cvt_pk_bf16_f32 v100, v108, v109
	v_cvt_pk_bf16_f32 v101, v106, v107
	global_store_dwordx4 v[120:121], v[98:101], off offset:64
	s_nop 1
	v_mul_f32_e32 v98, v103, v103
	v_mul_f32_e32 v99, v105, v105
	v_fmac_f32_e32 v98, v102, v102
	v_fmac_f32_e32 v99, v104, v104
	v_add_f32_e32 v98, v98, v99
	v_mul_f32_e32 v99, v109, v109
	v_fmac_f32_e32 v99, v108, v108
	v_add_f32_e32 v98, v99, v98
	v_mul_f32_e32 v99, v107, v107
	v_fmac_f32_e32 v99, v106, v106
	v_add_f32_e32 v98, v99, v98
	v_add_f32_e32 v98, v116, v98
	ds_bpermute_b32 v99, v145, v98
	s_waitcnt lgkmcnt(0)
	v_add_f32_e32 v98, v98, v99
	ds_bpermute_b32 v99, v144, v98
	s_and_saveexec_b64 s[56:57], s[38:39]
	s_cbranch_execz .LBB0_352
	s_waitcnt lgkmcnt(0)
	v_add_f32_e32 v100, v98, v99
	v_or_b32_e32 v98, 16, v138
	v_ashrrev_i32_e32 v99, 31, v98
	v_lshlrev_b64 v[98:99], 6, v[98:99]
	v_lshl_add_u64 v[98:99], s[80:81], 0, v[98:99]
	v_lshl_add_u64 v[98:99], s[54:55], 2, v[98:99]
	s_lshl_b32 s20, s74, 2
	v_lshl_add_u64 v[98:99], v[98:99], 0, s[20:21]
	global_store_dword v[98:99], v100, off
; __device__ __forceinline__ unsigned cvt_pk_bf16(float lo, float hi) { f32x2 v = {lo, hi}; bf16x2_t_ b = __builtin_convertvector(v, bf16x2_t_); return __builtin_bit_cast(unsigned, b); }
; __device__ __forceinline__ float bf_lo(unsigned w) { return __uint_as_float(w << 16); }
; __device__ __forceinline__ float bf_hi(unsigned w) { return __uint_as_float(w & 0xffff0000u); }
;     __device__ __forceinline__ void operator()(f32x4 (&acc)[2][2][4][2], const Unit& u, int wr, int wc, int fr, int fq) const {
;     ...
;         for (int ai = 0; ai < 2; ++ai)
; #pragma unroll
;             for (int m = 0; m < 4; ++m) {
;                 const int j = 128 * ai + 16 * m; float sq = 0.f;
; #pragma unroll
;                 for (int bj = 0; bj < 2; ++bj) {
;                     const size_t o = (size_t)j * 1024 + col0 + 128 * bj;
;                     f32x4 a, b;
;                     if (bb) { const u32x4 w = *(const u32x4*)(xb + (size_t)t0 * 1024 + o);
;                         a = (f32x4){bf_lo(w.x), bf_hi(w.x), bf_lo(w.y), bf_hi(w.y)}; b = (f32x4){bf_lo(w.z), bf_hi(w.z), bf_lo(w.w), bf_hi(w.w)}; }
;                     else { a = *(const f32x4*)(bp0 + o); b = *(const f32x4*)(bp0 + o + 4); }
;                     a = a + acc[ai][bj][m][0]; b = b + acc[ai][bj][m][1];
;                     if (wout) { float* op = out + (size_t)t0 * 1024 + o; *(f32x4*)op = a; *(f32x4*)(op + 4) = b; }
;                     u32x4 w; w.x = cvt_pk_bf16(a.x, a.y); w.y = cvt_pk_bf16(a.z, a.w); w.z = cvt_pk_bf16(b.x, b.y); w.w = cvt_pk_bf16(b.z, b.w);
;                     *(u32x4*)(xb + (size_t)t0 * 1024 + o) = w;
;                     sq += (a.x * a.x + a.y * a.y) + (a.z * a.z + a.w * a.w) + (b.x * b.x + b.y * b.y) + (b.z * b.z + b.w * b.w);
;                 }
;                 sq += __shfl_xor(sq, 16); sq += __shfl_xor(sq, 32);
;                 if (fq == 0) ss[(size_t)(t0 + j) * 16 + 4 * u.pn + wc] = sq;
.LBB0_352:
	s_or_b64 exec, exec, s[56:57]
	v_add_co_u32_e32 v102, vcc, 0x10000, v136
	s_nop 1
	v_addc_co_u32_e32 v103, vcc, 0, v137, vcc
	s_waitcnt lgkmcnt(0)
	s_waitcnt vmcnt(15)
	v_mov_b64_e32 v[98:99], v[166:167]
	v_mov_b64_e32 v[100:101], v[168:169]
	v_lshlrev_b32_e32 v104, 16, v98
	v_and_b32_e32 v105, 0xffff0000, v98
	v_lshlrev_b32_e32 v98, 16, v99
	v_and_b32_e32 v99, 0xffff0000, v99
	v_lshlrev_b32_e32 v106, 16, v100
	v_and_b32_e32 v107, 0xffff0000, v100
	v_lshlrev_b32_e32 v100, 16, v101
	v_and_b32_e32 v101, 0xffff0000, v101
	v_pk_add_f32 v[96:97], v[96:97], v[98:99]
	v_pk_add_f32 v[94:95], v[94:95], v[104:105]
	v_pk_add_f32 v[98:99], v[92:93], v[100:101]
	v_pk_add_f32 v[100:101], v[90:91], v[106:107]
	v_cvt_pk_bf16_f32 v90, v94, v95
	v_cvt_pk_bf16_f32 v91, v96, v97
	v_cvt_pk_bf16_f32 v92, v100, v101
	v_cvt_pk_bf16_f32 v93, v98, v99
	global_store_dwordx4 v[102:103], v[90:93], off
	s_nop 1
	v_mul_f32_e32 v90, v95, v95
	v_mul_f32_e32 v91, v97, v97
	v_fmac_f32_e32 v90, v94, v94
	v_fmac_f32_e32 v91, v96, v96
	v_add_f32_e32 v90, v90, v91
	v_mul_f32_e32 v91, v101, v101
	v_fmac_f32_e32 v91, v100, v100
	v_add_f32_e32 v90, v91, v90
	v_mul_f32_e32 v91, v99, v99
	v_fmac_f32_e32 v91, v98, v98
	v_add_f32_e32 v98, v91, v90
	s_waitcnt vmcnt(15)
	v_mov_b64_e32 v[90:91], v[170:171]
	v_mov_b64_e32 v[92:93], v[172:173]
	v_lshlrev_b32_e32 v94, 16, v90
	v_and_b32_e32 v95, 0xffff0000, v90
	v_lshlrev_b32_e32 v90, 16, v91
	v_and_b32_e32 v91, 0xffff0000, v91
	v_lshlrev_b32_e32 v96, 16, v92
	v_and_b32_e32 v97, 0xffff0000, v92
	v_lshlrev_b32_e32 v92, 16, v93
	v_and_b32_e32 v93, 0xffff0000, v93
	v_pk_add_f32 v[88:89], v[88:89], v[90:91]
	v_pk_add_f32 v[86:87], v[86:87], v[94:95]
	v_pk_add_f32 v[90:91], v[84:85], v[92:93]
	v_pk_add_f32 v[92:93], v[82:83], v[96:97]
	v_cvt_pk_bf16_f32 v82, v86, v87
	v_cvt_pk_bf16_f32 v83, v88, v89
	v_cvt_pk_bf16_f32 v84, v92, v93
	v_cvt_pk_bf16_f32 v85, v90, v91
	global_store_dwordx4 v[102:103], v[82:85], off offset:64
	s_nop 1
	v_mul_f32_e32 v82, v87, v87
	v_mul_f32_e32 v83, v89, v89
	v_fmac_f32_e32 v82, v86, v86
	v_fmac_f32_e32 v83, v88, v88
	v_add_f32_e32 v82, v82, v83
	v_mul_f32_e32 v83, v93, v93
	v_fmac_f32_e32 v83, v92, v92
	v_add_f32_e32 v82, v83, v82
	v_mul_f32_e32 v83, v91, v91
	v_fmac_f32_e32 v83, v90, v90
	v_add_f32_e32 v82, v83, v82
	v_add_f32_e32 v82, v98, v82
	ds_bpermute_b32 v83, v145, v82
	s_waitcnt lgkmcnt(0)
	v_add_f32_e32 v82, v82, v83
	ds_bpermute_b32 v83, v144, v82
	s_and_saveexec_b64 s[56:57], s[38:39]
	s_cbranch_execz .LBB0_354
	s_waitcnt lgkmcnt(0)
	v_add_f32_e32 v84, v82, v83
	v_or_b32_e32 v82, 32, v138
	v_ashrrev_i32_e32 v83, 31, v82
	v_lshlrev_b64 v[82:83], 6, v[82:83]
	v_lshl_add_u64 v[82:83], s[80:81], 0, v[82:83]
	v_lshl_add_u64 v[82:83], s[54:55], 2, v[82:83]
	s_lshl_b32 s20, s74, 2
	v_lshl_add_u64 v[82:83], v[82:83], 0, s[20:21]
	global_store_dword v[82:83], v84, off
.LBB0_354:
	s_or_b64 exec, exec, s[56:57]
	v_add_co_u32_e32 v86, vcc, 0x18000, v136
	s_nop 1
	v_addc_co_u32_e32 v87, vcc, 0, v137, vcc
	s_waitcnt lgkmcnt(0)
	s_waitcnt vmcnt(15)
	v_mov_b64_e32 v[82:83], v[174:175]
	v_mov_b64_e32 v[84:85], v[176:177]
	v_lshlrev_b32_e32 v88, 16, v82
	v_and_b32_e32 v89, 0xffff0000, v82
	v_lshlrev_b32_e32 v82, 16, v83
	v_and_b32_e32 v83, 0xffff0000, v83
	v_lshlrev_b32_e32 v90, 16, v84
	v_and_b32_e32 v91, 0xffff0000, v84
	v_lshlrev_b32_e32 v84, 16, v85
	v_and_b32_e32 v85, 0xffff0000, v85
	v_pk_add_f32 v[80:81], v[80:81], v[82:83]
	v_pk_add_f32 v[78:79], v[78:79], v[88:89]
	v_pk_add_f32 v[82:83], v[76:77], v[84:85]
	v_pk_add_f32 v[84:85], v[74:75], v[90:91]
	v_cvt_pk_bf16_f32 v74, v78, v79
	v_cvt_pk_bf16_f32 v75, v80, v81
	v_cvt_pk_bf16_f32 v76, v84, v85
	v_cvt_pk_bf16_f32 v77, v82, v83
	global_store_dwordx4 v[86:87], v[74:77], off
	s_nop 1
	v_mul_f32_e32 v74, v79, v79
	v_mul_f32_e32 v75, v81, v81
	v_fmac_f32_e32 v74, v78, v78
	v_fmac_f32_e32 v75, v80, v80
	v_add_f32_e32 v74, v74, v75
	v_mul_f32_e32 v75, v85, v85
	v_fmac_f32_e32 v75, v84, v84
	v_add_f32_e32 v74, v75, v74
	v_mul_f32_e32 v75, v83, v83
	v_fmac_f32_e32 v75, v82, v82
	v_add_f32_e32 v82, v75, v74
	s_waitcnt vmcnt(15)
	v_mov_b64_e32 v[74:75], v[178:179]
	v_mov_b64_e32 v[76:77], v[180:181]
	v_lshlrev_b32_e32 v78, 16, v74
	v_and_b32_e32 v79, 0xffff0000, v74
	v_lshlrev_b32_e32 v74, 16, v75
	v_and_b32_e32 v75, 0xffff0000, v75
	v_lshlrev_b32_e32 v80, 16, v76
	v_and_b32_e32 v81, 0xffff0000, v76
	v_lshlrev_b32_e32 v76, 16, v77
	v_and_b32_e32 v77, 0xffff0000, v77
	v_pk_add_f32 v[72:73], v[72:73], v[74:75]
	v_pk_add_f32 v[70:71], v[70:71], v[78:79]
	v_pk_add_f32 v[74:75], v[68:69], v[76:77]
	v_pk_add_f32 v[76:77], v[66:67], v[80:81]
	v_cvt_pk_bf16_f32 v66, v70, v71
	v_cvt_pk_bf16_f32 v67, v72, v73
	v_cvt_pk_bf16_f32 v68, v76, v77
	v_cvt_pk_bf16_f32 v69, v74, v75
	global_store_dwordx4 v[86:87], v[66:69], off offset:64
	s_nop 1
	v_mul_f32_e32 v66, v71, v71
	v_mul_f32_e32 v67, v73, v73
	v_fmac_f32_e32 v66, v70, v70
	v_fmac_f32_e32 v67, v72, v72
	v_add_f32_e32 v66, v66, v67
	v_mul_f32_e32 v67, v77, v77
	v_fmac_f32_e32 v67, v76, v76
	v_add_f32_e32 v66, v67, v66
	v_mul_f32_e32 v67, v75, v75
	v_fmac_f32_e32 v67, v74, v74
	v_add_f32_e32 v66, v67, v66
	v_add_f32_e32 v66, v82, v66
	ds_bpermute_b32 v67, v145, v66
	s_waitcnt lgkmcnt(0)
	v_add_f32_e32 v66, v66, v67
	ds_bpermute_b32 v67, v144, v66
	s_and_saveexec_b64 s[56:57], s[38:39]
	s_cbranch_execz .LBB0_356
	s_waitcnt lgkmcnt(0)
	v_add_f32_e32 v68, v66, v67
	v_or_b32_e32 v66, 48, v138
	v_ashrrev_i32_e32 v67, 31, v66
	v_lshlrev_b64 v[66:67], 6, v[66:67]
	v_lshl_add_u64 v[66:67], s[80:81], 0, v[66:67]
	v_lshl_add_u64 v[66:67], s[54:55], 2, v[66:67]
	s_lshl_b32 s20, s74, 2
	v_lshl_add_u64 v[66:67], v[66:67], 0, s[20:21]
	global_store_dword v[66:67], v68, off
; __device__ __forceinline__ unsigned cvt_pk_bf16(float lo, float hi) { f32x2 v = {lo, hi}; bf16x2_t_ b = __builtin_convertvector(v, bf16x2_t_); return __builtin_bit_cast(unsigned, b); }
; __device__ __forceinline__ float bf_lo(unsigned w) { return __uint_as_float(w << 16); }
; __device__ __forceinline__ float bf_hi(unsigned w) { return __uint_as_float(w & 0xffff0000u); }
;     __device__ __forceinline__ void operator()(f32x4 (&acc)[2][2][4][2], const Unit& u, int wr, int wc, int fr, int fq) const {
;     ...
;         for (int ai = 0; ai < 2; ++ai)
; #pragma unroll
;             for (int m = 0; m < 4; ++m) {
;                 const int j = 128 * ai + 16 * m; float sq = 0.f;
; #pragma unroll
;                 for (int bj = 0; bj < 2; ++bj) {
;                     const size_t o = (size_t)j * 1024 + col0 + 128 * bj;
;                     f32x4 a, b;
;                     if (bb) { const u32x4 w = *(const u32x4*)(xb + (size_t)t0 * 1024 + o);
;                         a = (f32x4){bf_lo(w.x), bf_hi(w.x), bf_lo(w.y), bf_hi(w.y)}; b = (f32x4){bf_lo(w.z), bf_hi(w.z), bf_lo(w.w), bf_hi(w.w)}; }
;                     else { a = *(const f32x4*)(bp0 + o); b = *(const f32x4*)(bp0 + o + 4); }
;                     a = a + acc[ai][bj][m][0]; b = b + acc[ai][bj][m][1];
;                     if (wout) { float* op = out + (size_t)t0 * 1024 + o; *(f32x4*)op = a; *(f32x4*)(op + 4) = b; }
;                     u32x4 w; w.x = cvt_pk_bf16(a.x, a.y); w.y = cvt_pk_bf16(a.z, a.w); w.z = cvt_pk_bf16(b.x, b.y); w.w = cvt_pk_bf16(b.z, b.w);
;                     *(u32x4*)(xb + (size_t)t0 * 1024 + o) = w;
;                     sq += (a.x * a.x + a.y * a.y) + (a.z * a.z + a.w * a.w) + (b.x * b.x + b.y * b.y) + (b.z * b.z + b.w * b.w);
;                 }
;                 sq += __shfl_xor(sq, 16); sq += __shfl_xor(sq, 32);
;                 if (fq == 0) ss[(size_t)(t0 + j) * 16 + 4 * u.pn + wc] = sq;
.LBB0_356:
	s_or_b64 exec, exec, s[56:57]
	v_add_co_u32_e32 v70, vcc, 0x40000, v136
	s_nop 1
	v_addc_co_u32_e32 v71, vcc, 0, v137, vcc
	s_waitcnt lgkmcnt(0)
	s_waitcnt vmcnt(15)
	v_mov_b64_e32 v[66:67], v[182:183]
	v_mov_b64_e32 v[68:69], v[184:185]
	v_lshlrev_b32_e32 v72, 16, v66
	v_and_b32_e32 v73, 0xffff0000, v66
	v_lshlrev_b32_e32 v66, 16, v67
	v_and_b32_e32 v67, 0xffff0000, v67
	v_lshlrev_b32_e32 v74, 16, v68
	v_and_b32_e32 v75, 0xffff0000, v68
	v_lshlrev_b32_e32 v68, 16, v69
	v_and_b32_e32 v69, 0xffff0000, v69
	v_pk_add_f32 v[64:65], v[64:65], v[66:67]
	v_pk_add_f32 v[62:63], v[62:63], v[72:73]
	v_pk_add_f32 v[66:67], v[60:61], v[68:69]
	v_pk_add_f32 v[68:69], v[58:59], v[74:75]
	v_cvt_pk_bf16_f32 v58, v62, v63
	v_cvt_pk_bf16_f32 v59, v64, v65
	v_cvt_pk_bf16_f32 v60, v68, v69
	v_cvt_pk_bf16_f32 v61, v66, v67
	global_store_dwordx4 v[70:71], v[58:61], off
	s_nop 1
	v_mul_f32_e32 v58, v63, v63
	v_mul_f32_e32 v59, v65, v65
	v_fmac_f32_e32 v58, v62, v62
	v_fmac_f32_e32 v59, v64, v64
	v_add_f32_e32 v58, v58, v59
	v_mul_f32_e32 v59, v69, v69
	v_fmac_f32_e32 v59, v68, v68
	v_add_f32_e32 v58, v59, v58
	v_mul_f32_e32 v59, v67, v67
	v_fmac_f32_e32 v59, v66, v66
	v_add_f32_e32 v66, v59, v58
	s_waitcnt vmcnt(15)
	v_mov_b64_e32 v[58:59], v[186:187]
	v_mov_b64_e32 v[60:61], v[188:189]
	v_lshlrev_b32_e32 v62, 16, v58
	v_and_b32_e32 v63, 0xffff0000, v58
	v_lshlrev_b32_e32 v58, 16, v59
	v_and_b32_e32 v59, 0xffff0000, v59
	v_lshlrev_b32_e32 v64, 16, v60
	v_and_b32_e32 v65, 0xffff0000, v60
	v_lshlrev_b32_e32 v60, 16, v61
	v_and_b32_e32 v61, 0xffff0000, v61
	v_pk_add_f32 v[56:57], v[56:57], v[58:59]
	v_pk_add_f32 v[54:55], v[54:55], v[62:63]
	v_pk_add_f32 v[58:59], v[52:53], v[60:61]
	v_pk_add_f32 v[60:61], v[50:51], v[64:65]
	v_cvt_pk_bf16_f32 v50, v54, v55
	v_cvt_pk_bf16_f32 v51, v56, v57
	v_cvt_pk_bf16_f32 v52, v60, v61
	v_cvt_pk_bf16_f32 v53, v58, v59
	global_store_dwordx4 v[70:71], v[50:53], off offset:64
	s_nop 1
	v_mul_f32_e32 v50, v55, v55
	v_mul_f32_e32 v51, v57, v57
	v_fmac_f32_e32 v50, v54, v54
	v_fmac_f32_e32 v51, v56, v56
	v_add_f32_e32 v50, v50, v51
	v_mul_f32_e32 v51, v61, v61
	v_fmac_f32_e32 v51, v60, v60
	v_add_f32_e32 v50, v51, v50
	v_mul_f32_e32 v51, v59, v59
	v_fmac_f32_e32 v51, v58, v58
	v_add_f32_e32 v50, v51, v50
	v_add_f32_e32 v50, v66, v50
	ds_bpermute_b32 v51, v145, v50
	s_waitcnt lgkmcnt(0)
	v_add_f32_e32 v50, v50, v51
	ds_bpermute_b32 v51, v144, v50
	s_and_saveexec_b64 s[56:57], s[38:39]
	s_cbranch_execz .LBB0_358
	s_waitcnt lgkmcnt(0)
	v_add_f32_e32 v52, v50, v51
	v_lshl_add_u64 v[50:51], s[54:55], 2, v[114:115]
	s_lshl_b32 s20, s74, 2
	v_lshl_add_u64 v[50:51], v[50:51], 0, s[20:21]
	v_add_co_u32_e32 v50, vcc, 0x2000, v50
	s_nop 1
	v_addc_co_u32_e32 v51, vcc, 0, v51, vcc
	global_store_dword v[50:51], v52, off
.LBB0_358:
	s_or_b64 exec, exec, s[56:57]
	v_add_co_u32_e32 v54, vcc, 0x48000, v136
	s_nop 1
	v_addc_co_u32_e32 v55, vcc, 0, v137, vcc
	s_waitcnt lgkmcnt(0)
	s_waitcnt vmcnt(15)
	v_mov_b64_e32 v[50:51], v[196:197]
	v_mov_b64_e32 v[52:53], v[198:199]
	v_lshlrev_b32_e32 v56, 16, v50
	v_and_b32_e32 v57, 0xffff0000, v50
	v_lshlrev_b32_e32 v50, 16, v51
	v_and_b32_e32 v51, 0xffff0000, v51
	v_lshlrev_b32_e32 v58, 16, v52
	v_and_b32_e32 v59, 0xffff0000, v52
	v_lshlrev_b32_e32 v52, 16, v53
	v_and_b32_e32 v53, 0xffff0000, v53
	v_pk_add_f32 v[48:49], v[48:49], v[50:51]
	v_pk_add_f32 v[46:47], v[46:47], v[56:57]
	v_pk_add_f32 v[50:51], v[44:45], v[52:53]
	v_pk_add_f32 v[52:53], v[42:43], v[58:59]
	v_cvt_pk_bf16_f32 v42, v46, v47
	v_cvt_pk_bf16_f32 v43, v48, v49
	v_cvt_pk_bf16_f32 v44, v52, v53
	v_cvt_pk_bf16_f32 v45, v50, v51
	global_store_dwordx4 v[54:55], v[42:45], off
	s_nop 1
	v_mul_f32_e32 v42, v47, v47
	v_mul_f32_e32 v43, v49, v49
	v_fmac_f32_e32 v42, v46, v46
	v_fmac_f32_e32 v43, v48, v48
	v_add_f32_e32 v42, v42, v43
	v_mul_f32_e32 v43, v53, v53
	v_fmac_f32_e32 v43, v52, v52
	v_add_f32_e32 v42, v43, v42
	v_mul_f32_e32 v43, v51, v51
	v_fmac_f32_e32 v43, v50, v50
	v_add_f32_e32 v50, v43, v42
	s_waitcnt vmcnt(15)
	v_mov_b64_e32 v[42:43], v[200:201]
	v_mov_b64_e32 v[44:45], v[202:203]
	v_lshlrev_b32_e32 v46, 16, v42
	v_and_b32_e32 v47, 0xffff0000, v42
	v_lshlrev_b32_e32 v42, 16, v43
	v_and_b32_e32 v43, 0xffff0000, v43
	v_lshlrev_b32_e32 v48, 16, v44
	v_and_b32_e32 v49, 0xffff0000, v44
	v_lshlrev_b32_e32 v44, 16, v45
	v_and_b32_e32 v45, 0xffff0000, v45
	v_pk_add_f32 v[40:41], v[40:41], v[42:43]
	v_pk_add_f32 v[38:39], v[38:39], v[46:47]
	v_pk_add_f32 v[42:43], v[36:37], v[44:45]
	v_pk_add_f32 v[44:45], v[34:35], v[48:49]
	v_cvt_pk_bf16_f32 v34, v38, v39
	v_cvt_pk_bf16_f32 v35, v40, v41
	v_cvt_pk_bf16_f32 v36, v44, v45
	v_cvt_pk_bf16_f32 v37, v42, v43
	global_store_dwordx4 v[54:55], v[34:37], off offset:64
	s_nop 1
	v_mul_f32_e32 v34, v39, v39
	v_mul_f32_e32 v35, v41, v41
	v_fmac_f32_e32 v34, v38, v38
	v_fmac_f32_e32 v35, v40, v40
	v_add_f32_e32 v34, v34, v35
	v_mul_f32_e32 v35, v45, v45
	v_fmac_f32_e32 v35, v44, v44
	v_add_f32_e32 v34, v35, v34
	v_mul_f32_e32 v35, v43, v43
	v_fmac_f32_e32 v35, v42, v42
	v_add_f32_e32 v34, v35, v34
	v_add_f32_e32 v34, v50, v34
	ds_bpermute_b32 v35, v145, v34
	s_waitcnt lgkmcnt(0)
	v_add_f32_e32 v34, v34, v35
	ds_bpermute_b32 v35, v144, v34
	s_and_saveexec_b64 s[56:57], s[38:39]
	s_cbranch_execz .LBB0_360
	s_waitcnt lgkmcnt(0)
	v_add_f32_e32 v36, v34, v35
	v_lshl_add_u64 v[34:35], s[54:55], 2, v[114:115]
	s_lshl_b32 s20, s74, 2
	v_lshl_add_u64 v[34:35], v[34:35], 0, s[20:21]
	v_add_co_u32_e32 v34, vcc, 0x2000, v34
	s_nop 1
	v_addc_co_u32_e32 v35, vcc, 0, v35, vcc
	global_store_dword v[34:35], v36, off offset:1024
; __device__ __forceinline__ unsigned cvt_pk_bf16(float lo, float hi) { f32x2 v = {lo, hi}; bf16x2_t_ b = __builtin_convertvector(v, bf16x2_t_); return __builtin_bit_cast(unsigned, b); }
; __device__ __forceinline__ float bf_lo(unsigned w) { return __uint_as_float(w << 16); }
; __device__ __forceinline__ float bf_hi(unsigned w) { return __uint_as_float(w & 0xffff0000u); }
;     __device__ __forceinline__ void operator()(f32x4 (&acc)[2][2][4][2], const Unit& u, int wr, int wc, int fr, int fq) const {
;     ...
;         for (int ai = 0; ai < 2; ++ai)
; #pragma unroll
;             for (int m = 0; m < 4; ++m) {
;                 const int j = 128 * ai + 16 * m; float sq = 0.f;
; #pragma unroll
;                 for (int bj = 0; bj < 2; ++bj) {
;                     const size_t o = (size_t)j * 1024 + col0 + 128 * bj;
;                     f32x4 a, b;
;                     if (bb) { const u32x4 w = *(const u32x4*)(xb + (size_t)t0 * 1024 + o);
;                         a = (f32x4){bf_lo(w.x), bf_hi(w.x), bf_lo(w.y), bf_hi(w.y)}; b = (f32x4){bf_lo(w.z), bf_hi(w.z), bf_lo(w.w), bf_hi(w.w)}; }
;                     else { a = *(const f32x4*)(bp0 + o); b = *(const f32x4*)(bp0 + o + 4); }
;                     a = a + acc[ai][bj][m][0]; b = b + acc[ai][bj][m][1];
;                     if (wout) { float* op = out + (size_t)t0 * 1024 + o; *(f32x4*)op = a; *(f32x4*)(op + 4) = b; }
;                     u32x4 w; w.x = cvt_pk_bf16(a.x, a.y); w.y = cvt_pk_bf16(a.z, a.w); w.z = cvt_pk_bf16(b.x, b.y); w.w = cvt_pk_bf16(b.z, b.w);
;                     *(u32x4*)(xb + (size_t)t0 * 1024 + o) = w;
;                     sq += (a.x * a.x + a.y * a.y) + (a.z * a.z + a.w * a.w) + (b.x * b.x + b.y * b.y) + (b.z * b.z + b.w * b.w);
;                 }
;                 sq += __shfl_xor(sq, 16); sq += __shfl_xor(sq, 32);
;                 if (fq == 0) ss[(size_t)(t0 + j) * 16 + 4 * u.pn + wc] = sq;
.LBB0_360:
	s_or_b64 exec, exec, s[56:57]
	v_add_co_u32_e32 v38, vcc, 0x50000, v136
	s_nop 1
	v_addc_co_u32_e32 v39, vcc, 0, v137, vcc
	s_waitcnt lgkmcnt(0)
	s_waitcnt vmcnt(15)
	v_mov_b64_e32 v[34:35], v[204:205]
	v_mov_b64_e32 v[36:37], v[206:207]
	v_lshlrev_b32_e32 v40, 16, v34
	v_and_b32_e32 v41, 0xffff0000, v34
	v_lshlrev_b32_e32 v34, 16, v35
	v_and_b32_e32 v35, 0xffff0000, v35
	v_lshlrev_b32_e32 v42, 16, v36
	v_and_b32_e32 v43, 0xffff0000, v36
	v_lshlrev_b32_e32 v36, 16, v37
	v_and_b32_e32 v37, 0xffff0000, v37
	v_pk_add_f32 v[32:33], v[32:33], v[34:35]
	v_pk_add_f32 v[30:31], v[30:31], v[40:41]
	v_pk_add_f32 v[34:35], v[28:29], v[36:37]
	v_pk_add_f32 v[36:37], v[26:27], v[42:43]
	v_cvt_pk_bf16_f32 v26, v30, v31
	v_cvt_pk_bf16_f32 v27, v32, v33
	v_cvt_pk_bf16_f32 v28, v36, v37
	v_cvt_pk_bf16_f32 v29, v34, v35
	global_store_dwordx4 v[38:39], v[26:29], off
	s_nop 1
	v_mul_f32_e32 v26, v31, v31
	v_mul_f32_e32 v27, v33, v33
	v_fmac_f32_e32 v26, v30, v30
	v_fmac_f32_e32 v27, v32, v32
	v_add_f32_e32 v26, v26, v27
	v_mul_f32_e32 v27, v37, v37
	v_fmac_f32_e32 v27, v36, v36
	v_add_f32_e32 v26, v27, v26
	v_mul_f32_e32 v27, v35, v35
	v_fmac_f32_e32 v27, v34, v34
	v_add_f32_e32 v34, v27, v26
	s_waitcnt vmcnt(15)
	v_mov_b64_e32 v[26:27], v[208:209]
	v_mov_b64_e32 v[28:29], v[210:211]
	v_lshlrev_b32_e32 v30, 16, v26
	v_and_b32_e32 v31, 0xffff0000, v26
	v_lshlrev_b32_e32 v26, 16, v27
	v_and_b32_e32 v27, 0xffff0000, v27
	v_lshlrev_b32_e32 v32, 16, v28
	v_and_b32_e32 v33, 0xffff0000, v28
	v_lshlrev_b32_e32 v28, 16, v29
	v_and_b32_e32 v29, 0xffff0000, v29
	v_pk_add_f32 v[24:25], v[24:25], v[26:27]
	v_pk_add_f32 v[22:23], v[22:23], v[30:31]
	v_pk_add_f32 v[26:27], v[20:21], v[28:29]
	v_pk_add_f32 v[28:29], v[18:19], v[32:33]
	v_cvt_pk_bf16_f32 v18, v22, v23
	v_cvt_pk_bf16_f32 v19, v24, v25
	v_cvt_pk_bf16_f32 v20, v28, v29
	v_cvt_pk_bf16_f32 v21, v26, v27
	global_store_dwordx4 v[38:39], v[18:21], off offset:64
	s_nop 1
	v_mul_f32_e32 v18, v23, v23
	v_mul_f32_e32 v19, v25, v25
	v_fmac_f32_e32 v18, v22, v22
	v_fmac_f32_e32 v19, v24, v24
	v_add_f32_e32 v18, v18, v19
	v_mul_f32_e32 v19, v29, v29
	v_fmac_f32_e32 v19, v28, v28
	v_add_f32_e32 v18, v19, v18
	v_mul_f32_e32 v19, v27, v27
	v_fmac_f32_e32 v19, v26, v26
	v_add_f32_e32 v18, v19, v18
	v_add_f32_e32 v18, v34, v18
	ds_bpermute_b32 v19, v145, v18
	s_waitcnt lgkmcnt(0)
	v_add_f32_e32 v18, v18, v19
	ds_bpermute_b32 v19, v144, v18
	s_and_saveexec_b64 s[56:57], s[38:39]
	s_cbranch_execz .LBB0_362
	s_waitcnt lgkmcnt(0)
	v_add_f32_e32 v20, v18, v19
	v_lshl_add_u64 v[18:19], s[54:55], 2, v[114:115]
	s_lshl_b32 s20, s74, 2
	v_lshl_add_u64 v[18:19], v[18:19], 0, s[20:21]
	v_add_co_u32_e32 v18, vcc, 0x2000, v18
	s_nop 1
	v_addc_co_u32_e32 v19, vcc, 0, v19, vcc
	global_store_dword v[18:19], v20, off offset:2048
.LBB0_362:
	s_or_b64 exec, exec, s[56:57]
	v_add_co_u32_e32 v22, vcc, 0x58000, v136
	s_nop 1
	v_addc_co_u32_e32 v23, vcc, 0, v137, vcc
	s_waitcnt lgkmcnt(0)
	s_waitcnt vmcnt(15)
	v_mov_b64_e32 v[18:19], v[212:213]
	v_mov_b64_e32 v[20:21], v[214:215]
	v_lshlrev_b32_e32 v24, 16, v18
	v_and_b32_e32 v25, 0xffff0000, v18
	v_lshlrev_b32_e32 v18, 16, v19
	v_and_b32_e32 v19, 0xffff0000, v19
	v_lshlrev_b32_e32 v26, 16, v20
	v_and_b32_e32 v27, 0xffff0000, v20
	v_lshlrev_b32_e32 v20, 16, v21
	v_and_b32_e32 v21, 0xffff0000, v21
	v_pk_add_f32 v[16:17], v[16:17], v[18:19]
	v_pk_add_f32 v[14:15], v[14:15], v[24:25]
	v_pk_add_f32 v[18:19], v[12:13], v[20:21]
	v_pk_add_f32 v[20:21], v[10:11], v[26:27]
	v_cvt_pk_bf16_f32 v10, v14, v15
	v_cvt_pk_bf16_f32 v11, v16, v17
	v_cvt_pk_bf16_f32 v12, v20, v21
	v_cvt_pk_bf16_f32 v13, v18, v19
	global_store_dwordx4 v[22:23], v[10:13], off
	s_nop 1
	v_mul_f32_e32 v10, v15, v15
	v_mul_f32_e32 v11, v17, v17
	v_fmac_f32_e32 v10, v14, v14
	v_fmac_f32_e32 v11, v16, v16
	v_add_f32_e32 v10, v10, v11
	v_mul_f32_e32 v11, v21, v21
	v_fmac_f32_e32 v11, v20, v20
	v_add_f32_e32 v10, v11, v10
	v_mul_f32_e32 v11, v19, v19
	v_fmac_f32_e32 v11, v18, v18
	v_add_f32_e32 v18, v11, v10
	s_waitcnt vmcnt(15)
	v_mov_b64_e32 v[10:11], v[236:237]
	v_mov_b64_e32 v[12:13], v[238:239]
	v_lshlrev_b32_e32 v14, 16, v10
	v_and_b32_e32 v15, 0xffff0000, v10
	v_lshlrev_b32_e32 v10, 16, v11
	v_and_b32_e32 v11, 0xffff0000, v11
	v_lshlrev_b32_e32 v16, 16, v12
	v_and_b32_e32 v17, 0xffff0000, v12
	v_lshlrev_b32_e32 v12, 16, v13
	v_and_b32_e32 v13, 0xffff0000, v13
	v_pk_add_f32 v[8:9], v[8:9], v[10:11]
	v_pk_add_f32 v[6:7], v[6:7], v[14:15]
	v_pk_add_f32 v[10:11], v[4:5], v[12:13]
	v_pk_add_f32 v[12:13], v[2:3], v[16:17]
	v_cvt_pk_bf16_f32 v2, v6, v7
	v_cvt_pk_bf16_f32 v3, v8, v9
	v_cvt_pk_bf16_f32 v4, v12, v13
	v_cvt_pk_bf16_f32 v5, v10, v11
	global_store_dwordx4 v[22:23], v[2:5], off offset:64
	s_nop 1
	v_mul_f32_e32 v2, v7, v7
	v_mul_f32_e32 v3, v9, v9
	v_fmac_f32_e32 v2, v6, v6
	v_fmac_f32_e32 v3, v8, v8
	v_add_f32_e32 v2, v2, v3
	v_mul_f32_e32 v3, v13, v13
	v_fmac_f32_e32 v3, v12, v12
	v_add_f32_e32 v2, v3, v2
	v_mul_f32_e32 v3, v11, v11
	v_fmac_f32_e32 v3, v10, v10
	v_add_f32_e32 v2, v3, v2
	v_add_f32_e32 v2, v18, v2
	ds_bpermute_b32 v3, v145, v2
	s_waitcnt lgkmcnt(0)
	v_add_f32_e32 v2, v2, v3
	ds_bpermute_b32 v3, v144, v2
	s_and_saveexec_b64 s[56:57], s[38:39]
	s_cbranch_execz .LBB0_364
	s_waitcnt lgkmcnt(0)
	v_add_f32_e32 v4, v2, v3
	v_lshl_add_u64 v[2:3], s[54:55], 2, v[114:115]
	s_lshl_b32 s20, s74, 2
	v_lshl_add_u64 v[2:3], v[2:3], 0, s[20:21]
	v_add_co_u32_e32 v2, vcc, 0x2000, v2
	s_nop 1
	v_addc_co_u32_e32 v3, vcc, 0, v3, vcc
	global_store_dword v[2:3], v4, off offset:3072
